# baseline (speedup 1.0000x reference)
; #define STAGE_A(POFF, h, kt) STAGE_AX(POFF, h, kt, brow)
; #define LDA(dst, b, h) _Pragma("unroll") for (int m = 0; m < 4; ++m) _Pragma("unroll") for (int k = 0; k < 2; ++k) \
;     dst[m][k] = *reinterpret_cast<const bf16x8*>((char*)SA(b, h) + lds_byte(wr * 64 + m * 16 + fr, k * 32 + fq * 8))
; #define LDB(dst, b, h) _Pragma("unroll") for (int n = 0; n < 2; ++n) _Pragma("unroll") for (int k = 0; k < 2; ++k) \
;     dst[n][k] = *reinterpret_cast<const bf16x8*>((char*)SB(b, h) + lds_byte(wc * 32 + n * 16 + fr, k * 32 + fq * 8))
; #define MMA(ai, bj, At_, Bt_) do { __builtin_amdgcn_s_setprio(1); \
;     _Pragma("unroll") for (int k = 0; k < 2; ++k) _Pragma("unroll") for (int m = 0; m < 4; ++m) _Pragma("unroll") for (int n = 0; n < 2; ++n) \
;       acc[ai][bj][m][n] = __builtin_amdgcn_mfma_f32_16x16x32_bf16(At_[m][k], Bt_[n][k], acc[ai][bj][m][n], 0, 0, 0); \
;     __builtin_amdgcn_s_setprio(0); } while (0)
; #define WAIT_V(n) asm volatile("s_waitcnt vmcnt(" #n ")" ::: "memory")
; #define BAR __builtin_amdgcn_s_barrier()
; #define SCHED __builtin_amdgcn_sched_barrier(0)
; #define TILE_RC(w_, brow_, bcol_) do { const int wg_ = ((w_) & 7) * qx + ((w_) >> 3); const int gid_ = wg_ / nig; \
;     brow_ = (gid_ * 8 + ((wg_ % nig) & 7)) * 256; bcol_ = ((wg_ % nig) >> 3) * 256; } while (0)
; template <int EPI, int N, int K>
; __device__ __forceinline__ void gemm_phase(const bf16_t* __restrict__ A, const bf16_t* __restrict__ Bt, const EpiArgs ea) {
;     ...
;   for (int w = blockIdx.x; w < nwg; w += gridDim.x) {
;     int brow, bcol; TILE_RC(w, brow, bcol);
;     f32x4 acc[2][2][4][2];
; #pragma unroll
;     for (int a = 0; a < 2; ++a)
; #pragma unroll
;       for (int b = 0; b < 2; ++b)
; #pragma unroll
;         for (int m = 0; m < 4; ++m)
; #pragma unroll
;           for (int n = 0; n < 2; ++n) acc[a][b][m][n] = (f32x4){0.f, 0.f, 0.f, 0.f};
;     bf16x8 At[4][2], B0[2][2], B1[2][2];
;     if (wr == 1) BAR;
;     if (w == (int)blockIdx.x) { WAIT_V(0); } else { WAIT_V(24); }
;     BAR;
;     BAR;
;     for (int t = 0; t < nt - 2; t += 2) {
;       LDB(B0, 0, 0); SCHED; LDA(At, 0, 0); STAGE_A(SA_OFF(1, 1), 1, t + 1);
;       WAIT_L(8); BAR; WAIT_L(0); MMA(0, 0, At, B0); BAR; SCHED;
.LBB0_132:
	s_and_b32 s0, s26, 7
	s_mulk_i32 s0, 0xc0
	s_ashr_i32 s1, s26, 3
	s_add_i32 s1, s0, s1
	s_mul_hi_i32 s0, s1, 0x2aaaaaab
	s_lshr_b32 s2, s0, 31
	s_ashr_i32 s0, s0, 5
	s_add_i32 s0, s0, s2
	s_mul_i32 s2, s0, 0xc0
	s_sub_i32 s27, s1, s2
	s_lshl_b32 s1, s27, 8
	s_lshl_b32 s2, s27, 5
	s_lshl_b32 s3, s27, 17
	s_and_b32 s27, s27, 7
	s_lshl_b32 s28, s0, 23
	s_lshl_b32 s27, s27, 20
	v_mov_b32_e32 v0, 0
	s_and_b32 s3, s3, 0xfff00000
	s_or_b32 s27, s28, s27
	s_mov_b32 s28, -2
	s_mov_b32 s29, 0
	v_mov_b32_e32 v1, v0
	v_mov_b32_e32 v2, v0
	v_mov_b32_e32 v3, v0
	v_mov_b32_e32 v4, v0
	v_mov_b32_e32 v5, v0
	v_mov_b32_e32 v6, v0
	v_mov_b32_e32 v7, v0
	v_mov_b32_e32 v8, v0
	v_mov_b32_e32 v9, v0
	v_mov_b32_e32 v10, v0
	v_mov_b32_e32 v11, v0
	v_mov_b32_e32 v12, v0
	v_mov_b32_e32 v13, v0
	v_mov_b32_e32 v14, v0
	v_mov_b32_e32 v15, v0
	v_mov_b32_e32 v16, v0
	v_mov_b32_e32 v17, v0
	v_mov_b32_e32 v18, v0
	v_mov_b32_e32 v19, v0
	v_mov_b32_e32 v20, v0
	v_mov_b32_e32 v21, v0
	v_mov_b32_e32 v22, v0
	v_mov_b32_e32 v23, v0
	v_mov_b32_e32 v24, v0
	v_mov_b32_e32 v25, v0
	v_mov_b32_e32 v26, v0
	v_mov_b32_e32 v27, v0
	v_mov_b32_e32 v28, v0
	v_mov_b32_e32 v29, v0
	v_mov_b32_e32 v30, v0
	v_mov_b32_e32 v31, v0
	v_mov_b32_e32 v32, v0
	v_mov_b32_e32 v33, v0
	v_mov_b32_e32 v34, v0
	v_mov_b32_e32 v35, v0
	v_mov_b32_e32 v36, v0
	v_mov_b32_e32 v37, v0
	v_mov_b32_e32 v38, v0
	v_mov_b32_e32 v39, v0
	v_mov_b32_e32 v40, v0
	v_mov_b32_e32 v41, v0
	v_mov_b32_e32 v42, v0
	v_mov_b32_e32 v43, v0
	v_mov_b32_e32 v44, v0
	v_mov_b32_e32 v45, v0
	v_mov_b32_e32 v46, v0
	v_mov_b32_e32 v47, v0
	v_mov_b32_e32 v48, v0
	v_mov_b32_e32 v49, v0
	v_mov_b32_e32 v50, v0
	v_mov_b32_e32 v51, v0
	v_mov_b32_e32 v52, v0
	v_mov_b32_e32 v53, v0
	v_mov_b32_e32 v54, v0
	v_mov_b32_e32 v55, v0
	v_mov_b32_e32 v56, v0
	v_mov_b32_e32 v57, v0
	v_mov_b32_e32 v58, v0
	v_mov_b32_e32 v59, v0
	v_mov_b32_e32 v60, v0
	v_mov_b32_e32 v61, v0
	v_mov_b32_e32 v62, v0
	v_mov_b32_e32 v63, v0
	v_mov_b32_e32 v64, v0
	v_mov_b32_e32 v65, v0
	v_mov_b32_e32 v66, v0
	v_mov_b32_e32 v67, v0
	v_mov_b32_e32 v68, v0
	v_mov_b32_e32 v69, v0
	v_mov_b32_e32 v70, v0
	v_mov_b32_e32 v71, v0
	v_mov_b32_e32 v72, v0
	v_mov_b32_e32 v73, v0
	v_mov_b32_e32 v74, v0
	v_mov_b32_e32 v75, v0
	v_mov_b32_e32 v76, v0
	v_mov_b32_e32 v77, v0
	v_mov_b32_e32 v78, v0
	v_mov_b32_e32 v79, v0
	v_mov_b32_e32 v80, v0
	v_mov_b32_e32 v81, v0
	v_mov_b32_e32 v82, v0
	v_mov_b32_e32 v83, v0
	v_mov_b32_e32 v84, v0
	v_mov_b32_e32 v85, v0
	v_mov_b32_e32 v86, v0
	v_mov_b32_e32 v87, v0
	v_mov_b32_e32 v88, v0
	v_mov_b32_e32 v89, v0
	v_mov_b32_e32 v90, v0
	v_mov_b32_e32 v91, v0
	v_mov_b32_e32 v92, v0
	v_mov_b32_e32 v93, v0
	v_mov_b32_e32 v94, v0
	v_mov_b32_e32 v95, v0
	v_mov_b32_e32 v96, v0
	v_mov_b32_e32 v97, v0
	v_mov_b32_e32 v98, v0
	v_mov_b32_e32 v99, v0
	v_mov_b32_e32 v100, v0
	v_mov_b32_e32 v101, v0
	v_mov_b32_e32 v102, v0
	v_mov_b32_e32 v103, v0
	v_mov_b32_e32 v104, v0
	v_mov_b32_e32 v105, v0
	v_mov_b32_e32 v106, v0
	v_mov_b32_e32 v107, v0
	v_mov_b32_e32 v108, v0
	v_mov_b32_e32 v109, v0
	v_mov_b32_e32 v110, v0
	v_mov_b32_e32 v111, v0
	v_mov_b32_e32 v112, v0
	v_mov_b32_e32 v113, v0
	v_mov_b32_e32 v114, v0
	v_mov_b32_e32 v115, v0
	v_mov_b32_e32 v116, v0
	v_mov_b32_e32 v117, v0
	v_mov_b32_e32 v118, v0
	v_mov_b32_e32 v119, v0
	v_mov_b32_e32 v120, v0
	v_mov_b32_e32 v121, v0
	v_mov_b32_e32 v122, v0
	v_mov_b32_e32 v123, v0
	v_mov_b32_e32 v124, v0
	v_mov_b32_e32 v125, v0
	v_mov_b32_e32 v126, v0
	v_mov_b32_e32 v127, v0
	s_barrier
	s_barrier
	ds_read_b128 v[154:157], v145
	ds_read_b128 v[158:161], v145 offset:1024
	ds_read_b128 v[162:165], v145 offset:2048
	ds_read_b128 v[166:169], v145 offset:3072
	ds_read_b128 v[170:173], v146
	ds_read_b128 v[174:177], v146 offset:1024
	ds_read_b128 v[178:181], v147
	ds_read_b128 v[182:185], v147 offset:1024
	ds_read_b128 v[186:189], v148
	ds_read_b128 v[190:193], v148 offset:1024
	ds_read_b128 v[194:197], v149
	ds_read_b128 v[198:201], v149 offset:1024
.LBB0_133:
	ds_read_b128 v[218:221], v146 offset:16384
	ds_read_b128 v[222:225], v146 offset:17408
	ds_read_b128 v[226:229], v147 offset:16384
	ds_read_b128 v[230:233], v147 offset:17408
	ds_read_b128 v[238:241], v148 offset:16384
	ds_read_b128 v[242:245], v148 offset:17408
	s_add_i32 s30, s27, s29
	s_or_b32 s31, s30, 0x80080
	s_mov_b32 m0, s24
	s_nop 0
	buffer_load_dwordx4 v131, s[48:51], s31 offen lds
	s_or_b32 s31, s30, 0xc0080
	s_mov_b32 m0, s25
	s_nop 0
	buffer_load_dwordx4 v131, s[48:51], s31 offen lds
	s_barrier
	s_waitcnt lgkmcnt(6)
	s_setprio 1
	v_mfma_f32_16x16x32_bf16 v[124:127], v[170:173], v[154:157], v[124:127]
	v_mfma_f32_16x16x32_bf16 v[120:123], v[170:173], v[162:165], v[120:123]
	v_mfma_f32_16x16x32_bf16 v[116:119], v[178:181], v[154:157], v[116:119]
	v_mfma_f32_16x16x32_bf16 v[112:115], v[178:181], v[162:165], v[112:115]
	v_mfma_f32_16x16x32_bf16 v[108:111], v[186:189], v[154:157], v[108:111]
	v_mfma_f32_16x16x32_bf16 v[104:107], v[186:189], v[162:165], v[104:107]
	v_mfma_f32_16x16x32_bf16 v[100:103], v[194:197], v[154:157], v[100:103]
	v_mfma_f32_16x16x32_bf16 v[96:99], v[194:197], v[162:165], v[96:99]
	v_mfma_f32_16x16x32_bf16 v[124:127], v[174:177], v[158:161], v[124:127]
	v_mfma_f32_16x16x32_bf16 v[120:123], v[174:177], v[166:169], v[120:123]
	v_mfma_f32_16x16x32_bf16 v[116:119], v[182:185], v[158:161], v[116:119]
	v_mfma_f32_16x16x32_bf16 v[112:115], v[182:185], v[166:169], v[112:115]
	v_mfma_f32_16x16x32_bf16 v[108:111], v[190:193], v[158:161], v[108:111]
	v_mfma_f32_16x16x32_bf16 v[104:107], v[190:193], v[166:169], v[104:107]
	v_mfma_f32_16x16x32_bf16 v[100:103], v[198:201], v[158:161], v[100:103]
	v_mfma_f32_16x16x32_bf16 v[96:99], v[198:201], v[166:169], v[96:99]
	s_setprio 0
	s_barrier
; #define STAGE_A(POFF, h, kt) STAGE_AX(POFF, h, kt, brow)
; #define STAGE_B(POFF, h, kt) STAGE_BX(POFF, h, kt, bcol)
; #define LDA(dst, b, h) _Pragma("unroll") for (int m = 0; m < 4; ++m) _Pragma("unroll") for (int k = 0; k < 2; ++k) \
;     dst[m][k] = *reinterpret_cast<const bf16x8*>((char*)SA(b, h) + lds_byte(wr * 64 + m * 16 + fr, k * 32 + fq * 8))
; #define LDB(dst, b, h) _Pragma("unroll") for (int n = 0; n < 2; ++n) _Pragma("unroll") for (int k = 0; k < 2; ++k) \
;     dst[n][k] = *reinterpret_cast<const bf16x8*>((char*)SB(b, h) + lds_byte(wc * 32 + n * 16 + fr, k * 32 + fq * 8))
; #define MMA(ai, bj, At_, Bt_) do { __builtin_amdgcn_s_setprio(1); \
;     _Pragma("unroll") for (int k = 0; k < 2; ++k) _Pragma("unroll") for (int m = 0; m < 4; ++m) _Pragma("unroll") for (int n = 0; n < 2; ++n) \
;       acc[ai][bj][m][n] = __builtin_amdgcn_mfma_f32_16x16x32_bf16(At_[m][k], Bt_[n][k], acc[ai][bj][m][n], 0, 0, 0); \
;     __builtin_amdgcn_s_setprio(0); } while (0)
; #define WAIT_V(n) asm volatile("s_waitcnt vmcnt(" #n ")" ::: "memory")
; #define BAR __builtin_amdgcn_s_barrier()
; #define SCHED __builtin_amdgcn_sched_barrier(0)
; template <int EPI, int N, int K>
; __device__ __forceinline__ void gemm_phase(const bf16_t* __restrict__ A, const bf16_t* __restrict__ Bt, const EpiArgs ea) {
;     ...
;       LDB(B1, 0, 1); STAGE_B(SB_OFF(0, 0), 0, t + 2);
;       BAR; WAIT_L(0); MMA(0, 1, At, B1); BAR;
;       LDA(At, 0, 1); STAGE_A(SA_OFF(0, 0), 0, t + 2);
;       BAR; WAIT_L(0); MMA(1, 0, At, B0); BAR; SCHED;
;       STAGE_B(SB_OFF(0, 1), 1, t + 2);
;       WAIT_V(6); BAR; MMA(1, 1, At, B1); BAR;
	ds_read_b128 v[202:205], v150
	ds_read_b128 v[206:209], v150 offset:1024
	ds_read_b128 v[210:213], v150 offset:2048
	ds_read_b128 v[214:217], v150 offset:3072
	ds_read_b128 v[246:249], v149 offset:16384
	ds_read_b128 v[250:253], v149 offset:17408
	s_add_i32 s31, s3, s29
	s_add_i32 s34, s31, 0x100
	s_mov_b32 m0, s11
	s_nop 0
	buffer_load_dwordx4 v134, s[72:75], s34 offen lds
	s_add_i32 s34, s31, 0x80100
	s_mov_b32 m0, s12
	s_nop 0
	buffer_load_dwordx4 v134, s[72:75], s34 offen lds
	s_waitcnt vmcnt(6)
	s_barrier
	s_waitcnt lgkmcnt(2)
	s_setprio 1
	v_mfma_f32_16x16x32_bf16 v[92:95], v[170:173], v[202:205], v[92:95]
	v_mfma_f32_16x16x32_bf16 v[88:91], v[170:173], v[210:213], v[88:91]
	v_mfma_f32_16x16x32_bf16 v[84:87], v[178:181], v[202:205], v[84:87]
	v_mfma_f32_16x16x32_bf16 v[80:83], v[178:181], v[210:213], v[80:83]
	v_mfma_f32_16x16x32_bf16 v[76:79], v[186:189], v[202:205], v[76:79]
	v_mfma_f32_16x16x32_bf16 v[72:75], v[186:189], v[210:213], v[72:75]
	v_mfma_f32_16x16x32_bf16 v[68:71], v[194:197], v[202:205], v[68:71]
	v_mfma_f32_16x16x32_bf16 v[64:67], v[194:197], v[210:213], v[64:67]
	v_mfma_f32_16x16x32_bf16 v[92:95], v[174:177], v[206:209], v[92:95]
	v_mfma_f32_16x16x32_bf16 v[88:91], v[174:177], v[214:217], v[88:91]
	v_mfma_f32_16x16x32_bf16 v[84:87], v[182:185], v[206:209], v[84:87]
	v_mfma_f32_16x16x32_bf16 v[80:83], v[182:185], v[214:217], v[80:83]
	v_mfma_f32_16x16x32_bf16 v[76:79], v[190:193], v[206:209], v[76:79]
	v_mfma_f32_16x16x32_bf16 v[72:75], v[190:193], v[214:217], v[72:75]
	v_mfma_f32_16x16x32_bf16 v[68:71], v[198:201], v[206:209], v[68:71]
	v_mfma_f32_16x16x32_bf16 v[64:67], v[198:201], v[214:217], v[64:67]
	s_setprio 0
	s_barrier
	ds_read_b128 v[170:173], v146 offset:32768
	ds_read_b128 v[174:177], v146 offset:33792
	ds_read_b128 v[178:181], v147 offset:32768
	ds_read_b128 v[182:185], v147 offset:33792
	ds_read_b128 v[186:189], v148 offset:32768
	ds_read_b128 v[190:193], v148 offset:33792
	s_add_i32 s34, s30, 0x100
	s_mov_b32 m0, s10
	s_nop 0
	buffer_load_dwordx4 v131, s[48:51], s34 offen lds
	s_add_i32 s35, s30, 0x40100
	s_mov_b32 m0, s13
	s_nop 0
	buffer_load_dwordx4 v131, s[48:51], s35 offen lds
	s_waitcnt vmcnt(10)
	s_barrier
	s_waitcnt lgkmcnt(6)
	s_setprio 1
	v_mfma_f32_16x16x32_bf16 v[60:63], v[218:221], v[154:157], v[60:63]
	v_mfma_f32_16x16x32_bf16 v[56:59], v[218:221], v[162:165], v[56:59]
	v_mfma_f32_16x16x32_bf16 v[52:55], v[226:229], v[154:157], v[52:55]
	v_mfma_f32_16x16x32_bf16 v[48:51], v[226:229], v[162:165], v[48:51]
	v_mfma_f32_16x16x32_bf16 v[44:47], v[238:241], v[154:157], v[44:47]
	v_mfma_f32_16x16x32_bf16 v[40:43], v[238:241], v[162:165], v[40:43]
	v_mfma_f32_16x16x32_bf16 v[36:39], v[246:249], v[154:157], v[36:39]
	v_mfma_f32_16x16x32_bf16 v[32:35], v[246:249], v[162:165], v[32:35]
	v_mfma_f32_16x16x32_bf16 v[60:63], v[222:225], v[158:161], v[60:63]
	v_mfma_f32_16x16x32_bf16 v[56:59], v[222:225], v[166:169], v[56:59]
	v_mfma_f32_16x16x32_bf16 v[52:55], v[230:233], v[158:161], v[52:55]
	v_mfma_f32_16x16x32_bf16 v[48:51], v[230:233], v[166:169], v[48:51]
	v_mfma_f32_16x16x32_bf16 v[44:47], v[242:245], v[158:161], v[44:47]
	v_mfma_f32_16x16x32_bf16 v[40:43], v[242:245], v[166:169], v[40:43]
	v_mfma_f32_16x16x32_bf16 v[36:39], v[250:253], v[158:161], v[36:39]
	v_mfma_f32_16x16x32_bf16 v[32:35], v[250:253], v[166:169], v[32:35]
	s_setprio 0
	s_barrier
	ds_read_b128 v[154:157], v151
	ds_read_b128 v[158:161], v151 offset:1024
	ds_read_b128 v[162:165], v151 offset:2048
	ds_read_b128 v[166:169], v151 offset:3072
	ds_read_b128 v[194:197], v149 offset:32768
	ds_read_b128 v[198:201], v149 offset:33792
	s_add_i32 s35, s31, 0x2100
	s_mov_b32 m0, s14
	s_nop 0
	buffer_load_dwordx4 v134, s[72:75], s35 offen lds
	s_add_i32 s35, s31, 0x82100
	s_mov_b32 m0, s15
	s_nop 0
	buffer_load_dwordx4 v134, s[72:75], s35 offen lds
	s_waitcnt vmcnt(6)
	s_barrier
	s_setprio 1
	v_mfma_f32_16x16x32_bf16 v[28:31], v[218:221], v[202:205], v[28:31]
	v_mfma_f32_16x16x32_bf16 v[24:27], v[218:221], v[210:213], v[24:27]
	v_mfma_f32_16x16x32_bf16 v[20:23], v[226:229], v[202:205], v[20:23]
	v_mfma_f32_16x16x32_bf16 v[16:19], v[226:229], v[210:213], v[16:19]
	v_mfma_f32_16x16x32_bf16 v[12:15], v[238:241], v[202:205], v[12:15]
	v_mfma_f32_16x16x32_bf16 v[8:11], v[238:241], v[210:213], v[8:11]
	v_mfma_f32_16x16x32_bf16 v[4:7], v[246:249], v[202:205], v[4:7]
	v_mfma_f32_16x16x32_bf16 v[0:3], v[246:249], v[210:213], v[0:3]
	v_mfma_f32_16x16x32_bf16 v[28:31], v[222:225], v[206:209], v[28:31]
	v_mfma_f32_16x16x32_bf16 v[24:27], v[222:225], v[214:217], v[24:27]
	v_mfma_f32_16x16x32_bf16 v[20:23], v[230:233], v[206:209], v[20:23]
	v_mfma_f32_16x16x32_bf16 v[16:19], v[230:233], v[214:217], v[16:19]
	v_mfma_f32_16x16x32_bf16 v[12:15], v[242:245], v[206:209], v[12:15]
	v_mfma_f32_16x16x32_bf16 v[8:11], v[242:245], v[214:217], v[8:11]
	v_mfma_f32_16x16x32_bf16 v[4:7], v[250:253], v[206:209], v[4:7]
	v_mfma_f32_16x16x32_bf16 v[0:3], v[250:253], v[214:217], v[0:3]
	s_setprio 0
	s_barrier
	ds_read_b128 v[218:221], v146 offset:49152
	ds_read_b128 v[222:225], v146 offset:50176
	ds_read_b128 v[226:229], v147 offset:49152
	ds_read_b128 v[230:233], v147 offset:50176
	ds_read_b128 v[238:241], v148 offset:49152
	ds_read_b128 v[242:245], v148 offset:50176
	s_or_b32 s35, s34, 0x80000
	s_mov_b32 m0, s16
	s_nop 0
	buffer_load_dwordx4 v131, s[48:51], s35 offen lds
	s_or_b32 s34, s34, 0xc0000
	s_mov_b32 m0, s17
	s_nop 0
	buffer_load_dwordx4 v131, s[48:51], s34 offen lds
	s_barrier
; #define STAGE_A(POFF, h, kt) STAGE_AX(POFF, h, kt, brow)
; #define STAGE_B(POFF, h, kt) STAGE_BX(POFF, h, kt, bcol)
; #define LDA(dst, b, h) _Pragma("unroll") for (int m = 0; m < 4; ++m) _Pragma("unroll") for (int k = 0; k < 2; ++k) \
;     dst[m][k] = *reinterpret_cast<const bf16x8*>((char*)SA(b, h) + lds_byte(wr * 64 + m * 16 + fr, k * 32 + fq * 8))
; #define LDB(dst, b, h) _Pragma("unroll") for (int n = 0; n < 2; ++n) _Pragma("unroll") for (int k = 0; k < 2; ++k) \
;     dst[n][k] = *reinterpret_cast<const bf16x8*>((char*)SB(b, h) + lds_byte(wc * 32 + n * 16 + fr, k * 32 + fq * 8))
; #define MMA(ai, bj, At_, Bt_) do { __builtin_amdgcn_s_setprio(1); \
;     _Pragma("unroll") for (int k = 0; k < 2; ++k) _Pragma("unroll") for (int m = 0; m < 4; ++m) _Pragma("unroll") for (int n = 0; n < 2; ++n) \
;       acc[ai][bj][m][n] = __builtin_amdgcn_mfma_f32_16x16x32_bf16(At_[m][k], Bt_[n][k], acc[ai][bj][m][n], 0, 0, 0); \
;     __builtin_amdgcn_s_setprio(0); } while (0)
; #define WAIT_V(n) asm volatile("s_waitcnt vmcnt(" #n ")" ::: "memory")
; #define BAR __builtin_amdgcn_s_barrier()
; #define SCHED __builtin_amdgcn_sched_barrier(0)
; template <int EPI, int N, int K>
; __device__ __forceinline__ void gemm_phase(const bf16_t* __restrict__ A, const bf16_t* __restrict__ Bt, const EpiArgs ea) {
;     ...
;       LDB(B0, 1, 0); SCHED; LDA(At, 1, 0); STAGE_A(SA_OFF(0, 1), 1, t + 2);
;       WAIT_L(8); BAR; WAIT_L(0); MMA(0, 0, At, B0); BAR; SCHED;
;       LDB(B1, 1, 1); STAGE_B(SB_OFF(1, 0), 0, t + 3);
;       BAR; WAIT_L(0); MMA(0, 1, At, B1); BAR;
;       LDA(At, 1, 1); STAGE_A(SA_OFF(1, 0), 0, t + 3);
;       BAR; WAIT_L(0); MMA(1, 0, At, B0); BAR; SCHED;
;       STAGE_B(SB_OFF(1, 1), 1, t + 3);
;       WAIT_V(6); BAR; MMA(1, 1, At, B1); BAR;
	s_waitcnt lgkmcnt(6)
	s_setprio 1
	v_mfma_f32_16x16x32_bf16 v[124:127], v[170:173], v[154:157], v[124:127]
	v_mfma_f32_16x16x32_bf16 v[120:123], v[170:173], v[162:165], v[120:123]
	v_mfma_f32_16x16x32_bf16 v[116:119], v[178:181], v[154:157], v[116:119]
	v_mfma_f32_16x16x32_bf16 v[112:115], v[178:181], v[162:165], v[112:115]
	v_mfma_f32_16x16x32_bf16 v[108:111], v[186:189], v[154:157], v[108:111]
	v_mfma_f32_16x16x32_bf16 v[104:107], v[186:189], v[162:165], v[104:107]
	v_mfma_f32_16x16x32_bf16 v[100:103], v[194:197], v[154:157], v[100:103]
	v_mfma_f32_16x16x32_bf16 v[96:99], v[194:197], v[162:165], v[96:99]
	v_mfma_f32_16x16x32_bf16 v[124:127], v[174:177], v[158:161], v[124:127]
	v_mfma_f32_16x16x32_bf16 v[120:123], v[174:177], v[166:169], v[120:123]
	v_mfma_f32_16x16x32_bf16 v[116:119], v[182:185], v[158:161], v[116:119]
	v_mfma_f32_16x16x32_bf16 v[112:115], v[182:185], v[166:169], v[112:115]
	v_mfma_f32_16x16x32_bf16 v[108:111], v[190:193], v[158:161], v[108:111]
	v_mfma_f32_16x16x32_bf16 v[104:107], v[190:193], v[166:169], v[104:107]
	v_mfma_f32_16x16x32_bf16 v[100:103], v[198:201], v[158:161], v[100:103]
	v_mfma_f32_16x16x32_bf16 v[96:99], v[198:201], v[166:169], v[96:99]
	s_setprio 0
	s_barrier
	ds_read_b128 v[202:205], v152
	ds_read_b128 v[206:209], v152 offset:1024
	ds_read_b128 v[210:213], v152 offset:2048
	ds_read_b128 v[214:217], v152 offset:3072
	ds_read_b128 v[246:249], v149 offset:49152
	ds_read_b128 v[250:253], v149 offset:50176
	s_add_i32 s34, s31, 0x180
	s_mov_b32 m0, s18
	s_nop 0
	buffer_load_dwordx4 v134, s[72:75], s34 offen lds
	s_add_i32 s34, s31, 0x80180
	s_mov_b32 m0, s19
	s_nop 0
	buffer_load_dwordx4 v134, s[72:75], s34 offen lds
	s_waitcnt vmcnt(6)
	s_barrier
	s_waitcnt lgkmcnt(2)
	s_setprio 1
	v_mfma_f32_16x16x32_bf16 v[92:95], v[170:173], v[202:205], v[92:95]
	v_mfma_f32_16x16x32_bf16 v[88:91], v[170:173], v[210:213], v[88:91]
	v_mfma_f32_16x16x32_bf16 v[84:87], v[178:181], v[202:205], v[84:87]
	v_mfma_f32_16x16x32_bf16 v[80:83], v[178:181], v[210:213], v[80:83]
	v_mfma_f32_16x16x32_bf16 v[76:79], v[186:189], v[202:205], v[76:79]
	v_mfma_f32_16x16x32_bf16 v[72:75], v[186:189], v[210:213], v[72:75]
	v_mfma_f32_16x16x32_bf16 v[68:71], v[194:197], v[202:205], v[68:71]
	v_mfma_f32_16x16x32_bf16 v[64:67], v[194:197], v[210:213], v[64:67]
	v_mfma_f32_16x16x32_bf16 v[92:95], v[174:177], v[206:209], v[92:95]
	v_mfma_f32_16x16x32_bf16 v[88:91], v[174:177], v[214:217], v[88:91]
	v_mfma_f32_16x16x32_bf16 v[84:87], v[182:185], v[206:209], v[84:87]
	v_mfma_f32_16x16x32_bf16 v[80:83], v[182:185], v[214:217], v[80:83]
	v_mfma_f32_16x16x32_bf16 v[76:79], v[190:193], v[206:209], v[76:79]
	v_mfma_f32_16x16x32_bf16 v[72:75], v[190:193], v[214:217], v[72:75]
	v_mfma_f32_16x16x32_bf16 v[68:71], v[198:201], v[206:209], v[68:71]
	v_mfma_f32_16x16x32_bf16 v[64:67], v[198:201], v[214:217], v[64:67]
	s_setprio 0
	s_barrier
	ds_read_b128 v[170:173], v146
	ds_read_b128 v[174:177], v146 offset:1024
	ds_read_b128 v[178:181], v147
	ds_read_b128 v[182:185], v147 offset:1024
	ds_read_b128 v[186:189], v148
	ds_read_b128 v[190:193], v148 offset:1024
	s_add_i32 s34, s30, 0x180
	s_mov_b32 m0, s20
	s_nop 0
	buffer_load_dwordx4 v131, s[48:51], s34 offen lds
	s_add_i32 s30, s30, 0x40180
	s_mov_b32 m0, s21
	s_nop 0
	buffer_load_dwordx4 v131, s[48:51], s30 offen lds
	s_waitcnt vmcnt(10)
	s_barrier
	s_waitcnt lgkmcnt(6)
	s_setprio 1
	v_mfma_f32_16x16x32_bf16 v[60:63], v[218:221], v[154:157], v[60:63]
	v_mfma_f32_16x16x32_bf16 v[56:59], v[218:221], v[162:165], v[56:59]
	v_mfma_f32_16x16x32_bf16 v[52:55], v[226:229], v[154:157], v[52:55]
	v_mfma_f32_16x16x32_bf16 v[48:51], v[226:229], v[162:165], v[48:51]
	v_mfma_f32_16x16x32_bf16 v[44:47], v[238:241], v[154:157], v[44:47]
	v_mfma_f32_16x16x32_bf16 v[40:43], v[238:241], v[162:165], v[40:43]
	v_mfma_f32_16x16x32_bf16 v[36:39], v[246:249], v[154:157], v[36:39]
	v_mfma_f32_16x16x32_bf16 v[32:35], v[246:249], v[162:165], v[32:35]
	v_mfma_f32_16x16x32_bf16 v[60:63], v[222:225], v[158:161], v[60:63]
	v_mfma_f32_16x16x32_bf16 v[56:59], v[222:225], v[166:169], v[56:59]
	v_mfma_f32_16x16x32_bf16 v[52:55], v[230:233], v[158:161], v[52:55]
	v_mfma_f32_16x16x32_bf16 v[48:51], v[230:233], v[166:169], v[48:51]
	v_mfma_f32_16x16x32_bf16 v[44:47], v[242:245], v[158:161], v[44:47]
	v_mfma_f32_16x16x32_bf16 v[40:43], v[242:245], v[166:169], v[40:43]
	v_mfma_f32_16x16x32_bf16 v[36:39], v[250:253], v[158:161], v[36:39]
	v_mfma_f32_16x16x32_bf16 v[32:35], v[250:253], v[166:169], v[32:35]
	s_setprio 0
	s_barrier
	ds_read_b128 v[154:157], v145
	ds_read_b128 v[158:161], v145 offset:1024
	ds_read_b128 v[162:165], v145 offset:2048
	ds_read_b128 v[166:169], v145 offset:3072
	ds_read_b128 v[194:197], v149
	ds_read_b128 v[198:201], v149 offset:1024
	s_add_i32 s30, s31, 0x2180
	s_mov_b32 m0, s22
	s_nop 0
	buffer_load_dwordx4 v134, s[72:75], s30 offen lds
	s_add_i32 s31, s31, 0x82180
	s_mov_b32 m0, s23
	s_nop 0
	buffer_load_dwordx4 v134, s[72:75], s31 offen lds
	s_waitcnt vmcnt(6)
	s_barrier
	s_setprio 1
	v_mfma_f32_16x16x32_bf16 v[28:31], v[218:221], v[202:205], v[28:31]
	v_mfma_f32_16x16x32_bf16 v[24:27], v[218:221], v[210:213], v[24:27]
	v_mfma_f32_16x16x32_bf16 v[20:23], v[226:229], v[202:205], v[20:23]
	v_mfma_f32_16x16x32_bf16 v[16:19], v[226:229], v[210:213], v[16:19]
	v_mfma_f32_16x16x32_bf16 v[12:15], v[238:241], v[202:205], v[12:15]
	v_mfma_f32_16x16x32_bf16 v[8:11], v[238:241], v[210:213], v[8:11]
	v_mfma_f32_16x16x32_bf16 v[4:7], v[246:249], v[202:205], v[4:7]
	v_mfma_f32_16x16x32_bf16 v[0:3], v[246:249], v[210:213], v[0:3]
	v_mfma_f32_16x16x32_bf16 v[28:31], v[222:225], v[206:209], v[28:31]
	v_mfma_f32_16x16x32_bf16 v[24:27], v[222:225], v[214:217], v[24:27]
	v_mfma_f32_16x16x32_bf16 v[20:23], v[230:233], v[206:209], v[20:23]
	v_mfma_f32_16x16x32_bf16 v[16:19], v[230:233], v[214:217], v[16:19]
	v_mfma_f32_16x16x32_bf16 v[12:15], v[242:245], v[206:209], v[12:15]
	v_mfma_f32_16x16x32_bf16 v[8:11], v[242:245], v[214:217], v[8:11]
	v_mfma_f32_16x16x32_bf16 v[4:7], v[250:253], v[206:209], v[4:7]
	v_mfma_f32_16x16x32_bf16 v[0:3], v[250:253], v[214:217], v[0:3]
	s_setprio 0
	s_add_i32 s28, s28, 2
	s_addk_i32 s29, 0x100
	s_cmp_lt_u32 s28, 28
	s_barrier
; #define STAGE_A(POFF, h, kt) STAGE_AX(POFF, h, kt, brow)
; #define LDA(dst, b, h) _Pragma("unroll") for (int m = 0; m < 4; ++m) _Pragma("unroll") for (int k = 0; k < 2; ++k) \
;     dst[m][k] = *reinterpret_cast<const bf16x8*>((char*)SA(b, h) + lds_byte(wr * 64 + m * 16 + fr, k * 32 + fq * 8))
; #define LDB(dst, b, h) _Pragma("unroll") for (int n = 0; n < 2; ++n) _Pragma("unroll") for (int k = 0; k < 2; ++k) \
;     dst[n][k] = *reinterpret_cast<const bf16x8*>((char*)SB(b, h) + lds_byte(wc * 32 + n * 16 + fr, k * 32 + fq * 8))
; #define MMA(ai, bj, At_, Bt_) do { __builtin_amdgcn_s_setprio(1); \
;     _Pragma("unroll") for (int k = 0; k < 2; ++k) _Pragma("unroll") for (int m = 0; m < 4; ++m) _Pragma("unroll") for (int n = 0; n < 2; ++n) \
;       acc[ai][bj][m][n] = __builtin_amdgcn_mfma_f32_16x16x32_bf16(At_[m][k], Bt_[n][k], acc[ai][bj][m][n], 0, 0, 0); \
;     __builtin_amdgcn_s_setprio(0); } while (0)
; #define WAIT_V(n) asm volatile("s_waitcnt vmcnt(" #n ")" ::: "memory")
; #define BAR __builtin_amdgcn_s_barrier()
; template <int EPI, int N, int K>
; __device__ __forceinline__ void gemm_phase(const bf16_t* __restrict__ A, const bf16_t* __restrict__ Bt, const EpiArgs ea) {
;     ...
;     { LDB(B0, 0, 0); LDA(At, 0, 0); STAGE_A(SA_OFF(1, 1), 1, nt - 1);
;       BAR; WAIT_L(0); MMA(0, 0, At, B0); BAR;
;       LDB(B1, 0, 1); BAR; WAIT_L(0); MMA(0, 1, At, B1); BAR;
;       LDA(At, 0, 1); WAIT_V(4); BAR; WAIT_L(0); MMA(1, 0, At, B0); MMA(1, 1, At, B1); BAR; }
	s_cbranch_scc1 .LBB0_133
	s_and_b32 s1, s1, 0x700
	s_lshl_b32 s0, s0, 11
	s_or_b32 s27, s1, s0
	s_lshl_b32 s0, s27, 12
	s_or_b32 s1, s0, 0x80f80
	s_mov_b32 m0, s24
	s_nop 0
	buffer_load_dwordx4 v131, s[48:51], s1 offen lds
	s_or_b32 s0, s0, 0xc0f80
	s_mov_b32 m0, s25
	s_nop 0
	buffer_load_dwordx4 v131, s[48:51], s0 offen lds
	s_barrier
	s_waitcnt lgkmcnt(0)
	s_setprio 1
	v_mfma_f32_16x16x32_bf16 v[124:127], v[170:173], v[154:157], v[124:127]
	v_mfma_f32_16x16x32_bf16 v[120:123], v[170:173], v[162:165], v[120:123]
	v_mfma_f32_16x16x32_bf16 v[116:119], v[178:181], v[154:157], v[116:119]
	v_mfma_f32_16x16x32_bf16 v[112:115], v[178:181], v[162:165], v[112:115]
	v_mfma_f32_16x16x32_bf16 v[108:111], v[186:189], v[154:157], v[108:111]
	v_mfma_f32_16x16x32_bf16 v[104:107], v[186:189], v[162:165], v[104:107]
	v_mfma_f32_16x16x32_bf16 v[100:103], v[194:197], v[154:157], v[100:103]
	v_mfma_f32_16x16x32_bf16 v[96:99], v[194:197], v[162:165], v[96:99]
	v_mfma_f32_16x16x32_bf16 v[124:127], v[174:177], v[158:161], v[124:127]
	v_mfma_f32_16x16x32_bf16 v[120:123], v[174:177], v[166:169], v[120:123]
	v_mfma_f32_16x16x32_bf16 v[116:119], v[182:185], v[158:161], v[116:119]
	v_mfma_f32_16x16x32_bf16 v[112:115], v[182:185], v[166:169], v[112:115]
	v_mfma_f32_16x16x32_bf16 v[108:111], v[190:193], v[158:161], v[108:111]
	v_mfma_f32_16x16x32_bf16 v[104:107], v[190:193], v[166:169], v[104:107]
	v_mfma_f32_16x16x32_bf16 v[100:103], v[198:201], v[158:161], v[100:103]
	v_mfma_f32_16x16x32_bf16 v[96:99], v[198:201], v[166:169], v[96:99]
	s_setprio 0
	s_barrier
	ds_read_b128 v[202:205], v150
	ds_read_b128 v[206:209], v150 offset:1024
	ds_read_b128 v[210:213], v150 offset:2048
	ds_read_b128 v[214:217], v150 offset:3072
	s_barrier
	s_waitcnt lgkmcnt(0)
	s_setprio 1
	v_mfma_f32_16x16x32_bf16 v[92:95], v[170:173], v[202:205], v[92:95]
	v_mfma_f32_16x16x32_bf16 v[88:91], v[170:173], v[210:213], v[88:91]
	v_mfma_f32_16x16x32_bf16 v[76:79], v[186:189], v[202:205], v[76:79]
	v_mfma_f32_16x16x32_bf16 v[72:75], v[186:189], v[210:213], v[72:75]
	v_mfma_f32_16x16x32_bf16 v[68:71], v[194:197], v[202:205], v[68:71]
	v_mfma_f32_16x16x32_bf16 v[64:67], v[194:197], v[210:213], v[64:67]
	v_mfma_f32_16x16x32_bf16 v[84:87], v[178:181], v[202:205], v[84:87]
	v_mfma_f32_16x16x32_bf16 v[80:83], v[178:181], v[210:213], v[80:83]
	v_mfma_f32_16x16x32_bf16 v[92:95], v[174:177], v[206:209], v[92:95]
	v_mfma_f32_16x16x32_bf16 v[88:91], v[174:177], v[214:217], v[88:91]
	v_mfma_f32_16x16x32_bf16 v[76:79], v[190:193], v[206:209], v[76:79]
	v_mfma_f32_16x16x32_bf16 v[72:75], v[190:193], v[214:217], v[72:75]
	v_mfma_f32_16x16x32_bf16 v[68:71], v[198:201], v[206:209], v[68:71]
	v_mfma_f32_16x16x32_bf16 v[64:67], v[198:201], v[214:217], v[64:67]
	v_mfma_f32_16x16x32_bf16 v[170:173], v[182:185], v[206:209], v[84:87]
	v_mfma_f32_16x16x32_bf16 v[174:177], v[182:185], v[214:217], v[80:83]
	s_setprio 0
	s_barrier
	s_nop 0
	ds_read_b128 v[80:83], v146 offset:16384
	ds_read_b128 v[84:87], v146 offset:17408
	ds_read_b128 v[178:181], v147 offset:16384
	ds_read_b128 v[182:185], v147 offset:17408
	ds_read_b128 v[186:189], v148 offset:16384
	ds_read_b128 v[190:193], v148 offset:17408
	ds_read_b128 v[194:197], v149 offset:16384
	ds_read_b128 v[198:201], v149 offset:17408
	s_waitcnt vmcnt(4)
	s_barrier
	s_waitcnt lgkmcnt(0)
	s_setprio 1
	v_mfma_f32_16x16x32_bf16 v[52:55], v[178:181], v[154:157], v[52:55]
	v_mfma_f32_16x16x32_bf16 v[48:51], v[178:181], v[162:165], v[48:51]
	v_mfma_f32_16x16x32_bf16 v[44:47], v[186:189], v[154:157], v[44:47]
	v_mfma_f32_16x16x32_bf16 v[40:43], v[186:189], v[162:165], v[40:43]
	v_mfma_f32_16x16x32_bf16 v[36:39], v[194:197], v[154:157], v[36:39]
	v_mfma_f32_16x16x32_bf16 v[32:35], v[194:197], v[162:165], v[32:35]
	v_mfma_f32_16x16x32_bf16 v[60:63], v[80:83], v[154:157], v[60:63]
	v_mfma_f32_16x16x32_bf16 v[56:59], v[80:83], v[162:165], v[56:59]
	v_mfma_f32_16x16x32_bf16 v[52:55], v[182:185], v[158:161], v[52:55]
	v_mfma_f32_16x16x32_bf16 v[48:51], v[182:185], v[166:169], v[48:51]
	v_mfma_f32_16x16x32_bf16 v[44:47], v[190:193], v[158:161], v[44:47]
	v_mfma_f32_16x16x32_bf16 v[40:43], v[190:193], v[166:169], v[40:43]
	v_mfma_f32_16x16x32_bf16 v[36:39], v[198:201], v[158:161], v[36:39]
	v_mfma_f32_16x16x32_bf16 v[32:35], v[198:201], v[166:169], v[32:35]
	v_mfma_f32_16x16x32_bf16 v[154:157], v[84:87], v[158:161], v[60:63]
	v_mfma_f32_16x16x32_bf16 v[162:165], v[84:87], v[166:169], v[56:59]
	s_setprio 0
	s_setprio 1
	v_mfma_f32_16x16x32_bf16 v[28:31], v[80:83], v[202:205], v[28:31]
	v_mfma_f32_16x16x32_bf16 v[24:27], v[80:83], v[210:213], v[24:27]
	v_mfma_f32_16x16x32_bf16 v[12:15], v[186:189], v[202:205], v[12:15]
	v_mfma_f32_16x16x32_bf16 v[8:11], v[186:189], v[210:213], v[8:11]
	v_mfma_f32_16x16x32_bf16 v[20:23], v[178:181], v[202:205], v[20:23]
	v_mfma_f32_16x16x32_bf16 v[16:19], v[178:181], v[210:213], v[16:19]
	v_mfma_f32_16x16x32_bf16 v[4:7], v[194:197], v[202:205], v[4:7]
	v_mfma_f32_16x16x32_bf16 v[0:3], v[194:197], v[210:213], v[0:3]
	v_mfma_f32_16x16x32_bf16 v[28:31], v[84:87], v[206:209], v[28:31]
	v_mfma_f32_16x16x32_bf16 v[24:27], v[84:87], v[214:217], v[24:27]
	v_mfma_f32_16x16x32_bf16 v[12:15], v[190:193], v[206:209], v[12:15]
	v_mfma_f32_16x16x32_bf16 v[8:11], v[190:193], v[214:217], v[8:11]
	v_mfma_f32_16x16x32_bf16 v[158:161], v[182:185], v[206:209], v[20:23]
	v_mfma_f32_16x16x32_bf16 v[166:169], v[182:185], v[214:217], v[16:19]
	v_mfma_f32_16x16x32_bf16 v[178:181], v[198:201], v[206:209], v[4:7]
	v_mfma_f32_16x16x32_bf16 v[182:185], v[198:201], v[214:217], v[0:3]
	s_setprio 0
	s_barrier
; #define LDA(dst, b, h) _Pragma("unroll") for (int m = 0; m < 4; ++m) _Pragma("unroll") for (int k = 0; k < 2; ++k) \
;     dst[m][k] = *reinterpret_cast<const bf16x8*>((char*)SA(b, h) + lds_byte(wr * 64 + m * 16 + fr, k * 32 + fq * 8))
; #define LDB(dst, b, h) _Pragma("unroll") for (int n = 0; n < 2; ++n) _Pragma("unroll") for (int k = 0; k < 2; ++k) \
;     dst[n][k] = *reinterpret_cast<const bf16x8*>((char*)SB(b, h) + lds_byte(wc * 32 + n * 16 + fr, k * 32 + fq * 8))
; #define MMA(ai, bj, At_, Bt_) do { __builtin_amdgcn_s_setprio(1); \
;     _Pragma("unroll") for (int k = 0; k < 2; ++k) _Pragma("unroll") for (int m = 0; m < 4; ++m) _Pragma("unroll") for (int n = 0; n < 2; ++n) \
;       acc[ai][bj][m][n] = __builtin_amdgcn_mfma_f32_16x16x32_bf16(At_[m][k], Bt_[n][k], acc[ai][bj][m][n], 0, 0, 0); \
;     __builtin_amdgcn_s_setprio(0); } while (0)
; #define WAIT_V(n) asm volatile("s_waitcnt vmcnt(" #n ")" ::: "memory")
; #define BAR __builtin_amdgcn_s_barrier()
; template <int EPI, int N, int K>
; __device__ __forceinline__ void gemm_phase(const bf16_t* __restrict__ A, const bf16_t* __restrict__ Bt, const EpiArgs ea) {
;     ...
;     { LDB(B0, 1, 0); LDA(At, 1, 0); WAIT_V(2); BAR; WAIT_L(0); MMA(0, 0, At, B0); BAR;
;       LDB(B1, 1, 1); WAIT_V(0); BAR; WAIT_L(0); MMA(0, 1, At, B1); BAR;
;       LDA(At, 1, 1); BAR; WAIT_L(0); MMA(1, 0, At, B0); MMA(1, 1, At, B1); BAR; }
;     if (wr == 0) BAR;
	s_nop 0
	ds_read_b128 v[0:3], v151
	ds_read_b128 v[4:7], v151 offset:1024
	ds_read_b128 v[16:19], v151 offset:2048
	ds_read_b128 v[186:189], v151 offset:3072
	ds_read_b128 v[20:23], v146 offset:32768
	ds_read_b128 v[190:193], v146 offset:33792
	ds_read_b128 v[194:197], v147 offset:32768
	ds_read_b128 v[198:201], v147 offset:33792
	ds_read_b128 v[202:205], v148 offset:32768
	ds_read_b128 v[206:209], v148 offset:33792
	ds_read_b128 v[210:213], v149 offset:32768
	ds_read_b128 v[214:217], v149 offset:33792
	s_waitcnt vmcnt(2)
	s_barrier
	s_waitcnt lgkmcnt(0)
	s_setprio 1
	v_mfma_f32_16x16x32_bf16 v[56:59], v[20:23], v[0:3], v[124:127]
	v_mfma_f32_16x16x32_bf16 v[60:63], v[20:23], v[16:19], v[120:123]
	v_mfma_f32_16x16x32_bf16 v[80:83], v[194:197], v[0:3], v[116:119]
	v_mfma_f32_16x16x32_bf16 v[84:87], v[194:197], v[16:19], v[112:115]
	v_mfma_f32_16x16x32_bf16 v[108:111], v[202:205], v[0:3], v[108:111]
	v_mfma_f32_16x16x32_bf16 v[104:107], v[202:205], v[16:19], v[104:107]
	v_mfma_f32_16x16x32_bf16 v[120:123], v[210:213], v[0:3], v[100:103]
	v_mfma_f32_16x16x32_bf16 v[124:127], v[210:213], v[16:19], v[96:99]
	v_mfma_f32_16x16x32_bf16 v[116:119], v[190:193], v[4:7], v[56:59]
	v_mfma_f32_16x16x32_bf16 v[112:115], v[190:193], v[186:189], v[60:63]
	v_mfma_f32_16x16x32_bf16 v[100:103], v[198:201], v[4:7], v[80:83]
	v_mfma_f32_16x16x32_bf16 v[96:99], v[198:201], v[186:189], v[84:87]
	v_mfma_f32_16x16x32_bf16 v[84:87], v[206:209], v[4:7], v[108:111]
	v_mfma_f32_16x16x32_bf16 v[80:83], v[206:209], v[186:189], v[104:107]
	v_mfma_f32_16x16x32_bf16 v[60:63], v[214:217], v[4:7], v[120:123]
	v_mfma_f32_16x16x32_bf16 v[56:59], v[214:217], v[186:189], v[124:127]
	s_setprio 0
	s_barrier
	ds_read_b128 v[218:221], v152
	ds_read_b128 v[222:225], v152 offset:1024
	ds_read_b128 v[226:229], v152 offset:2048
	ds_read_b128 v[230:233], v152 offset:3072
	s_waitcnt vmcnt(0)
	s_barrier
	s_waitcnt lgkmcnt(0)
	s_setprio 1
	v_mfma_f32_16x16x32_bf16 v[92:95], v[20:23], v[218:221], v[92:95]
	v_mfma_f32_16x16x32_bf16 v[20:23], v[20:23], v[226:229], v[88:91]
	v_mfma_f32_16x16x32_bf16 v[88:91], v[194:197], v[218:221], v[170:173]
	v_mfma_f32_16x16x32_bf16 v[104:107], v[194:197], v[226:229], v[174:177]
	v_mfma_f32_16x16x32_bf16 v[76:79], v[202:205], v[218:221], v[76:79]
	v_mfma_f32_16x16x32_bf16 v[72:75], v[202:205], v[226:229], v[72:75]
	v_mfma_f32_16x16x32_bf16 v[68:71], v[210:213], v[218:221], v[68:71]
	v_mfma_f32_16x16x32_bf16 v[64:67], v[210:213], v[226:229], v[64:67]
	v_mfma_f32_16x16x32_bf16 v[124:127], v[190:193], v[222:225], v[92:95]
	v_mfma_f32_16x16x32_bf16 v[120:123], v[190:193], v[230:233], v[20:23]
	v_mfma_f32_16x16x32_bf16 v[108:111], v[198:201], v[222:225], v[88:91]
	v_mfma_f32_16x16x32_bf16 v[104:107], v[198:201], v[230:233], v[104:107]
	v_mfma_f32_16x16x32_bf16 v[92:95], v[206:209], v[222:225], v[76:79]
	v_mfma_f32_16x16x32_bf16 v[88:91], v[206:209], v[230:233], v[72:75]
	v_mfma_f32_16x16x32_bf16 v[76:79], v[214:217], v[222:225], v[68:71]
	v_mfma_f32_16x16x32_bf16 v[72:75], v[214:217], v[230:233], v[64:67]
	s_setprio 0
	s_barrier
	s_nop 0
	ds_read_b128 v[64:67], v146 offset:49152
	ds_read_b128 v[170:173], v146 offset:50176
	ds_read_b128 v[68:71], v147 offset:49152
	ds_read_b128 v[174:177], v147 offset:50176
	ds_read_b128 v[190:193], v148 offset:49152
	ds_read_b128 v[194:197], v148 offset:50176
	ds_read_b128 v[198:201], v149 offset:49152
	ds_read_b128 v[202:205], v149 offset:50176
	s_barrier
	s_waitcnt lgkmcnt(0)
	s_setprio 1
	v_mfma_f32_16x16x32_bf16 v[20:23], v[64:67], v[0:3], v[154:157]
	v_mfma_f32_16x16x32_bf16 v[154:157], v[64:67], v[16:19], v[162:165]
	v_mfma_f32_16x16x32_bf16 v[162:165], v[68:71], v[0:3], v[52:55]
	v_mfma_f32_16x16x32_bf16 v[206:209], v[68:71], v[16:19], v[48:51]
	v_mfma_f32_16x16x32_bf16 v[44:47], v[190:193], v[0:3], v[44:47]
	v_mfma_f32_16x16x32_bf16 v[40:43], v[190:193], v[16:19], v[40:43]
	v_mfma_f32_16x16x32_bf16 v[0:3], v[198:201], v[0:3], v[36:39]
	v_mfma_f32_16x16x32_bf16 v[210:213], v[198:201], v[16:19], v[32:35]
	v_mfma_f32_16x16x32_bf16 v[52:55], v[170:173], v[4:7], v[20:23]
	v_mfma_f32_16x16x32_bf16 v[48:51], v[170:173], v[186:189], v[154:157]
	v_mfma_f32_16x16x32_bf16 v[36:39], v[174:177], v[4:7], v[162:165]
	v_mfma_f32_16x16x32_bf16 v[32:35], v[174:177], v[186:189], v[206:209]
	v_mfma_f32_16x16x32_bf16 v[20:23], v[194:197], v[4:7], v[44:47]
	v_mfma_f32_16x16x32_bf16 v[16:19], v[194:197], v[186:189], v[40:43]
	v_mfma_f32_16x16x32_bf16 v[4:7], v[202:205], v[4:7], v[0:3]
	v_mfma_f32_16x16x32_bf16 v[0:3], v[202:205], v[186:189], v[210:213]
	s_setprio 0
	s_setprio 1
	v_mfma_f32_16x16x32_bf16 v[28:31], v[64:67], v[218:221], v[28:31]
	v_mfma_f32_16x16x32_bf16 v[24:27], v[64:67], v[226:229], v[24:27]
	v_mfma_f32_16x16x32_bf16 v[40:43], v[68:71], v[218:221], v[158:161]
	v_mfma_f32_16x16x32_bf16 v[154:157], v[68:71], v[226:229], v[166:169]
	v_mfma_f32_16x16x32_bf16 v[12:15], v[190:193], v[218:221], v[12:15]
	v_mfma_f32_16x16x32_bf16 v[8:11], v[190:193], v[226:229], v[8:11]
	v_mfma_f32_16x16x32_bf16 v[158:161], v[198:201], v[218:221], v[178:181]
	v_mfma_f32_16x16x32_bf16 v[162:165], v[198:201], v[226:229], v[182:185]
	v_mfma_f32_16x16x32_bf16 v[68:71], v[170:173], v[222:225], v[28:31]
	v_mfma_f32_16x16x32_bf16 v[64:67], v[170:173], v[230:233], v[24:27]
	v_mfma_f32_16x16x32_bf16 v[44:47], v[174:177], v[222:225], v[40:43]
	v_mfma_f32_16x16x32_bf16 v[40:43], v[174:177], v[230:233], v[154:157]
	v_mfma_f32_16x16x32_bf16 v[28:31], v[194:197], v[222:225], v[12:15]
	v_mfma_f32_16x16x32_bf16 v[24:27], v[194:197], v[230:233], v[8:11]
	v_mfma_f32_16x16x32_bf16 v[12:15], v[202:205], v[222:225], v[158:161]
	v_mfma_f32_16x16x32_bf16 v[8:11], v[202:205], v[230:233], v[162:165]
	s_setprio 0
	s_barrier
	s_and_saveexec_b64 s[0:1], s[6:7]
	s_cbranch_execz .LBB0_136
	s_barrier

; #define STAGE_A(POFF, h, kt) STAGE_AX(POFF, h, kt, brow)
; #define LDA(dst, b, h) _Pragma("unroll") for (int m = 0; m < 4; ++m) _Pragma("unroll") for (int k = 0; k < 2; ++k) \
;     dst[m][k] = *reinterpret_cast<const bf16x8*>((char*)SA(b, h) + lds_byte(wr * 64 + m * 16 + fr, k * 32 + fq * 8))
; #define LDB(dst, b, h) _Pragma("unroll") for (int n = 0; n < 2; ++n) _Pragma("unroll") for (int k = 0; k < 2; ++k) \
;     dst[n][k] = *reinterpret_cast<const bf16x8*>((char*)SB(b, h) + lds_byte(wc * 32 + n * 16 + fr, k * 32 + fq * 8))
; #define MMA(ai, bj, At_, Bt_) do { __builtin_amdgcn_s_setprio(1); \
;     _Pragma("unroll") for (int k = 0; k < 2; ++k) _Pragma("unroll") for (int m = 0; m < 4; ++m) _Pragma("unroll") for (int n = 0; n < 2; ++n) \
;       acc[ai][bj][m][n] = __builtin_amdgcn_mfma_f32_16x16x32_bf16(At_[m][k], Bt_[n][k], acc[ai][bj][m][n], 0, 0, 0); \
;     __builtin_amdgcn_s_setprio(0); } while (0)
; #define WAIT_V(n) asm volatile("s_waitcnt vmcnt(" #n ")" ::: "memory")
; #define BAR __builtin_amdgcn_s_barrier()
; #define SCHED __builtin_amdgcn_sched_barrier(0)
; #define TILE_RC(w_, brow_, bcol_) do { const int wg_ = ((w_) & 7) * qx + ((w_) >> 3); const int gid_ = wg_ / nig; \
;     brow_ = (gid_ * 8 + ((wg_ % nig) & 7)) * 256; bcol_ = ((wg_ % nig) >> 3) * 256; } while (0)
; template <int EPI, int N, int K>
; __device__ __forceinline__ void gemm_phase(const bf16_t* __restrict__ A, const bf16_t* __restrict__ Bt, const EpiArgs ea) {
;     ...
;   for (int w = blockIdx.x; w < nwg; w += gridDim.x) {
;     int brow, bcol; TILE_RC(w, brow, bcol);
;     f32x4 acc[2][2][4][2];
; #pragma unroll
;     for (int a = 0; a < 2; ++a)
; #pragma unroll
;       for (int b = 0; b < 2; ++b)
; #pragma unroll
;         for (int m = 0; m < 4; ++m)
; #pragma unroll
;           for (int n = 0; n < 2; ++n) acc[a][b][m][n] = (f32x4){0.f, 0.f, 0.f, 0.f};
;     bf16x8 At[4][2], B0[2][2], B1[2][2];
;     if (wr == 1) BAR;
;     if (w == (int)blockIdx.x) { WAIT_V(0); } else { WAIT_V(24); }
;     BAR;
;     BAR;
;     for (int t = 0; t < nt - 2; t += 2) {
;       LDB(B0, 0, 0); SCHED; LDA(At, 0, 0); STAGE_A(SA_OFF(1, 1), 1, t + 1);
;       WAIT_L(8); BAR; WAIT_L(0); MMA(0, 0, At, B0); BAR; SCHED;
.LBB0_269:
	s_and_b32 s0, s26, 7
	s_mulk_i32 s0, 0x50
	s_ashr_i32 s1, s26, 3
	s_add_i32 s1, s0, s1
	s_mul_hi_i32 s0, s1, 0x66666667
	s_lshr_b32 s2, s0, 31
	s_ashr_i32 s0, s0, 5
	s_add_i32 s0, s0, s2
	s_mul_i32 s2, s0, 0x50
	s_sub_i32 s27, s1, s2
	s_lshl_b32 s1, s27, 8
	s_lshl_b32 s2, s27, 5
	s_lshl_b32 s3, s27, 17
	s_and_b32 s27, s27, 7
	s_lshl_b32 s28, s0, 23
	s_lshl_b32 s27, s27, 20
	v_mov_b32_e32 v0, 0
	s_barrier
	s_barrier
	s_and_b32 s3, s3, 0xfff00000
	s_or_b32 s27, s28, s27
	s_mov_b32 s28, -2
	s_mov_b32 s29, 0
	v_mov_b32_e32 v1, v0
	v_mov_b32_e32 v2, v0
	v_mov_b32_e32 v3, v0
	v_mov_b32_e32 v4, v0
	v_mov_b32_e32 v5, v0
	v_mov_b32_e32 v6, v0
	v_mov_b32_e32 v7, v0
	v_mov_b32_e32 v8, v0
	v_mov_b32_e32 v9, v0
	v_mov_b32_e32 v10, v0
	v_mov_b32_e32 v11, v0
	v_mov_b32_e32 v12, v0
	v_mov_b32_e32 v13, v0
	v_mov_b32_e32 v14, v0
	v_mov_b32_e32 v15, v0
	v_mov_b32_e32 v16, v0
	v_mov_b32_e32 v17, v0
	v_mov_b32_e32 v18, v0
	v_mov_b32_e32 v19, v0
	v_mov_b32_e32 v20, v0
	v_mov_b32_e32 v21, v0
	v_mov_b32_e32 v22, v0
	v_mov_b32_e32 v23, v0
	v_mov_b32_e32 v24, v0
	v_mov_b32_e32 v25, v0
	v_mov_b32_e32 v26, v0
	v_mov_b32_e32 v27, v0
	v_mov_b32_e32 v28, v0
	v_mov_b32_e32 v29, v0
	v_mov_b32_e32 v30, v0
	v_mov_b32_e32 v31, v0
	v_mov_b32_e32 v32, v0
	v_mov_b32_e32 v33, v0
	v_mov_b32_e32 v34, v0
	v_mov_b32_e32 v35, v0
	v_mov_b32_e32 v36, v0
	v_mov_b32_e32 v37, v0
	v_mov_b32_e32 v38, v0
	v_mov_b32_e32 v39, v0
	v_mov_b32_e32 v40, v0
	v_mov_b32_e32 v41, v0
	v_mov_b32_e32 v42, v0
	v_mov_b32_e32 v43, v0
	v_mov_b32_e32 v44, v0
	v_mov_b32_e32 v45, v0
	v_mov_b32_e32 v46, v0
	v_mov_b32_e32 v47, v0
	v_mov_b32_e32 v48, v0
	v_mov_b32_e32 v49, v0
	v_mov_b32_e32 v50, v0
	v_mov_b32_e32 v51, v0
	v_mov_b32_e32 v52, v0
	v_mov_b32_e32 v53, v0
	v_mov_b32_e32 v54, v0
	v_mov_b32_e32 v55, v0
	v_mov_b32_e32 v56, v0
	v_mov_b32_e32 v57, v0
	v_mov_b32_e32 v58, v0
	v_mov_b32_e32 v59, v0
	v_mov_b32_e32 v60, v0
	v_mov_b32_e32 v61, v0
	v_mov_b32_e32 v62, v0
	v_mov_b32_e32 v63, v0
	v_mov_b32_e32 v64, v0
	v_mov_b32_e32 v65, v0
	v_mov_b32_e32 v66, v0
	v_mov_b32_e32 v67, v0
	v_mov_b32_e32 v68, v0
	v_mov_b32_e32 v69, v0
	v_mov_b32_e32 v70, v0
	v_mov_b32_e32 v71, v0
	v_mov_b32_e32 v72, v0
	v_mov_b32_e32 v73, v0
	v_mov_b32_e32 v74, v0
	v_mov_b32_e32 v75, v0
	v_mov_b32_e32 v76, v0
	v_mov_b32_e32 v77, v0
	v_mov_b32_e32 v78, v0
	v_mov_b32_e32 v79, v0
	v_mov_b32_e32 v80, v0
	v_mov_b32_e32 v81, v0
	v_mov_b32_e32 v82, v0
	v_mov_b32_e32 v83, v0
	v_mov_b32_e32 v84, v0
	v_mov_b32_e32 v85, v0
	v_mov_b32_e32 v86, v0
	v_mov_b32_e32 v87, v0
	v_mov_b32_e32 v88, v0
	v_mov_b32_e32 v89, v0
	v_mov_b32_e32 v90, v0
	v_mov_b32_e32 v91, v0
	v_mov_b32_e32 v92, v0
	v_mov_b32_e32 v93, v0
	v_mov_b32_e32 v94, v0
	v_mov_b32_e32 v95, v0
	v_mov_b32_e32 v96, v0
	v_mov_b32_e32 v97, v0
	v_mov_b32_e32 v98, v0
	v_mov_b32_e32 v99, v0
	v_mov_b32_e32 v100, v0
	v_mov_b32_e32 v101, v0
	v_mov_b32_e32 v102, v0
	v_mov_b32_e32 v103, v0
	v_mov_b32_e32 v104, v0
	v_mov_b32_e32 v105, v0
	v_mov_b32_e32 v106, v0
	v_mov_b32_e32 v107, v0
	v_mov_b32_e32 v108, v0
	v_mov_b32_e32 v109, v0
	v_mov_b32_e32 v110, v0
	v_mov_b32_e32 v111, v0
	v_mov_b32_e32 v112, v0
	v_mov_b32_e32 v113, v0
	v_mov_b32_e32 v114, v0
	v_mov_b32_e32 v115, v0
	v_mov_b32_e32 v116, v0
	v_mov_b32_e32 v117, v0
	v_mov_b32_e32 v118, v0
	v_mov_b32_e32 v119, v0
	v_mov_b32_e32 v120, v0
	v_mov_b32_e32 v121, v0
	v_mov_b32_e32 v122, v0
	v_mov_b32_e32 v123, v0
	v_mov_b32_e32 v124, v0
	v_mov_b32_e32 v125, v0
	v_mov_b32_e32 v126, v0
	v_mov_b32_e32 v127, v0
	ds_read_b128 v[154:157], v145
	ds_read_b128 v[158:161], v145 offset:1024
	ds_read_b128 v[162:165], v145 offset:2048
	ds_read_b128 v[166:169], v145 offset:3072
	ds_read_b128 v[170:173], v146
	ds_read_b128 v[174:177], v146 offset:1024
	ds_read_b128 v[178:181], v147
	ds_read_b128 v[182:185], v147 offset:1024
	ds_read_b128 v[186:189], v148
	ds_read_b128 v[190:193], v148 offset:1024
	ds_read_b128 v[194:197], v149
	ds_read_b128 v[198:201], v149 offset:1024
.LBB0_270:
	ds_read_b128 v[218:221], v146 offset:16384
	ds_read_b128 v[222:225], v146 offset:17408
	ds_read_b128 v[226:229], v147 offset:16384
	ds_read_b128 v[230:233], v147 offset:17408
	ds_read_b128 v[238:241], v148 offset:16384
	ds_read_b128 v[242:245], v148 offset:17408
	s_add_i32 s30, s27, s29
	s_or_b32 s31, s30, 0x80080
	s_mov_b32 m0, s24
	s_nop 0
	buffer_load_dwordx4 v131, s[48:51], s31 offen lds
	s_or_b32 s31, s30, 0xc0080
	s_mov_b32 m0, s25
	s_nop 0
	buffer_load_dwordx4 v131, s[48:51], s31 offen lds
	s_barrier
	s_waitcnt lgkmcnt(6)
	s_setprio 1
	v_mfma_f32_16x16x32_bf16 v[124:127], v[170:173], v[154:157], v[124:127]
	v_mfma_f32_16x16x32_bf16 v[120:123], v[170:173], v[162:165], v[120:123]
	v_mfma_f32_16x16x32_bf16 v[116:119], v[178:181], v[154:157], v[116:119]
	v_mfma_f32_16x16x32_bf16 v[112:115], v[178:181], v[162:165], v[112:115]
	v_mfma_f32_16x16x32_bf16 v[108:111], v[186:189], v[154:157], v[108:111]
	v_mfma_f32_16x16x32_bf16 v[104:107], v[186:189], v[162:165], v[104:107]
	v_mfma_f32_16x16x32_bf16 v[100:103], v[194:197], v[154:157], v[100:103]
	v_mfma_f32_16x16x32_bf16 v[96:99], v[194:197], v[162:165], v[96:99]
	v_mfma_f32_16x16x32_bf16 v[124:127], v[174:177], v[158:161], v[124:127]
	v_mfma_f32_16x16x32_bf16 v[120:123], v[174:177], v[166:169], v[120:123]
	v_mfma_f32_16x16x32_bf16 v[116:119], v[182:185], v[158:161], v[116:119]
	v_mfma_f32_16x16x32_bf16 v[112:115], v[182:185], v[166:169], v[112:115]
	v_mfma_f32_16x16x32_bf16 v[108:111], v[190:193], v[158:161], v[108:111]
	v_mfma_f32_16x16x32_bf16 v[104:107], v[190:193], v[166:169], v[104:107]
	v_mfma_f32_16x16x32_bf16 v[100:103], v[198:201], v[158:161], v[100:103]
	v_mfma_f32_16x16x32_bf16 v[96:99], v[198:201], v[166:169], v[96:99]
	s_setprio 0
	s_barrier
; #define STAGE_A(POFF, h, kt) STAGE_AX(POFF, h, kt, brow)
; #define STAGE_B(POFF, h, kt) STAGE_BX(POFF, h, kt, bcol)
; #define LDA(dst, b, h) _Pragma("unroll") for (int m = 0; m < 4; ++m) _Pragma("unroll") for (int k = 0; k < 2; ++k) \
;     dst[m][k] = *reinterpret_cast<const bf16x8*>((char*)SA(b, h) + lds_byte(wr * 64 + m * 16 + fr, k * 32 + fq * 8))
; #define LDB(dst, b, h) _Pragma("unroll") for (int n = 0; n < 2; ++n) _Pragma("unroll") for (int k = 0; k < 2; ++k) \
;     dst[n][k] = *reinterpret_cast<const bf16x8*>((char*)SB(b, h) + lds_byte(wc * 32 + n * 16 + fr, k * 32 + fq * 8))
; #define MMA(ai, bj, At_, Bt_) do { __builtin_amdgcn_s_setprio(1); \
;     _Pragma("unroll") for (int k = 0; k < 2; ++k) _Pragma("unroll") for (int m = 0; m < 4; ++m) _Pragma("unroll") for (int n = 0; n < 2; ++n) \
;       acc[ai][bj][m][n] = __builtin_amdgcn_mfma_f32_16x16x32_bf16(At_[m][k], Bt_[n][k], acc[ai][bj][m][n], 0, 0, 0); \
;     __builtin_amdgcn_s_setprio(0); } while (0)
; #define WAIT_V(n) asm volatile("s_waitcnt vmcnt(" #n ")" ::: "memory")
; #define BAR __builtin_amdgcn_s_barrier()
; #define SCHED __builtin_amdgcn_sched_barrier(0)
; template <int EPI, int N, int K>
; __device__ __forceinline__ void gemm_phase(const bf16_t* __restrict__ A, const bf16_t* __restrict__ Bt, const EpiArgs ea) {
;     ...
;       LDB(B1, 0, 1); STAGE_B(SB_OFF(0, 0), 0, t + 2);
;       BAR; WAIT_L(0); MMA(0, 1, At, B1); BAR;
;       LDA(At, 0, 1); STAGE_A(SA_OFF(0, 0), 0, t + 2);
;       BAR; WAIT_L(0); MMA(1, 0, At, B0); BAR; SCHED;
;       STAGE_B(SB_OFF(0, 1), 1, t + 2);
;       WAIT_V(6); BAR; MMA(1, 1, At, B1); BAR;
	ds_read_b128 v[202:205], v150
	ds_read_b128 v[206:209], v150 offset:1024
	ds_read_b128 v[210:213], v150 offset:2048
	ds_read_b128 v[214:217], v150 offset:3072
	ds_read_b128 v[246:249], v149 offset:16384
	ds_read_b128 v[250:253], v149 offset:17408
	s_add_i32 s31, s3, s29
	s_add_i32 s34, s31, 0x100
	s_mov_b32 m0, s11
	s_nop 0
	buffer_load_dwordx4 v134, s[56:59], s34 offen lds
	s_add_i32 s34, s31, 0x80100
	s_mov_b32 m0, s12
	s_nop 0
	buffer_load_dwordx4 v134, s[56:59], s34 offen lds
	s_waitcnt vmcnt(6)
	s_barrier
	s_waitcnt lgkmcnt(2)
	s_setprio 1
	v_mfma_f32_16x16x32_bf16 v[92:95], v[170:173], v[202:205], v[92:95]
	v_mfma_f32_16x16x32_bf16 v[88:91], v[170:173], v[210:213], v[88:91]
	v_mfma_f32_16x16x32_bf16 v[84:87], v[178:181], v[202:205], v[84:87]
	v_mfma_f32_16x16x32_bf16 v[80:83], v[178:181], v[210:213], v[80:83]
	v_mfma_f32_16x16x32_bf16 v[76:79], v[186:189], v[202:205], v[76:79]
	v_mfma_f32_16x16x32_bf16 v[72:75], v[186:189], v[210:213], v[72:75]
	v_mfma_f32_16x16x32_bf16 v[68:71], v[194:197], v[202:205], v[68:71]
	v_mfma_f32_16x16x32_bf16 v[64:67], v[194:197], v[210:213], v[64:67]
	v_mfma_f32_16x16x32_bf16 v[92:95], v[174:177], v[206:209], v[92:95]
	v_mfma_f32_16x16x32_bf16 v[88:91], v[174:177], v[214:217], v[88:91]
	v_mfma_f32_16x16x32_bf16 v[84:87], v[182:185], v[206:209], v[84:87]
	v_mfma_f32_16x16x32_bf16 v[80:83], v[182:185], v[214:217], v[80:83]
	v_mfma_f32_16x16x32_bf16 v[76:79], v[190:193], v[206:209], v[76:79]
	v_mfma_f32_16x16x32_bf16 v[72:75], v[190:193], v[214:217], v[72:75]
	v_mfma_f32_16x16x32_bf16 v[68:71], v[198:201], v[206:209], v[68:71]
	v_mfma_f32_16x16x32_bf16 v[64:67], v[198:201], v[214:217], v[64:67]
	s_setprio 0
	s_barrier
	ds_read_b128 v[170:173], v146 offset:32768
	ds_read_b128 v[174:177], v146 offset:33792
	ds_read_b128 v[178:181], v147 offset:32768
	ds_read_b128 v[182:185], v147 offset:33792
	ds_read_b128 v[186:189], v148 offset:32768
	ds_read_b128 v[190:193], v148 offset:33792
	s_add_i32 s34, s30, 0x100
	s_mov_b32 m0, s10
	s_nop 0
	buffer_load_dwordx4 v131, s[48:51], s34 offen lds
	s_add_i32 s35, s30, 0x40100
	s_mov_b32 m0, s13
	s_nop 0
	buffer_load_dwordx4 v131, s[48:51], s35 offen lds
	s_waitcnt vmcnt(10)
	s_barrier
	s_waitcnt lgkmcnt(6)
	s_setprio 1
	v_mfma_f32_16x16x32_bf16 v[60:63], v[218:221], v[154:157], v[60:63]
	v_mfma_f32_16x16x32_bf16 v[56:59], v[218:221], v[162:165], v[56:59]
	v_mfma_f32_16x16x32_bf16 v[52:55], v[226:229], v[154:157], v[52:55]
	v_mfma_f32_16x16x32_bf16 v[48:51], v[226:229], v[162:165], v[48:51]
	v_mfma_f32_16x16x32_bf16 v[44:47], v[238:241], v[154:157], v[44:47]
	v_mfma_f32_16x16x32_bf16 v[40:43], v[238:241], v[162:165], v[40:43]
	v_mfma_f32_16x16x32_bf16 v[36:39], v[246:249], v[154:157], v[36:39]
	v_mfma_f32_16x16x32_bf16 v[32:35], v[246:249], v[162:165], v[32:35]
	v_mfma_f32_16x16x32_bf16 v[60:63], v[222:225], v[158:161], v[60:63]
	v_mfma_f32_16x16x32_bf16 v[56:59], v[222:225], v[166:169], v[56:59]
	v_mfma_f32_16x16x32_bf16 v[52:55], v[230:233], v[158:161], v[52:55]
	v_mfma_f32_16x16x32_bf16 v[48:51], v[230:233], v[166:169], v[48:51]
	v_mfma_f32_16x16x32_bf16 v[44:47], v[242:245], v[158:161], v[44:47]
	v_mfma_f32_16x16x32_bf16 v[40:43], v[242:245], v[166:169], v[40:43]
	v_mfma_f32_16x16x32_bf16 v[36:39], v[250:253], v[158:161], v[36:39]
	v_mfma_f32_16x16x32_bf16 v[32:35], v[250:253], v[166:169], v[32:35]
	s_setprio 0
	s_barrier
	ds_read_b128 v[154:157], v151
	ds_read_b128 v[158:161], v151 offset:1024
	ds_read_b128 v[162:165], v151 offset:2048
	ds_read_b128 v[166:169], v151 offset:3072
	ds_read_b128 v[194:197], v149 offset:32768
	ds_read_b128 v[198:201], v149 offset:33792
	s_add_i32 s35, s31, 0x2100
	s_mov_b32 m0, s14
	s_nop 0
	buffer_load_dwordx4 v134, s[56:59], s35 offen lds
	s_add_i32 s35, s31, 0x82100
	s_mov_b32 m0, s15
	s_nop 0
	buffer_load_dwordx4 v134, s[56:59], s35 offen lds
	s_waitcnt vmcnt(6)
	s_barrier
	s_setprio 1
	v_mfma_f32_16x16x32_bf16 v[28:31], v[218:221], v[202:205], v[28:31]
	v_mfma_f32_16x16x32_bf16 v[24:27], v[218:221], v[210:213], v[24:27]
	v_mfma_f32_16x16x32_bf16 v[20:23], v[226:229], v[202:205], v[20:23]
	v_mfma_f32_16x16x32_bf16 v[16:19], v[226:229], v[210:213], v[16:19]
	v_mfma_f32_16x16x32_bf16 v[12:15], v[238:241], v[202:205], v[12:15]
	v_mfma_f32_16x16x32_bf16 v[8:11], v[238:241], v[210:213], v[8:11]
	v_mfma_f32_16x16x32_bf16 v[4:7], v[246:249], v[202:205], v[4:7]
	v_mfma_f32_16x16x32_bf16 v[0:3], v[246:249], v[210:213], v[0:3]
	v_mfma_f32_16x16x32_bf16 v[28:31], v[222:225], v[206:209], v[28:31]
	v_mfma_f32_16x16x32_bf16 v[24:27], v[222:225], v[214:217], v[24:27]
	v_mfma_f32_16x16x32_bf16 v[20:23], v[230:233], v[206:209], v[20:23]
	v_mfma_f32_16x16x32_bf16 v[16:19], v[230:233], v[214:217], v[16:19]
	v_mfma_f32_16x16x32_bf16 v[12:15], v[242:245], v[206:209], v[12:15]
	v_mfma_f32_16x16x32_bf16 v[8:11], v[242:245], v[214:217], v[8:11]
	v_mfma_f32_16x16x32_bf16 v[4:7], v[250:253], v[206:209], v[4:7]
	v_mfma_f32_16x16x32_bf16 v[0:3], v[250:253], v[214:217], v[0:3]
	s_setprio 0
	s_barrier
	ds_read_b128 v[218:221], v146 offset:49152
	ds_read_b128 v[222:225], v146 offset:50176
	ds_read_b128 v[226:229], v147 offset:49152
	ds_read_b128 v[230:233], v147 offset:50176
	ds_read_b128 v[238:241], v148 offset:49152
	ds_read_b128 v[242:245], v148 offset:50176
	s_or_b32 s35, s34, 0x80000
	s_mov_b32 m0, s16
	s_nop 0
	buffer_load_dwordx4 v131, s[48:51], s35 offen lds
	s_or_b32 s34, s34, 0xc0000
	s_mov_b32 m0, s17
	s_nop 0
	buffer_load_dwordx4 v131, s[48:51], s34 offen lds
	s_barrier
; #define STAGE_A(POFF, h, kt) STAGE_AX(POFF, h, kt, brow)
; #define STAGE_B(POFF, h, kt) STAGE_BX(POFF, h, kt, bcol)
; #define LDA(dst, b, h) _Pragma("unroll") for (int m = 0; m < 4; ++m) _Pragma("unroll") for (int k = 0; k < 2; ++k) \
;     dst[m][k] = *reinterpret_cast<const bf16x8*>((char*)SA(b, h) + lds_byte(wr * 64 + m * 16 + fr, k * 32 + fq * 8))
; #define LDB(dst, b, h) _Pragma("unroll") for (int n = 0; n < 2; ++n) _Pragma("unroll") for (int k = 0; k < 2; ++k) \
;     dst[n][k] = *reinterpret_cast<const bf16x8*>((char*)SB(b, h) + lds_byte(wc * 32 + n * 16 + fr, k * 32 + fq * 8))
; #define MMA(ai, bj, At_, Bt_) do { __builtin_amdgcn_s_setprio(1); \
;     _Pragma("unroll") for (int k = 0; k < 2; ++k) _Pragma("unroll") for (int m = 0; m < 4; ++m) _Pragma("unroll") for (int n = 0; n < 2; ++n) \
;       acc[ai][bj][m][n] = __builtin_amdgcn_mfma_f32_16x16x32_bf16(At_[m][k], Bt_[n][k], acc[ai][bj][m][n], 0, 0, 0); \
;     __builtin_amdgcn_s_setprio(0); } while (0)
; #define WAIT_V(n) asm volatile("s_waitcnt vmcnt(" #n ")" ::: "memory")
; #define BAR __builtin_amdgcn_s_barrier()
; #define SCHED __builtin_amdgcn_sched_barrier(0)
; template <int EPI, int N, int K>
; __device__ __forceinline__ void gemm_phase(const bf16_t* __restrict__ A, const bf16_t* __restrict__ Bt, const EpiArgs ea) {
;     ...
;       LDB(B0, 1, 0); SCHED; LDA(At, 1, 0); STAGE_A(SA_OFF(0, 1), 1, t + 2);
;       WAIT_L(8); BAR; WAIT_L(0); MMA(0, 0, At, B0); BAR; SCHED;
;       LDB(B1, 1, 1); STAGE_B(SB_OFF(1, 0), 0, t + 3);
;       BAR; WAIT_L(0); MMA(0, 1, At, B1); BAR;
;       LDA(At, 1, 1); STAGE_A(SA_OFF(1, 0), 0, t + 3);
;       BAR; WAIT_L(0); MMA(1, 0, At, B0); BAR; SCHED;
;       STAGE_B(SB_OFF(1, 1), 1, t + 3);
;       WAIT_V(6); BAR; MMA(1, 1, At, B1); BAR;
	s_waitcnt lgkmcnt(6)
	s_setprio 1
	v_mfma_f32_16x16x32_bf16 v[124:127], v[170:173], v[154:157], v[124:127]
	v_mfma_f32_16x16x32_bf16 v[120:123], v[170:173], v[162:165], v[120:123]
	v_mfma_f32_16x16x32_bf16 v[116:119], v[178:181], v[154:157], v[116:119]
	v_mfma_f32_16x16x32_bf16 v[112:115], v[178:181], v[162:165], v[112:115]
	v_mfma_f32_16x16x32_bf16 v[108:111], v[186:189], v[154:157], v[108:111]
	v_mfma_f32_16x16x32_bf16 v[104:107], v[186:189], v[162:165], v[104:107]
	v_mfma_f32_16x16x32_bf16 v[100:103], v[194:197], v[154:157], v[100:103]
	v_mfma_f32_16x16x32_bf16 v[96:99], v[194:197], v[162:165], v[96:99]
	v_mfma_f32_16x16x32_bf16 v[124:127], v[174:177], v[158:161], v[124:127]
	v_mfma_f32_16x16x32_bf16 v[120:123], v[174:177], v[166:169], v[120:123]
	v_mfma_f32_16x16x32_bf16 v[116:119], v[182:185], v[158:161], v[116:119]
	v_mfma_f32_16x16x32_bf16 v[112:115], v[182:185], v[166:169], v[112:115]
	v_mfma_f32_16x16x32_bf16 v[108:111], v[190:193], v[158:161], v[108:111]
	v_mfma_f32_16x16x32_bf16 v[104:107], v[190:193], v[166:169], v[104:107]
	v_mfma_f32_16x16x32_bf16 v[100:103], v[198:201], v[158:161], v[100:103]
	v_mfma_f32_16x16x32_bf16 v[96:99], v[198:201], v[166:169], v[96:99]
	s_setprio 0
	s_barrier
	ds_read_b128 v[202:205], v152
	ds_read_b128 v[206:209], v152 offset:1024
	ds_read_b128 v[210:213], v152 offset:2048
	ds_read_b128 v[214:217], v152 offset:3072
	ds_read_b128 v[246:249], v149 offset:49152
	ds_read_b128 v[250:253], v149 offset:50176
	s_add_i32 s34, s31, 0x180
	s_mov_b32 m0, s18
	s_nop 0
	buffer_load_dwordx4 v134, s[56:59], s34 offen lds
	s_add_i32 s34, s31, 0x80180
	s_mov_b32 m0, s19
	s_nop 0
	buffer_load_dwordx4 v134, s[56:59], s34 offen lds
	s_waitcnt vmcnt(6)
	s_barrier
	s_waitcnt lgkmcnt(2)
	s_setprio 1
	v_mfma_f32_16x16x32_bf16 v[92:95], v[170:173], v[202:205], v[92:95]
	v_mfma_f32_16x16x32_bf16 v[88:91], v[170:173], v[210:213], v[88:91]
	v_mfma_f32_16x16x32_bf16 v[84:87], v[178:181], v[202:205], v[84:87]
	v_mfma_f32_16x16x32_bf16 v[80:83], v[178:181], v[210:213], v[80:83]
	v_mfma_f32_16x16x32_bf16 v[76:79], v[186:189], v[202:205], v[76:79]
	v_mfma_f32_16x16x32_bf16 v[72:75], v[186:189], v[210:213], v[72:75]
	v_mfma_f32_16x16x32_bf16 v[68:71], v[194:197], v[202:205], v[68:71]
	v_mfma_f32_16x16x32_bf16 v[64:67], v[194:197], v[210:213], v[64:67]
	v_mfma_f32_16x16x32_bf16 v[92:95], v[174:177], v[206:209], v[92:95]
	v_mfma_f32_16x16x32_bf16 v[88:91], v[174:177], v[214:217], v[88:91]
	v_mfma_f32_16x16x32_bf16 v[84:87], v[182:185], v[206:209], v[84:87]
	v_mfma_f32_16x16x32_bf16 v[80:83], v[182:185], v[214:217], v[80:83]
	v_mfma_f32_16x16x32_bf16 v[76:79], v[190:193], v[206:209], v[76:79]
	v_mfma_f32_16x16x32_bf16 v[72:75], v[190:193], v[214:217], v[72:75]
	v_mfma_f32_16x16x32_bf16 v[68:71], v[198:201], v[206:209], v[68:71]
	v_mfma_f32_16x16x32_bf16 v[64:67], v[198:201], v[214:217], v[64:67]
	s_setprio 0
	s_barrier
	ds_read_b128 v[170:173], v146
	ds_read_b128 v[174:177], v146 offset:1024
	ds_read_b128 v[178:181], v147
	ds_read_b128 v[182:185], v147 offset:1024
	ds_read_b128 v[186:189], v148
	ds_read_b128 v[190:193], v148 offset:1024
	s_add_i32 s34, s30, 0x180
	s_mov_b32 m0, s20
	s_nop 0
	buffer_load_dwordx4 v131, s[48:51], s34 offen lds
	s_add_i32 s30, s30, 0x40180
	s_mov_b32 m0, s21
	s_nop 0
	buffer_load_dwordx4 v131, s[48:51], s30 offen lds
	s_waitcnt vmcnt(10)
	s_barrier
	s_waitcnt lgkmcnt(6)
	s_setprio 1
	v_mfma_f32_16x16x32_bf16 v[60:63], v[218:221], v[154:157], v[60:63]
	v_mfma_f32_16x16x32_bf16 v[56:59], v[218:221], v[162:165], v[56:59]
	v_mfma_f32_16x16x32_bf16 v[52:55], v[226:229], v[154:157], v[52:55]
	v_mfma_f32_16x16x32_bf16 v[48:51], v[226:229], v[162:165], v[48:51]
	v_mfma_f32_16x16x32_bf16 v[44:47], v[238:241], v[154:157], v[44:47]
	v_mfma_f32_16x16x32_bf16 v[40:43], v[238:241], v[162:165], v[40:43]
	v_mfma_f32_16x16x32_bf16 v[36:39], v[246:249], v[154:157], v[36:39]
	v_mfma_f32_16x16x32_bf16 v[32:35], v[246:249], v[162:165], v[32:35]
	v_mfma_f32_16x16x32_bf16 v[60:63], v[222:225], v[158:161], v[60:63]
	v_mfma_f32_16x16x32_bf16 v[56:59], v[222:225], v[166:169], v[56:59]
	v_mfma_f32_16x16x32_bf16 v[52:55], v[230:233], v[158:161], v[52:55]
	v_mfma_f32_16x16x32_bf16 v[48:51], v[230:233], v[166:169], v[48:51]
	v_mfma_f32_16x16x32_bf16 v[44:47], v[242:245], v[158:161], v[44:47]
	v_mfma_f32_16x16x32_bf16 v[40:43], v[242:245], v[166:169], v[40:43]
	v_mfma_f32_16x16x32_bf16 v[36:39], v[250:253], v[158:161], v[36:39]
	v_mfma_f32_16x16x32_bf16 v[32:35], v[250:253], v[166:169], v[32:35]
	s_setprio 0
	s_barrier
	ds_read_b128 v[154:157], v145
	ds_read_b128 v[158:161], v145 offset:1024
	ds_read_b128 v[162:165], v145 offset:2048
	ds_read_b128 v[166:169], v145 offset:3072
	ds_read_b128 v[194:197], v149
	ds_read_b128 v[198:201], v149 offset:1024
	s_add_i32 s30, s31, 0x2180
	s_mov_b32 m0, s22
	s_nop 0
	buffer_load_dwordx4 v134, s[56:59], s30 offen lds
	s_add_i32 s31, s31, 0x82180
	s_mov_b32 m0, s23
	s_nop 0
	buffer_load_dwordx4 v134, s[56:59], s31 offen lds
	s_waitcnt vmcnt(6)
	s_barrier
	s_setprio 1
	v_mfma_f32_16x16x32_bf16 v[28:31], v[218:221], v[202:205], v[28:31]
	v_mfma_f32_16x16x32_bf16 v[24:27], v[218:221], v[210:213], v[24:27]
	v_mfma_f32_16x16x32_bf16 v[20:23], v[226:229], v[202:205], v[20:23]
	v_mfma_f32_16x16x32_bf16 v[16:19], v[226:229], v[210:213], v[16:19]
	v_mfma_f32_16x16x32_bf16 v[12:15], v[238:241], v[202:205], v[12:15]
	v_mfma_f32_16x16x32_bf16 v[8:11], v[238:241], v[210:213], v[8:11]
	v_mfma_f32_16x16x32_bf16 v[4:7], v[246:249], v[202:205], v[4:7]
	v_mfma_f32_16x16x32_bf16 v[0:3], v[246:249], v[210:213], v[0:3]
	v_mfma_f32_16x16x32_bf16 v[28:31], v[222:225], v[206:209], v[28:31]
	v_mfma_f32_16x16x32_bf16 v[24:27], v[222:225], v[214:217], v[24:27]
	v_mfma_f32_16x16x32_bf16 v[20:23], v[230:233], v[206:209], v[20:23]
	v_mfma_f32_16x16x32_bf16 v[16:19], v[230:233], v[214:217], v[16:19]
	v_mfma_f32_16x16x32_bf16 v[12:15], v[242:245], v[206:209], v[12:15]
	v_mfma_f32_16x16x32_bf16 v[8:11], v[242:245], v[214:217], v[8:11]
	v_mfma_f32_16x16x32_bf16 v[4:7], v[250:253], v[206:209], v[4:7]
	v_mfma_f32_16x16x32_bf16 v[0:3], v[250:253], v[214:217], v[0:3]
	s_setprio 0
	s_add_i32 s28, s28, 2
	s_addk_i32 s29, 0x100
	s_cmp_lt_u32 s28, 28
	s_barrier
; #define STAGE_A(POFF, h, kt) STAGE_AX(POFF, h, kt, brow)
; #define LDA(dst, b, h) _Pragma("unroll") for (int m = 0; m < 4; ++m) _Pragma("unroll") for (int k = 0; k < 2; ++k) \
;     dst[m][k] = *reinterpret_cast<const bf16x8*>((char*)SA(b, h) + lds_byte(wr * 64 + m * 16 + fr, k * 32 + fq * 8))
; #define LDB(dst, b, h) _Pragma("unroll") for (int n = 0; n < 2; ++n) _Pragma("unroll") for (int k = 0; k < 2; ++k) \
;     dst[n][k] = *reinterpret_cast<const bf16x8*>((char*)SB(b, h) + lds_byte(wc * 32 + n * 16 + fr, k * 32 + fq * 8))
; #define MMA(ai, bj, At_, Bt_) do { __builtin_amdgcn_s_setprio(1); \
;     _Pragma("unroll") for (int k = 0; k < 2; ++k) _Pragma("unroll") for (int m = 0; m < 4; ++m) _Pragma("unroll") for (int n = 0; n < 2; ++n) \
;       acc[ai][bj][m][n] = __builtin_amdgcn_mfma_f32_16x16x32_bf16(At_[m][k], Bt_[n][k], acc[ai][bj][m][n], 0, 0, 0); \
;     __builtin_amdgcn_s_setprio(0); } while (0)
; #define WAIT_V(n) asm volatile("s_waitcnt vmcnt(" #n ")" ::: "memory")
; #define BAR __builtin_amdgcn_s_barrier()
; template <int EPI, int N, int K>
; __device__ __forceinline__ void gemm_phase(const bf16_t* __restrict__ A, const bf16_t* __restrict__ Bt, const EpiArgs ea) {
;     ...
;     { LDB(B0, 0, 0); LDA(At, 0, 0); STAGE_A(SA_OFF(1, 1), 1, nt - 1);
;       BAR; WAIT_L(0); MMA(0, 0, At, B0); BAR;
;       LDB(B1, 0, 1); BAR; WAIT_L(0); MMA(0, 1, At, B1); BAR;
;       LDA(At, 0, 1); WAIT_V(4); BAR; WAIT_L(0); MMA(1, 0, At, B0); MMA(1, 1, At, B1); BAR; }
	s_cbranch_scc1 .LBB0_270
	s_and_b32 s1, s1, 0x700
	s_lshl_b32 s0, s0, 11
	s_or_b32 s27, s1, s0
	s_lshl_b32 s0, s27, 12
	s_or_b32 s1, s0, 0x80f80
	s_mov_b32 m0, s24
	s_nop 0
	buffer_load_dwordx4 v131, s[48:51], s1 offen lds
	s_or_b32 s0, s0, 0xc0f80
	s_mov_b32 m0, s25
	s_nop 0
	buffer_load_dwordx4 v131, s[48:51], s0 offen lds
	s_barrier
	s_waitcnt lgkmcnt(0)
	s_setprio 1
	v_mfma_f32_16x16x32_bf16 v[124:127], v[170:173], v[154:157], v[124:127]
	v_mfma_f32_16x16x32_bf16 v[120:123], v[170:173], v[162:165], v[120:123]
	v_mfma_f32_16x16x32_bf16 v[116:119], v[178:181], v[154:157], v[116:119]
	v_mfma_f32_16x16x32_bf16 v[112:115], v[178:181], v[162:165], v[112:115]
	v_mfma_f32_16x16x32_bf16 v[108:111], v[186:189], v[154:157], v[108:111]
	v_mfma_f32_16x16x32_bf16 v[104:107], v[186:189], v[162:165], v[104:107]
	v_mfma_f32_16x16x32_bf16 v[100:103], v[194:197], v[154:157], v[100:103]
	v_mfma_f32_16x16x32_bf16 v[96:99], v[194:197], v[162:165], v[96:99]
	v_mfma_f32_16x16x32_bf16 v[124:127], v[174:177], v[158:161], v[124:127]
	v_mfma_f32_16x16x32_bf16 v[120:123], v[174:177], v[166:169], v[120:123]
	v_mfma_f32_16x16x32_bf16 v[116:119], v[182:185], v[158:161], v[116:119]
	v_mfma_f32_16x16x32_bf16 v[112:115], v[182:185], v[166:169], v[112:115]
	v_mfma_f32_16x16x32_bf16 v[108:111], v[190:193], v[158:161], v[108:111]
	v_mfma_f32_16x16x32_bf16 v[104:107], v[190:193], v[166:169], v[104:107]
	v_mfma_f32_16x16x32_bf16 v[100:103], v[198:201], v[158:161], v[100:103]
	v_mfma_f32_16x16x32_bf16 v[96:99], v[198:201], v[166:169], v[96:99]
	s_setprio 0
	s_barrier
	ds_read_b128 v[202:205], v150
	ds_read_b128 v[206:209], v150 offset:1024
	ds_read_b128 v[210:213], v150 offset:2048
	ds_read_b128 v[214:217], v150 offset:3072
	s_barrier
	s_waitcnt lgkmcnt(0)
	s_setprio 1
	v_mfma_f32_16x16x32_bf16 v[92:95], v[170:173], v[202:205], v[92:95]
	v_mfma_f32_16x16x32_bf16 v[88:91], v[170:173], v[210:213], v[88:91]
	v_mfma_f32_16x16x32_bf16 v[76:79], v[186:189], v[202:205], v[76:79]
	v_mfma_f32_16x16x32_bf16 v[72:75], v[186:189], v[210:213], v[72:75]
	v_mfma_f32_16x16x32_bf16 v[68:71], v[194:197], v[202:205], v[68:71]
	v_mfma_f32_16x16x32_bf16 v[64:67], v[194:197], v[210:213], v[64:67]
	v_mfma_f32_16x16x32_bf16 v[84:87], v[178:181], v[202:205], v[84:87]
	v_mfma_f32_16x16x32_bf16 v[80:83], v[178:181], v[210:213], v[80:83]
	v_mfma_f32_16x16x32_bf16 v[92:95], v[174:177], v[206:209], v[92:95]
	v_mfma_f32_16x16x32_bf16 v[88:91], v[174:177], v[214:217], v[88:91]
	v_mfma_f32_16x16x32_bf16 v[76:79], v[190:193], v[206:209], v[76:79]
	v_mfma_f32_16x16x32_bf16 v[72:75], v[190:193], v[214:217], v[72:75]
	v_mfma_f32_16x16x32_bf16 v[68:71], v[198:201], v[206:209], v[68:71]
	v_mfma_f32_16x16x32_bf16 v[64:67], v[198:201], v[214:217], v[64:67]
	v_mfma_f32_16x16x32_bf16 v[170:173], v[182:185], v[206:209], v[84:87]
	v_mfma_f32_16x16x32_bf16 v[174:177], v[182:185], v[214:217], v[80:83]
	s_setprio 0
	s_barrier
	s_nop 0
	ds_read_b128 v[80:83], v146 offset:16384
	ds_read_b128 v[84:87], v146 offset:17408
	ds_read_b128 v[178:181], v147 offset:16384
	ds_read_b128 v[182:185], v147 offset:17408
	ds_read_b128 v[186:189], v148 offset:16384
	ds_read_b128 v[190:193], v148 offset:17408
	ds_read_b128 v[194:197], v149 offset:16384
	ds_read_b128 v[198:201], v149 offset:17408
	s_waitcnt vmcnt(4)
	s_barrier
	s_waitcnt lgkmcnt(0)
	s_setprio 1
	v_mfma_f32_16x16x32_bf16 v[52:55], v[178:181], v[154:157], v[52:55]
	v_mfma_f32_16x16x32_bf16 v[48:51], v[178:181], v[162:165], v[48:51]
	v_mfma_f32_16x16x32_bf16 v[44:47], v[186:189], v[154:157], v[44:47]
	v_mfma_f32_16x16x32_bf16 v[40:43], v[186:189], v[162:165], v[40:43]
	v_mfma_f32_16x16x32_bf16 v[36:39], v[194:197], v[154:157], v[36:39]
	v_mfma_f32_16x16x32_bf16 v[32:35], v[194:197], v[162:165], v[32:35]
	v_mfma_f32_16x16x32_bf16 v[60:63], v[80:83], v[154:157], v[60:63]
	v_mfma_f32_16x16x32_bf16 v[56:59], v[80:83], v[162:165], v[56:59]
	v_mfma_f32_16x16x32_bf16 v[52:55], v[182:185], v[158:161], v[52:55]
	v_mfma_f32_16x16x32_bf16 v[48:51], v[182:185], v[166:169], v[48:51]
	v_mfma_f32_16x16x32_bf16 v[44:47], v[190:193], v[158:161], v[44:47]
	v_mfma_f32_16x16x32_bf16 v[40:43], v[190:193], v[166:169], v[40:43]
	v_mfma_f32_16x16x32_bf16 v[36:39], v[198:201], v[158:161], v[36:39]
	v_mfma_f32_16x16x32_bf16 v[32:35], v[198:201], v[166:169], v[32:35]
	v_mfma_f32_16x16x32_bf16 v[154:157], v[84:87], v[158:161], v[60:63]
	v_mfma_f32_16x16x32_bf16 v[162:165], v[84:87], v[166:169], v[56:59]
	s_setprio 0
	s_setprio 1
	v_mfma_f32_16x16x32_bf16 v[28:31], v[80:83], v[202:205], v[28:31]
	v_mfma_f32_16x16x32_bf16 v[24:27], v[80:83], v[210:213], v[24:27]
	v_mfma_f32_16x16x32_bf16 v[12:15], v[186:189], v[202:205], v[12:15]
	v_mfma_f32_16x16x32_bf16 v[8:11], v[186:189], v[210:213], v[8:11]
	v_mfma_f32_16x16x32_bf16 v[20:23], v[178:181], v[202:205], v[20:23]
	v_mfma_f32_16x16x32_bf16 v[16:19], v[178:181], v[210:213], v[16:19]
	v_mfma_f32_16x16x32_bf16 v[4:7], v[194:197], v[202:205], v[4:7]
	v_mfma_f32_16x16x32_bf16 v[0:3], v[194:197], v[210:213], v[0:3]
	v_mfma_f32_16x16x32_bf16 v[28:31], v[84:87], v[206:209], v[28:31]
	v_mfma_f32_16x16x32_bf16 v[24:27], v[84:87], v[214:217], v[24:27]
	v_mfma_f32_16x16x32_bf16 v[12:15], v[190:193], v[206:209], v[12:15]
	v_mfma_f32_16x16x32_bf16 v[8:11], v[190:193], v[214:217], v[8:11]
	v_mfma_f32_16x16x32_bf16 v[158:161], v[182:185], v[206:209], v[20:23]
	v_mfma_f32_16x16x32_bf16 v[166:169], v[182:185], v[214:217], v[16:19]
	v_mfma_f32_16x16x32_bf16 v[178:181], v[198:201], v[206:209], v[4:7]
	v_mfma_f32_16x16x32_bf16 v[182:185], v[198:201], v[214:217], v[0:3]
	s_setprio 0
	s_barrier
; #define LDA(dst, b, h) _Pragma("unroll") for (int m = 0; m < 4; ++m) _Pragma("unroll") for (int k = 0; k < 2; ++k) \
;     dst[m][k] = *reinterpret_cast<const bf16x8*>((char*)SA(b, h) + lds_byte(wr * 64 + m * 16 + fr, k * 32 + fq * 8))
; #define LDB(dst, b, h) _Pragma("unroll") for (int n = 0; n < 2; ++n) _Pragma("unroll") for (int k = 0; k < 2; ++k) \
;     dst[n][k] = *reinterpret_cast<const bf16x8*>((char*)SB(b, h) + lds_byte(wc * 32 + n * 16 + fr, k * 32 + fq * 8))
; #define MMA(ai, bj, At_, Bt_) do { __builtin_amdgcn_s_setprio(1); \
;     _Pragma("unroll") for (int k = 0; k < 2; ++k) _Pragma("unroll") for (int m = 0; m < 4; ++m) _Pragma("unroll") for (int n = 0; n < 2; ++n) \
;       acc[ai][bj][m][n] = __builtin_amdgcn_mfma_f32_16x16x32_bf16(At_[m][k], Bt_[n][k], acc[ai][bj][m][n], 0, 0, 0); \
;     __builtin_amdgcn_s_setprio(0); } while (0)
; #define WAIT_V(n) asm volatile("s_waitcnt vmcnt(" #n ")" ::: "memory")
; #define BAR __builtin_amdgcn_s_barrier()
; template <int EPI, int N, int K>
; __device__ __forceinline__ void gemm_phase(const bf16_t* __restrict__ A, const bf16_t* __restrict__ Bt, const EpiArgs ea) {
;     ...
;     { LDB(B0, 1, 0); LDA(At, 1, 0); WAIT_V(2); BAR; WAIT_L(0); MMA(0, 0, At, B0); BAR;
;       LDB(B1, 1, 1); WAIT_V(0); BAR; WAIT_L(0); MMA(0, 1, At, B1); BAR;
;       LDA(At, 1, 1); BAR; WAIT_L(0); MMA(1, 0, At, B0); MMA(1, 1, At, B1); BAR; }
;     if (wr == 0) BAR;
	s_nop 0
	ds_read_b128 v[0:3], v151
	ds_read_b128 v[4:7], v151 offset:1024
	ds_read_b128 v[16:19], v151 offset:2048
	ds_read_b128 v[186:189], v151 offset:3072
	ds_read_b128 v[20:23], v146 offset:32768
	ds_read_b128 v[190:193], v146 offset:33792
	ds_read_b128 v[194:197], v147 offset:32768
	ds_read_b128 v[198:201], v147 offset:33792
	ds_read_b128 v[202:205], v148 offset:32768
	ds_read_b128 v[206:209], v148 offset:33792
	ds_read_b128 v[210:213], v149 offset:32768
	ds_read_b128 v[214:217], v149 offset:33792
	s_waitcnt vmcnt(2)
	s_barrier
	s_waitcnt lgkmcnt(0)
	s_setprio 1
	v_mfma_f32_16x16x32_bf16 v[56:59], v[20:23], v[0:3], v[124:127]
	v_mfma_f32_16x16x32_bf16 v[60:63], v[20:23], v[16:19], v[120:123]
	v_mfma_f32_16x16x32_bf16 v[80:83], v[194:197], v[0:3], v[116:119]
	v_mfma_f32_16x16x32_bf16 v[84:87], v[194:197], v[16:19], v[112:115]
	v_mfma_f32_16x16x32_bf16 v[108:111], v[202:205], v[0:3], v[108:111]
	v_mfma_f32_16x16x32_bf16 v[104:107], v[202:205], v[16:19], v[104:107]
	v_mfma_f32_16x16x32_bf16 v[120:123], v[210:213], v[0:3], v[100:103]
	v_mfma_f32_16x16x32_bf16 v[124:127], v[210:213], v[16:19], v[96:99]
	v_mfma_f32_16x16x32_bf16 v[116:119], v[190:193], v[4:7], v[56:59]
	v_mfma_f32_16x16x32_bf16 v[112:115], v[190:193], v[186:189], v[60:63]
	v_mfma_f32_16x16x32_bf16 v[100:103], v[198:201], v[4:7], v[80:83]
	v_mfma_f32_16x16x32_bf16 v[96:99], v[198:201], v[186:189], v[84:87]
	v_mfma_f32_16x16x32_bf16 v[84:87], v[206:209], v[4:7], v[108:111]
	v_mfma_f32_16x16x32_bf16 v[80:83], v[206:209], v[186:189], v[104:107]
	v_mfma_f32_16x16x32_bf16 v[60:63], v[214:217], v[4:7], v[120:123]
	v_mfma_f32_16x16x32_bf16 v[56:59], v[214:217], v[186:189], v[124:127]
	s_setprio 0
	s_barrier
	ds_read_b128 v[218:221], v152
	ds_read_b128 v[222:225], v152 offset:1024
	ds_read_b128 v[226:229], v152 offset:2048
	ds_read_b128 v[230:233], v152 offset:3072
	s_waitcnt vmcnt(0)
	s_barrier
	s_waitcnt lgkmcnt(0)
	s_setprio 1
	v_mfma_f32_16x16x32_bf16 v[92:95], v[20:23], v[218:221], v[92:95]
	v_mfma_f32_16x16x32_bf16 v[20:23], v[20:23], v[226:229], v[88:91]
	v_mfma_f32_16x16x32_bf16 v[88:91], v[194:197], v[218:221], v[170:173]
	v_mfma_f32_16x16x32_bf16 v[104:107], v[194:197], v[226:229], v[174:177]
	v_mfma_f32_16x16x32_bf16 v[76:79], v[202:205], v[218:221], v[76:79]
	v_mfma_f32_16x16x32_bf16 v[72:75], v[202:205], v[226:229], v[72:75]
	v_mfma_f32_16x16x32_bf16 v[68:71], v[210:213], v[218:221], v[68:71]
	v_mfma_f32_16x16x32_bf16 v[64:67], v[210:213], v[226:229], v[64:67]
	v_mfma_f32_16x16x32_bf16 v[124:127], v[190:193], v[222:225], v[92:95]
	v_mfma_f32_16x16x32_bf16 v[120:123], v[190:193], v[230:233], v[20:23]
	v_mfma_f32_16x16x32_bf16 v[108:111], v[198:201], v[222:225], v[88:91]
	v_mfma_f32_16x16x32_bf16 v[104:107], v[198:201], v[230:233], v[104:107]
	v_mfma_f32_16x16x32_bf16 v[92:95], v[206:209], v[222:225], v[76:79]
	v_mfma_f32_16x16x32_bf16 v[88:91], v[206:209], v[230:233], v[72:75]
	v_mfma_f32_16x16x32_bf16 v[76:79], v[214:217], v[222:225], v[68:71]
	v_mfma_f32_16x16x32_bf16 v[72:75], v[214:217], v[230:233], v[64:67]
	s_setprio 0
	s_barrier
	s_nop 0
	ds_read_b128 v[64:67], v146 offset:49152
	ds_read_b128 v[170:173], v146 offset:50176
	ds_read_b128 v[68:71], v147 offset:49152
	ds_read_b128 v[174:177], v147 offset:50176
	ds_read_b128 v[190:193], v148 offset:49152
	ds_read_b128 v[194:197], v148 offset:50176
	ds_read_b128 v[198:201], v149 offset:49152
	ds_read_b128 v[202:205], v149 offset:50176
	s_barrier
	s_waitcnt lgkmcnt(0)
	s_setprio 1
	v_mfma_f32_16x16x32_bf16 v[20:23], v[64:67], v[0:3], v[154:157]
	v_mfma_f32_16x16x32_bf16 v[154:157], v[64:67], v[16:19], v[162:165]
	v_mfma_f32_16x16x32_bf16 v[162:165], v[68:71], v[0:3], v[52:55]
	v_mfma_f32_16x16x32_bf16 v[206:209], v[68:71], v[16:19], v[48:51]
	v_mfma_f32_16x16x32_bf16 v[44:47], v[190:193], v[0:3], v[44:47]
	v_mfma_f32_16x16x32_bf16 v[40:43], v[190:193], v[16:19], v[40:43]
	v_mfma_f32_16x16x32_bf16 v[0:3], v[198:201], v[0:3], v[36:39]
	v_mfma_f32_16x16x32_bf16 v[210:213], v[198:201], v[16:19], v[32:35]
	v_mfma_f32_16x16x32_bf16 v[52:55], v[170:173], v[4:7], v[20:23]
	v_mfma_f32_16x16x32_bf16 v[48:51], v[170:173], v[186:189], v[154:157]
	v_mfma_f32_16x16x32_bf16 v[36:39], v[174:177], v[4:7], v[162:165]
	v_mfma_f32_16x16x32_bf16 v[32:35], v[174:177], v[186:189], v[206:209]
	v_mfma_f32_16x16x32_bf16 v[20:23], v[194:197], v[4:7], v[44:47]
	v_mfma_f32_16x16x32_bf16 v[16:19], v[194:197], v[186:189], v[40:43]
	v_mfma_f32_16x16x32_bf16 v[4:7], v[202:205], v[4:7], v[0:3]
	v_mfma_f32_16x16x32_bf16 v[0:3], v[202:205], v[186:189], v[210:213]
	s_setprio 0
	s_setprio 1
	v_mfma_f32_16x16x32_bf16 v[28:31], v[64:67], v[218:221], v[28:31]
	v_mfma_f32_16x16x32_bf16 v[24:27], v[64:67], v[226:229], v[24:27]
	v_mfma_f32_16x16x32_bf16 v[40:43], v[68:71], v[218:221], v[158:161]
	v_mfma_f32_16x16x32_bf16 v[154:157], v[68:71], v[226:229], v[166:169]
	v_mfma_f32_16x16x32_bf16 v[12:15], v[190:193], v[218:221], v[12:15]
	v_mfma_f32_16x16x32_bf16 v[8:11], v[190:193], v[226:229], v[8:11]
	v_mfma_f32_16x16x32_bf16 v[158:161], v[198:201], v[218:221], v[178:181]
	v_mfma_f32_16x16x32_bf16 v[162:165], v[198:201], v[226:229], v[182:185]
	v_mfma_f32_16x16x32_bf16 v[68:71], v[170:173], v[222:225], v[28:31]
	v_mfma_f32_16x16x32_bf16 v[64:67], v[170:173], v[230:233], v[24:27]
	v_mfma_f32_16x16x32_bf16 v[44:47], v[174:177], v[222:225], v[40:43]
	v_mfma_f32_16x16x32_bf16 v[40:43], v[174:177], v[230:233], v[154:157]
	v_mfma_f32_16x16x32_bf16 v[28:31], v[194:197], v[222:225], v[12:15]
	v_mfma_f32_16x16x32_bf16 v[24:27], v[194:197], v[230:233], v[8:11]
	v_mfma_f32_16x16x32_bf16 v[12:15], v[202:205], v[222:225], v[158:161]
	v_mfma_f32_16x16x32_bf16 v[8:11], v[202:205], v[230:233], v[162:165]
	s_setprio 0
	s_barrier
	s_and_saveexec_b64 s[0:1], s[6:7]
	s_cbranch_execz .LBB0_273
	s_barrier

; #define STAGE_A(POFF, h, kt) STAGE_AX(POFF, h, kt, brow)
; #define LDA(dst, b, h) _Pragma("unroll") for (int m = 0; m < 4; ++m) _Pragma("unroll") for (int k = 0; k < 2; ++k) \
;     dst[m][k] = *reinterpret_cast<const bf16x8*>((char*)SA(b, h) + lds_byte(wr * 64 + m * 16 + fr, k * 32 + fq * 8))
; #define LDB(dst, b, h) _Pragma("unroll") for (int n = 0; n < 2; ++n) _Pragma("unroll") for (int k = 0; k < 2; ++k) \
;     dst[n][k] = *reinterpret_cast<const bf16x8*>((char*)SB(b, h) + lds_byte(wc * 32 + n * 16 + fr, k * 32 + fq * 8))
; #define MMA(ai, bj, At_, Bt_) do { __builtin_amdgcn_s_setprio(1); \
;     _Pragma("unroll") for (int k = 0; k < 2; ++k) _Pragma("unroll") for (int m = 0; m < 4; ++m) _Pragma("unroll") for (int n = 0; n < 2; ++n) \
;       acc[ai][bj][m][n] = __builtin_amdgcn_mfma_f32_16x16x32_bf16(At_[m][k], Bt_[n][k], acc[ai][bj][m][n], 0, 0, 0); \
;     __builtin_amdgcn_s_setprio(0); } while (0)
; #define WAIT_V(n) asm volatile("s_waitcnt vmcnt(" #n ")" ::: "memory")
; #define BAR __builtin_amdgcn_s_barrier()
; #define SCHED __builtin_amdgcn_sched_barrier(0)
; #define TILE_RC(w_, brow_, bcol_) do { const int wg_ = ((w_) & 7) * qx + ((w_) >> 3); const int gid_ = wg_ / nig; \
;     brow_ = (gid_ * 8 + ((wg_ % nig) & 7)) * 256; bcol_ = ((wg_ % nig) >> 3) * 256; } while (0)
; template <int EPI, int N, int K>
; __device__ __forceinline__ void gemm_phase(const bf16_t* __restrict__ A, const bf16_t* __restrict__ Bt, const EpiArgs ea) {
;     ...
;   for (int w = blockIdx.x; w < nwg; w += gridDim.x) {
;     int brow, bcol; TILE_RC(w, brow, bcol);
;     f32x4 acc[2][2][4][2];
; #pragma unroll
;     for (int a = 0; a < 2; ++a)
; #pragma unroll
;       for (int b = 0; b < 2; ++b)
; #pragma unroll
;         for (int m = 0; m < 4; ++m)
; #pragma unroll
;           for (int n = 0; n < 2; ++n) acc[a][b][m][n] = (f32x4){0.f, 0.f, 0.f, 0.f};
;     bf16x8 At[4][2], B0[2][2], B1[2][2];
;     if (wr == 1) BAR;
;     if (w == (int)blockIdx.x) { WAIT_V(0); } else { WAIT_V(24); }
;     BAR;
;     BAR;
;     for (int t = 0; t < nt - 2; t += 2) {
;       LDB(B0, 0, 0); SCHED; LDA(At, 0, 0); STAGE_A(SA_OFF(1, 1), 1, t + 1);
;       WAIT_L(8); BAR; WAIT_L(0); MMA(0, 0, At, B0); BAR; SCHED;
.LBB0_389:
	s_lshl_b32 s2, s30, 6
	s_and_b32 s2, s2, 0x1c0
	s_ashr_i32 s3, s30, 3
	s_add_i32 s3, s2, s3
	s_ashr_i32 s2, s3, 31
	s_lshr_b32 s2, s2, 26
	s_add_i32 s12, s3, s2
	s_ashr_i32 s2, s12, 6
	s_andn2_b32 s12, s12, 63
	s_sub_i32 s31, s3, s12
	s_lshl_b32 s3, s31, 8
	s_lshl_b32 s12, s31, 5
	s_lshl_b32 s13, s31, 17
	s_and_b32 s31, s31, 7
	s_lshl_b32 s34, s2, 23
	s_lshl_b32 s31, s31, 20
	v_mov_b32_e32 v0, 0
	s_and_b32 s13, s13, 0xfff00000
	s_or_b32 s31, s34, s31
	s_mov_b32 s34, -2
	s_mov_b32 s35, 0
	v_mov_b32_e32 v1, v0
	v_mov_b32_e32 v2, v0
	v_mov_b32_e32 v3, v0
	v_mov_b32_e32 v4, v0
	v_mov_b32_e32 v5, v0
	v_mov_b32_e32 v6, v0
	v_mov_b32_e32 v7, v0
	v_mov_b32_e32 v8, v0
	v_mov_b32_e32 v9, v0
	v_mov_b32_e32 v10, v0
	v_mov_b32_e32 v11, v0
	v_mov_b32_e32 v12, v0
	v_mov_b32_e32 v13, v0
	v_mov_b32_e32 v14, v0
	v_mov_b32_e32 v15, v0
	v_mov_b32_e32 v16, v0
	v_mov_b32_e32 v17, v0
	v_mov_b32_e32 v18, v0
	v_mov_b32_e32 v19, v0
	v_mov_b32_e32 v20, v0
	v_mov_b32_e32 v21, v0
	v_mov_b32_e32 v22, v0
	v_mov_b32_e32 v23, v0
	v_mov_b32_e32 v24, v0
	v_mov_b32_e32 v25, v0
	v_mov_b32_e32 v26, v0
	v_mov_b32_e32 v27, v0
	v_mov_b32_e32 v28, v0
	v_mov_b32_e32 v29, v0
	v_mov_b32_e32 v30, v0
	v_mov_b32_e32 v31, v0
	v_mov_b32_e32 v32, v0
	v_mov_b32_e32 v33, v0
	v_mov_b32_e32 v34, v0
	v_mov_b32_e32 v35, v0
	v_mov_b32_e32 v36, v0
	v_mov_b32_e32 v37, v0
	v_mov_b32_e32 v38, v0
	v_mov_b32_e32 v39, v0
	v_mov_b32_e32 v40, v0
	v_mov_b32_e32 v41, v0
	v_mov_b32_e32 v42, v0
	v_mov_b32_e32 v43, v0
	v_mov_b32_e32 v44, v0
	v_mov_b32_e32 v45, v0
	v_mov_b32_e32 v46, v0
	v_mov_b32_e32 v47, v0
	v_mov_b32_e32 v48, v0
	v_mov_b32_e32 v49, v0
	v_mov_b32_e32 v50, v0
	v_mov_b32_e32 v51, v0
	v_mov_b32_e32 v52, v0
	v_mov_b32_e32 v53, v0
	v_mov_b32_e32 v54, v0
	v_mov_b32_e32 v55, v0
	v_mov_b32_e32 v56, v0
	v_mov_b32_e32 v57, v0
	v_mov_b32_e32 v58, v0
	v_mov_b32_e32 v59, v0
	v_mov_b32_e32 v60, v0
	v_mov_b32_e32 v61, v0
	v_mov_b32_e32 v62, v0
	v_mov_b32_e32 v63, v0
	v_mov_b32_e32 v64, v0
	v_mov_b32_e32 v65, v0
	v_mov_b32_e32 v66, v0
	v_mov_b32_e32 v67, v0
	v_mov_b32_e32 v68, v0
	v_mov_b32_e32 v69, v0
	v_mov_b32_e32 v70, v0
	v_mov_b32_e32 v71, v0
	v_mov_b32_e32 v72, v0
	v_mov_b32_e32 v73, v0
	v_mov_b32_e32 v74, v0
	v_mov_b32_e32 v75, v0
	v_mov_b32_e32 v76, v0
	v_mov_b32_e32 v77, v0
	v_mov_b32_e32 v78, v0
	v_mov_b32_e32 v79, v0
	v_mov_b32_e32 v80, v0
	v_mov_b32_e32 v81, v0
	v_mov_b32_e32 v82, v0
	v_mov_b32_e32 v83, v0
	v_mov_b32_e32 v84, v0
	v_mov_b32_e32 v85, v0
	v_mov_b32_e32 v86, v0
	v_mov_b32_e32 v87, v0
	v_mov_b32_e32 v88, v0
	v_mov_b32_e32 v89, v0
	v_mov_b32_e32 v90, v0
	v_mov_b32_e32 v91, v0
	v_mov_b32_e32 v92, v0
	v_mov_b32_e32 v93, v0
	v_mov_b32_e32 v94, v0
	v_mov_b32_e32 v95, v0
	v_mov_b32_e32 v96, v0
	v_mov_b32_e32 v97, v0
	v_mov_b32_e32 v98, v0
	v_mov_b32_e32 v99, v0
	v_mov_b32_e32 v100, v0
	v_mov_b32_e32 v101, v0
	v_mov_b32_e32 v102, v0
	v_mov_b32_e32 v103, v0
	v_mov_b32_e32 v104, v0
	v_mov_b32_e32 v105, v0
	v_mov_b32_e32 v106, v0
	v_mov_b32_e32 v107, v0
	v_mov_b32_e32 v108, v0
	v_mov_b32_e32 v109, v0
	v_mov_b32_e32 v110, v0
	v_mov_b32_e32 v111, v0
	v_mov_b32_e32 v112, v0
	v_mov_b32_e32 v113, v0
	v_mov_b32_e32 v114, v0
	v_mov_b32_e32 v115, v0
	v_mov_b32_e32 v116, v0
	v_mov_b32_e32 v117, v0
	v_mov_b32_e32 v118, v0
	v_mov_b32_e32 v119, v0
	v_mov_b32_e32 v120, v0
	v_mov_b32_e32 v121, v0
	v_mov_b32_e32 v122, v0
	v_mov_b32_e32 v123, v0
	v_mov_b32_e32 v124, v0
	v_mov_b32_e32 v125, v0
	v_mov_b32_e32 v126, v0
	v_mov_b32_e32 v127, v0
	s_barrier
	s_barrier
	ds_read_b128 v[132:135], v147
	ds_read_b128 v[156:159], v147 offset:1024
	ds_read_b128 v[160:163], v147 offset:2048
	ds_read_b128 v[164:167], v147 offset:3072
	ds_read_b128 v[168:171], v148
	ds_read_b128 v[172:175], v148 offset:1024
	ds_read_b128 v[176:179], v149
	ds_read_b128 v[180:183], v149 offset:1024
	ds_read_b128 v[184:187], v150
	ds_read_b128 v[188:191], v150 offset:1024
	ds_read_b128 v[192:195], v151
	ds_read_b128 v[196:199], v151 offset:1024
.LBB0_390:
	ds_read_b128 v[218:221], v148 offset:16384
	ds_read_b128 v[222:225], v148 offset:17408
	ds_read_b128 v[226:229], v149 offset:16384
	ds_read_b128 v[230:233], v149 offset:17408
	ds_read_b128 v[238:241], v150 offset:16384
	ds_read_b128 v[242:245], v150 offset:17408
	s_add_i32 s36, s31, s35
	s_or_b32 s37, s36, 0x80080
	s_mov_b32 s62, s50
	s_mov_b32 s63, s51
	s_mov_b32 m0, s28
	s_nop 0
	buffer_load_dwordx4 v131, s[60:63], s37 offen lds
	s_or_b32 s37, s36, 0xc0080
	s_mov_b32 m0, s29
	s_nop 0
	buffer_load_dwordx4 v131, s[60:63], s37 offen lds
	s_barrier
	s_waitcnt lgkmcnt(6)
	s_setprio 1
	v_mfma_f32_16x16x32_bf16 v[124:127], v[168:171], v[132:135], v[124:127]
	v_mfma_f32_16x16x32_bf16 v[120:123], v[168:171], v[160:163], v[120:123]
	v_mfma_f32_16x16x32_bf16 v[116:119], v[176:179], v[132:135], v[116:119]
	v_mfma_f32_16x16x32_bf16 v[112:115], v[176:179], v[160:163], v[112:115]
	v_mfma_f32_16x16x32_bf16 v[108:111], v[184:187], v[132:135], v[108:111]
	v_mfma_f32_16x16x32_bf16 v[104:107], v[184:187], v[160:163], v[104:107]
	v_mfma_f32_16x16x32_bf16 v[100:103], v[192:195], v[132:135], v[100:103]
	v_mfma_f32_16x16x32_bf16 v[96:99], v[192:195], v[160:163], v[96:99]
	v_mfma_f32_16x16x32_bf16 v[124:127], v[172:175], v[156:159], v[124:127]
	v_mfma_f32_16x16x32_bf16 v[120:123], v[172:175], v[164:167], v[120:123]
	v_mfma_f32_16x16x32_bf16 v[116:119], v[180:183], v[156:159], v[116:119]
	v_mfma_f32_16x16x32_bf16 v[112:115], v[180:183], v[164:167], v[112:115]
	v_mfma_f32_16x16x32_bf16 v[108:111], v[188:191], v[156:159], v[108:111]
	v_mfma_f32_16x16x32_bf16 v[104:107], v[188:191], v[164:167], v[104:107]
	v_mfma_f32_16x16x32_bf16 v[100:103], v[196:199], v[156:159], v[100:103]
	v_mfma_f32_16x16x32_bf16 v[96:99], v[196:199], v[164:167], v[96:99]
	s_setprio 0
	s_barrier
; #define STAGE_A(POFF, h, kt) STAGE_AX(POFF, h, kt, brow)
; #define STAGE_B(POFF, h, kt) STAGE_BX(POFF, h, kt, bcol)
; #define LDA(dst, b, h) _Pragma("unroll") for (int m = 0; m < 4; ++m) _Pragma("unroll") for (int k = 0; k < 2; ++k) \
;     dst[m][k] = *reinterpret_cast<const bf16x8*>((char*)SA(b, h) + lds_byte(wr * 64 + m * 16 + fr, k * 32 + fq * 8))
; #define LDB(dst, b, h) _Pragma("unroll") for (int n = 0; n < 2; ++n) _Pragma("unroll") for (int k = 0; k < 2; ++k) \
;     dst[n][k] = *reinterpret_cast<const bf16x8*>((char*)SB(b, h) + lds_byte(wc * 32 + n * 16 + fr, k * 32 + fq * 8))
; #define MMA(ai, bj, At_, Bt_) do { __builtin_amdgcn_s_setprio(1); \
;     _Pragma("unroll") for (int k = 0; k < 2; ++k) _Pragma("unroll") for (int m = 0; m < 4; ++m) _Pragma("unroll") for (int n = 0; n < 2; ++n) \
;       acc[ai][bj][m][n] = __builtin_amdgcn_mfma_f32_16x16x32_bf16(At_[m][k], Bt_[n][k], acc[ai][bj][m][n], 0, 0, 0); \
;     __builtin_amdgcn_s_setprio(0); } while (0)
; #define WAIT_V(n) asm volatile("s_waitcnt vmcnt(" #n ")" ::: "memory")
; #define BAR __builtin_amdgcn_s_barrier()
; #define SCHED __builtin_amdgcn_sched_barrier(0)
; template <int EPI, int N, int K>
; __device__ __forceinline__ void gemm_phase(const bf16_t* __restrict__ A, const bf16_t* __restrict__ Bt, const EpiArgs ea) {
;     ...
;       LDB(B1, 0, 1); STAGE_B(SB_OFF(0, 0), 0, t + 2);
;       BAR; WAIT_L(0); MMA(0, 1, At, B1); BAR;
;       LDA(At, 0, 1); STAGE_A(SA_OFF(0, 0), 0, t + 2);
;       BAR; WAIT_L(0); MMA(1, 0, At, B0); BAR; SCHED;
;       STAGE_B(SB_OFF(0, 1), 1, t + 2);
;       WAIT_V(6); BAR; MMA(1, 1, At, B1); BAR;
	ds_read_b128 v[200:203], v152
	ds_read_b128 v[204:207], v152 offset:1024
	ds_read_b128 v[208:211], v152 offset:2048
	ds_read_b128 v[212:215], v152 offset:3072
	ds_read_b128 v[246:249], v151 offset:16384
	ds_read_b128 v[250:253], v151 offset:17408
	s_add_i32 s37, s13, s35
	s_add_i32 s38, s37, 0x100
	s_mov_b32 m0, s15
	s_nop 0
	buffer_load_dwordx4 v144, s[76:79], s38 offen lds
	s_add_i32 s38, s37, 0x80100
	s_mov_b32 m0, s16
	s_nop 0
	buffer_load_dwordx4 v144, s[76:79], s38 offen lds
	s_waitcnt vmcnt(6)
	s_barrier
	s_waitcnt lgkmcnt(2)
	s_setprio 1
	v_mfma_f32_16x16x32_bf16 v[92:95], v[168:171], v[200:203], v[92:95]
	v_mfma_f32_16x16x32_bf16 v[88:91], v[168:171], v[208:211], v[88:91]
	v_mfma_f32_16x16x32_bf16 v[84:87], v[176:179], v[200:203], v[84:87]
	v_mfma_f32_16x16x32_bf16 v[80:83], v[176:179], v[208:211], v[80:83]
	v_mfma_f32_16x16x32_bf16 v[76:79], v[184:187], v[200:203], v[76:79]
	v_mfma_f32_16x16x32_bf16 v[72:75], v[184:187], v[208:211], v[72:75]
	v_mfma_f32_16x16x32_bf16 v[68:71], v[192:195], v[200:203], v[68:71]
	v_mfma_f32_16x16x32_bf16 v[64:67], v[192:195], v[208:211], v[64:67]
	v_mfma_f32_16x16x32_bf16 v[92:95], v[172:175], v[204:207], v[92:95]
	v_mfma_f32_16x16x32_bf16 v[88:91], v[172:175], v[212:215], v[88:91]
	v_mfma_f32_16x16x32_bf16 v[84:87], v[180:183], v[204:207], v[84:87]
	v_mfma_f32_16x16x32_bf16 v[80:83], v[180:183], v[212:215], v[80:83]
	v_mfma_f32_16x16x32_bf16 v[76:79], v[188:191], v[204:207], v[76:79]
	v_mfma_f32_16x16x32_bf16 v[72:75], v[188:191], v[212:215], v[72:75]
	v_mfma_f32_16x16x32_bf16 v[68:71], v[196:199], v[204:207], v[68:71]
	v_mfma_f32_16x16x32_bf16 v[64:67], v[196:199], v[212:215], v[64:67]
	s_setprio 0
	s_barrier
	ds_read_b128 v[168:171], v148 offset:32768
	ds_read_b128 v[172:175], v148 offset:33792
	ds_read_b128 v[176:179], v149 offset:32768
	ds_read_b128 v[180:183], v149 offset:33792
	ds_read_b128 v[184:187], v150 offset:32768
	ds_read_b128 v[188:191], v150 offset:33792
	s_add_i32 s38, s36, 0x100
	s_mov_b32 m0, s14
	s_nop 0
	buffer_load_dwordx4 v131, s[60:63], s38 offen lds
	s_add_i32 s39, s36, 0x40100
	s_mov_b32 m0, s17
	s_nop 0
	buffer_load_dwordx4 v131, s[60:63], s39 offen lds
	s_waitcnt vmcnt(10)
	s_barrier
	s_waitcnt lgkmcnt(6)
	s_setprio 1
	v_mfma_f32_16x16x32_bf16 v[60:63], v[218:221], v[132:135], v[60:63]
	v_mfma_f32_16x16x32_bf16 v[56:59], v[218:221], v[160:163], v[56:59]
	v_mfma_f32_16x16x32_bf16 v[52:55], v[226:229], v[132:135], v[52:55]
	v_mfma_f32_16x16x32_bf16 v[48:51], v[226:229], v[160:163], v[48:51]
	v_mfma_f32_16x16x32_bf16 v[44:47], v[238:241], v[132:135], v[44:47]
	v_mfma_f32_16x16x32_bf16 v[40:43], v[238:241], v[160:163], v[40:43]
	v_mfma_f32_16x16x32_bf16 v[36:39], v[246:249], v[132:135], v[36:39]
	v_mfma_f32_16x16x32_bf16 v[32:35], v[246:249], v[160:163], v[32:35]
	v_mfma_f32_16x16x32_bf16 v[60:63], v[222:225], v[156:159], v[60:63]
	v_mfma_f32_16x16x32_bf16 v[56:59], v[222:225], v[164:167], v[56:59]
	v_mfma_f32_16x16x32_bf16 v[52:55], v[230:233], v[156:159], v[52:55]
	v_mfma_f32_16x16x32_bf16 v[48:51], v[230:233], v[164:167], v[48:51]
	v_mfma_f32_16x16x32_bf16 v[44:47], v[242:245], v[156:159], v[44:47]
	v_mfma_f32_16x16x32_bf16 v[40:43], v[242:245], v[164:167], v[40:43]
	v_mfma_f32_16x16x32_bf16 v[36:39], v[250:253], v[156:159], v[36:39]
	v_mfma_f32_16x16x32_bf16 v[32:35], v[250:253], v[164:167], v[32:35]
	s_setprio 0
	s_barrier
	ds_read_b128 v[132:135], v153
	ds_read_b128 v[156:159], v153 offset:1024
	ds_read_b128 v[160:163], v153 offset:2048
	ds_read_b128 v[164:167], v153 offset:3072
	ds_read_b128 v[192:195], v151 offset:32768
	ds_read_b128 v[196:199], v151 offset:33792
	s_add_i32 s39, s37, 0x2100
	s_mov_b32 m0, s18
	s_nop 0
	buffer_load_dwordx4 v144, s[76:79], s39 offen lds
	s_add_i32 s39, s37, 0x82100
	s_mov_b32 m0, s19
	s_nop 0
	buffer_load_dwordx4 v144, s[76:79], s39 offen lds
	s_waitcnt vmcnt(6)
	s_barrier
	s_setprio 1
	v_mfma_f32_16x16x32_bf16 v[28:31], v[218:221], v[200:203], v[28:31]
	v_mfma_f32_16x16x32_bf16 v[24:27], v[218:221], v[208:211], v[24:27]
	v_mfma_f32_16x16x32_bf16 v[20:23], v[226:229], v[200:203], v[20:23]
	v_mfma_f32_16x16x32_bf16 v[16:19], v[226:229], v[208:211], v[16:19]
	v_mfma_f32_16x16x32_bf16 v[12:15], v[238:241], v[200:203], v[12:15]
	v_mfma_f32_16x16x32_bf16 v[8:11], v[238:241], v[208:211], v[8:11]
	v_mfma_f32_16x16x32_bf16 v[4:7], v[246:249], v[200:203], v[4:7]
	v_mfma_f32_16x16x32_bf16 v[0:3], v[246:249], v[208:211], v[0:3]
	v_mfma_f32_16x16x32_bf16 v[28:31], v[222:225], v[204:207], v[28:31]
	v_mfma_f32_16x16x32_bf16 v[24:27], v[222:225], v[212:215], v[24:27]
	v_mfma_f32_16x16x32_bf16 v[20:23], v[230:233], v[204:207], v[20:23]
	v_mfma_f32_16x16x32_bf16 v[16:19], v[230:233], v[212:215], v[16:19]
	v_mfma_f32_16x16x32_bf16 v[12:15], v[242:245], v[204:207], v[12:15]
	v_mfma_f32_16x16x32_bf16 v[8:11], v[242:245], v[212:215], v[8:11]
	v_mfma_f32_16x16x32_bf16 v[4:7], v[250:253], v[204:207], v[4:7]
	v_mfma_f32_16x16x32_bf16 v[0:3], v[250:253], v[212:215], v[0:3]
	s_setprio 0
	s_barrier
	ds_read_b128 v[218:221], v148 offset:49152
	ds_read_b128 v[222:225], v148 offset:50176
	ds_read_b128 v[226:229], v149 offset:49152
	ds_read_b128 v[230:233], v149 offset:50176
	ds_read_b128 v[238:241], v150 offset:49152
	ds_read_b128 v[242:245], v150 offset:50176
	s_or_b32 s39, s38, 0x80000
	s_mov_b32 m0, s20
	s_nop 0
	buffer_load_dwordx4 v131, s[60:63], s39 offen lds
	s_or_b32 s38, s38, 0xc0000
	s_mov_b32 m0, s21
	s_nop 0
	buffer_load_dwordx4 v131, s[60:63], s38 offen lds
	s_barrier
; #define STAGE_A(POFF, h, kt) STAGE_AX(POFF, h, kt, brow)
; #define STAGE_B(POFF, h, kt) STAGE_BX(POFF, h, kt, bcol)
; #define LDA(dst, b, h) _Pragma("unroll") for (int m = 0; m < 4; ++m) _Pragma("unroll") for (int k = 0; k < 2; ++k) \
;     dst[m][k] = *reinterpret_cast<const bf16x8*>((char*)SA(b, h) + lds_byte(wr * 64 + m * 16 + fr, k * 32 + fq * 8))
; #define LDB(dst, b, h) _Pragma("unroll") for (int n = 0; n < 2; ++n) _Pragma("unroll") for (int k = 0; k < 2; ++k) \
;     dst[n][k] = *reinterpret_cast<const bf16x8*>((char*)SB(b, h) + lds_byte(wc * 32 + n * 16 + fr, k * 32 + fq * 8))
; #define MMA(ai, bj, At_, Bt_) do { __builtin_amdgcn_s_setprio(1); \
;     _Pragma("unroll") for (int k = 0; k < 2; ++k) _Pragma("unroll") for (int m = 0; m < 4; ++m) _Pragma("unroll") for (int n = 0; n < 2; ++n) \
;       acc[ai][bj][m][n] = __builtin_amdgcn_mfma_f32_16x16x32_bf16(At_[m][k], Bt_[n][k], acc[ai][bj][m][n], 0, 0, 0); \
;     __builtin_amdgcn_s_setprio(0); } while (0)
; #define WAIT_V(n) asm volatile("s_waitcnt vmcnt(" #n ")" ::: "memory")
; #define BAR __builtin_amdgcn_s_barrier()
; #define SCHED __builtin_amdgcn_sched_barrier(0)
; template <int EPI, int N, int K>
; __device__ __forceinline__ void gemm_phase(const bf16_t* __restrict__ A, const bf16_t* __restrict__ Bt, const EpiArgs ea) {
;     ...
;       LDB(B0, 1, 0); SCHED; LDA(At, 1, 0); STAGE_A(SA_OFF(0, 1), 1, t + 2);
;       WAIT_L(8); BAR; WAIT_L(0); MMA(0, 0, At, B0); BAR; SCHED;
;       LDB(B1, 1, 1); STAGE_B(SB_OFF(1, 0), 0, t + 3);
;       BAR; WAIT_L(0); MMA(0, 1, At, B1); BAR;
;       LDA(At, 1, 1); STAGE_A(SA_OFF(1, 0), 0, t + 3);
;       BAR; WAIT_L(0); MMA(1, 0, At, B0); BAR; SCHED;
;       STAGE_B(SB_OFF(1, 1), 1, t + 3);
;       WAIT_V(6); BAR; MMA(1, 1, At, B1); BAR;
	s_waitcnt lgkmcnt(6)
	s_setprio 1
	v_mfma_f32_16x16x32_bf16 v[124:127], v[168:171], v[132:135], v[124:127]
	v_mfma_f32_16x16x32_bf16 v[120:123], v[168:171], v[160:163], v[120:123]
	v_mfma_f32_16x16x32_bf16 v[116:119], v[176:179], v[132:135], v[116:119]
	v_mfma_f32_16x16x32_bf16 v[112:115], v[176:179], v[160:163], v[112:115]
	v_mfma_f32_16x16x32_bf16 v[108:111], v[184:187], v[132:135], v[108:111]
	v_mfma_f32_16x16x32_bf16 v[104:107], v[184:187], v[160:163], v[104:107]
	v_mfma_f32_16x16x32_bf16 v[100:103], v[192:195], v[132:135], v[100:103]
	v_mfma_f32_16x16x32_bf16 v[96:99], v[192:195], v[160:163], v[96:99]
	v_mfma_f32_16x16x32_bf16 v[124:127], v[172:175], v[156:159], v[124:127]
	v_mfma_f32_16x16x32_bf16 v[120:123], v[172:175], v[164:167], v[120:123]
	v_mfma_f32_16x16x32_bf16 v[116:119], v[180:183], v[156:159], v[116:119]
	v_mfma_f32_16x16x32_bf16 v[112:115], v[180:183], v[164:167], v[112:115]
	v_mfma_f32_16x16x32_bf16 v[108:111], v[188:191], v[156:159], v[108:111]
	v_mfma_f32_16x16x32_bf16 v[104:107], v[188:191], v[164:167], v[104:107]
	v_mfma_f32_16x16x32_bf16 v[100:103], v[196:199], v[156:159], v[100:103]
	v_mfma_f32_16x16x32_bf16 v[96:99], v[196:199], v[164:167], v[96:99]
	s_setprio 0
	s_barrier
	ds_read_b128 v[200:203], v154
	ds_read_b128 v[204:207], v154 offset:1024
	ds_read_b128 v[208:211], v154 offset:2048
	ds_read_b128 v[212:215], v154 offset:3072
	ds_read_b128 v[246:249], v151 offset:49152
	ds_read_b128 v[250:253], v151 offset:50176
	s_add_i32 s38, s37, 0x180
	s_mov_b32 m0, s22
	s_nop 0
	buffer_load_dwordx4 v144, s[76:79], s38 offen lds
	s_add_i32 s38, s37, 0x80180
	s_mov_b32 m0, s23
	s_nop 0
	buffer_load_dwordx4 v144, s[76:79], s38 offen lds
	s_waitcnt vmcnt(6)
	s_barrier
	s_waitcnt lgkmcnt(2)
	s_setprio 1
	v_mfma_f32_16x16x32_bf16 v[92:95], v[168:171], v[200:203], v[92:95]
	v_mfma_f32_16x16x32_bf16 v[88:91], v[168:171], v[208:211], v[88:91]
	v_mfma_f32_16x16x32_bf16 v[84:87], v[176:179], v[200:203], v[84:87]
	v_mfma_f32_16x16x32_bf16 v[80:83], v[176:179], v[208:211], v[80:83]
	v_mfma_f32_16x16x32_bf16 v[76:79], v[184:187], v[200:203], v[76:79]
	v_mfma_f32_16x16x32_bf16 v[72:75], v[184:187], v[208:211], v[72:75]
	v_mfma_f32_16x16x32_bf16 v[68:71], v[192:195], v[200:203], v[68:71]
	v_mfma_f32_16x16x32_bf16 v[64:67], v[192:195], v[208:211], v[64:67]
	v_mfma_f32_16x16x32_bf16 v[92:95], v[172:175], v[204:207], v[92:95]
	v_mfma_f32_16x16x32_bf16 v[88:91], v[172:175], v[212:215], v[88:91]
	v_mfma_f32_16x16x32_bf16 v[84:87], v[180:183], v[204:207], v[84:87]
	v_mfma_f32_16x16x32_bf16 v[80:83], v[180:183], v[212:215], v[80:83]
	v_mfma_f32_16x16x32_bf16 v[76:79], v[188:191], v[204:207], v[76:79]
	v_mfma_f32_16x16x32_bf16 v[72:75], v[188:191], v[212:215], v[72:75]
	v_mfma_f32_16x16x32_bf16 v[68:71], v[196:199], v[204:207], v[68:71]
	v_mfma_f32_16x16x32_bf16 v[64:67], v[196:199], v[212:215], v[64:67]
	s_setprio 0
	s_barrier
	ds_read_b128 v[168:171], v148
	ds_read_b128 v[172:175], v148 offset:1024
	ds_read_b128 v[176:179], v149
	ds_read_b128 v[180:183], v149 offset:1024
	ds_read_b128 v[184:187], v150
	ds_read_b128 v[188:191], v150 offset:1024
	s_add_i32 s38, s36, 0x180
	s_mov_b32 m0, s24
	s_nop 0
	buffer_load_dwordx4 v131, s[60:63], s38 offen lds
	s_add_i32 s36, s36, 0x40180
	s_mov_b32 m0, s25
	s_nop 0
	buffer_load_dwordx4 v131, s[60:63], s36 offen lds
	s_waitcnt vmcnt(10)
	s_barrier
	s_waitcnt lgkmcnt(6)
	s_setprio 1
	v_mfma_f32_16x16x32_bf16 v[60:63], v[218:221], v[132:135], v[60:63]
	v_mfma_f32_16x16x32_bf16 v[56:59], v[218:221], v[160:163], v[56:59]
	v_mfma_f32_16x16x32_bf16 v[52:55], v[226:229], v[132:135], v[52:55]
	v_mfma_f32_16x16x32_bf16 v[48:51], v[226:229], v[160:163], v[48:51]
	v_mfma_f32_16x16x32_bf16 v[44:47], v[238:241], v[132:135], v[44:47]
	v_mfma_f32_16x16x32_bf16 v[40:43], v[238:241], v[160:163], v[40:43]
	v_mfma_f32_16x16x32_bf16 v[36:39], v[246:249], v[132:135], v[36:39]
	v_mfma_f32_16x16x32_bf16 v[32:35], v[246:249], v[160:163], v[32:35]
	v_mfma_f32_16x16x32_bf16 v[60:63], v[222:225], v[156:159], v[60:63]
	v_mfma_f32_16x16x32_bf16 v[56:59], v[222:225], v[164:167], v[56:59]
	v_mfma_f32_16x16x32_bf16 v[52:55], v[230:233], v[156:159], v[52:55]
	v_mfma_f32_16x16x32_bf16 v[48:51], v[230:233], v[164:167], v[48:51]
	v_mfma_f32_16x16x32_bf16 v[44:47], v[242:245], v[156:159], v[44:47]
	v_mfma_f32_16x16x32_bf16 v[40:43], v[242:245], v[164:167], v[40:43]
	v_mfma_f32_16x16x32_bf16 v[36:39], v[250:253], v[156:159], v[36:39]
	v_mfma_f32_16x16x32_bf16 v[32:35], v[250:253], v[164:167], v[32:35]
	s_setprio 0
	s_barrier
	ds_read_b128 v[132:135], v147
	ds_read_b128 v[156:159], v147 offset:1024
	ds_read_b128 v[160:163], v147 offset:2048
	ds_read_b128 v[164:167], v147 offset:3072
	ds_read_b128 v[192:195], v151
	ds_read_b128 v[196:199], v151 offset:1024
	s_add_i32 s36, s37, 0x2180
	s_mov_b32 m0, s26
	s_nop 0
	buffer_load_dwordx4 v144, s[76:79], s36 offen lds
	s_add_i32 s37, s37, 0x82180
	s_mov_b32 m0, s27
	s_nop 0
	buffer_load_dwordx4 v144, s[76:79], s37 offen lds
	s_waitcnt vmcnt(6)
	s_barrier
	s_setprio 1
	v_mfma_f32_16x16x32_bf16 v[28:31], v[218:221], v[200:203], v[28:31]
	v_mfma_f32_16x16x32_bf16 v[24:27], v[218:221], v[208:211], v[24:27]
	v_mfma_f32_16x16x32_bf16 v[20:23], v[226:229], v[200:203], v[20:23]
	v_mfma_f32_16x16x32_bf16 v[16:19], v[226:229], v[208:211], v[16:19]
	v_mfma_f32_16x16x32_bf16 v[12:15], v[238:241], v[200:203], v[12:15]
	v_mfma_f32_16x16x32_bf16 v[8:11], v[238:241], v[208:211], v[8:11]
	v_mfma_f32_16x16x32_bf16 v[4:7], v[246:249], v[200:203], v[4:7]
	v_mfma_f32_16x16x32_bf16 v[0:3], v[246:249], v[208:211], v[0:3]
	v_mfma_f32_16x16x32_bf16 v[28:31], v[222:225], v[204:207], v[28:31]
	v_mfma_f32_16x16x32_bf16 v[24:27], v[222:225], v[212:215], v[24:27]
	v_mfma_f32_16x16x32_bf16 v[20:23], v[230:233], v[204:207], v[20:23]
	v_mfma_f32_16x16x32_bf16 v[16:19], v[230:233], v[212:215], v[16:19]
	v_mfma_f32_16x16x32_bf16 v[12:15], v[242:245], v[204:207], v[12:15]
	v_mfma_f32_16x16x32_bf16 v[8:11], v[242:245], v[212:215], v[8:11]
	v_mfma_f32_16x16x32_bf16 v[4:7], v[250:253], v[204:207], v[4:7]
	v_mfma_f32_16x16x32_bf16 v[0:3], v[250:253], v[212:215], v[0:3]
	s_setprio 0
	s_add_i32 s34, s34, 2
	s_addk_i32 s35, 0x100
	s_cmp_lt_u32 s34, 28
	s_barrier
; #define STAGE_A(POFF, h, kt) STAGE_AX(POFF, h, kt, brow)
; #define LDA(dst, b, h) _Pragma("unroll") for (int m = 0; m < 4; ++m) _Pragma("unroll") for (int k = 0; k < 2; ++k) \
;     dst[m][k] = *reinterpret_cast<const bf16x8*>((char*)SA(b, h) + lds_byte(wr * 64 + m * 16 + fr, k * 32 + fq * 8))
; #define LDB(dst, b, h) _Pragma("unroll") for (int n = 0; n < 2; ++n) _Pragma("unroll") for (int k = 0; k < 2; ++k) \
;     dst[n][k] = *reinterpret_cast<const bf16x8*>((char*)SB(b, h) + lds_byte(wc * 32 + n * 16 + fr, k * 32 + fq * 8))
; #define MMA(ai, bj, At_, Bt_) do { __builtin_amdgcn_s_setprio(1); \
;     _Pragma("unroll") for (int k = 0; k < 2; ++k) _Pragma("unroll") for (int m = 0; m < 4; ++m) _Pragma("unroll") for (int n = 0; n < 2; ++n) \
;       acc[ai][bj][m][n] = __builtin_amdgcn_mfma_f32_16x16x32_bf16(At_[m][k], Bt_[n][k], acc[ai][bj][m][n], 0, 0, 0); \
;     __builtin_amdgcn_s_setprio(0); } while (0)
; #define WAIT_V(n) asm volatile("s_waitcnt vmcnt(" #n ")" ::: "memory")
; #define BAR __builtin_amdgcn_s_barrier()
; template <int EPI, int N, int K>
; __device__ __forceinline__ void gemm_phase(const bf16_t* __restrict__ A, const bf16_t* __restrict__ Bt, const EpiArgs ea) {
;     ...
;     { LDB(B0, 0, 0); LDA(At, 0, 0); STAGE_A(SA_OFF(1, 1), 1, nt - 1);
;       BAR; WAIT_L(0); MMA(0, 0, At, B0); BAR;
;       LDB(B1, 0, 1); BAR; WAIT_L(0); MMA(0, 1, At, B1); BAR;
;       LDA(At, 0, 1); WAIT_V(4); BAR; WAIT_L(0); MMA(1, 0, At, B0); MMA(1, 1, At, B1); BAR; }
	s_cbranch_scc1 .LBB0_390
	s_and_b32 s3, s3, 0x700
	s_lshl_b32 s2, s2, 11
	s_or_b32 s31, s3, s2
	s_lshl_b32 s2, s31, 12
	s_or_b32 s3, s2, 0x80f80
	s_mov_b32 m0, s28
	s_nop 0
	buffer_load_dwordx4 v131, s[60:63], s3 offen lds
	s_or_b32 s2, s2, 0xc0f80
	s_mov_b32 m0, s29
	s_nop 0
	buffer_load_dwordx4 v131, s[60:63], s2 offen lds
	s_barrier
	s_waitcnt lgkmcnt(0)
	s_setprio 1
	v_mfma_f32_16x16x32_bf16 v[124:127], v[168:171], v[132:135], v[124:127]
	v_mfma_f32_16x16x32_bf16 v[120:123], v[168:171], v[160:163], v[120:123]
	v_mfma_f32_16x16x32_bf16 v[116:119], v[176:179], v[132:135], v[116:119]
	v_mfma_f32_16x16x32_bf16 v[112:115], v[176:179], v[160:163], v[112:115]
	v_mfma_f32_16x16x32_bf16 v[108:111], v[184:187], v[132:135], v[108:111]
	v_mfma_f32_16x16x32_bf16 v[104:107], v[184:187], v[160:163], v[104:107]
	v_mfma_f32_16x16x32_bf16 v[100:103], v[192:195], v[132:135], v[100:103]
	v_mfma_f32_16x16x32_bf16 v[96:99], v[192:195], v[160:163], v[96:99]
	v_mfma_f32_16x16x32_bf16 v[124:127], v[172:175], v[156:159], v[124:127]
	v_mfma_f32_16x16x32_bf16 v[120:123], v[172:175], v[164:167], v[120:123]
	v_mfma_f32_16x16x32_bf16 v[116:119], v[180:183], v[156:159], v[116:119]
	v_mfma_f32_16x16x32_bf16 v[112:115], v[180:183], v[164:167], v[112:115]
	v_mfma_f32_16x16x32_bf16 v[108:111], v[188:191], v[156:159], v[108:111]
	v_mfma_f32_16x16x32_bf16 v[104:107], v[188:191], v[164:167], v[104:107]
	v_mfma_f32_16x16x32_bf16 v[100:103], v[196:199], v[156:159], v[100:103]
	v_mfma_f32_16x16x32_bf16 v[96:99], v[196:199], v[164:167], v[96:99]
	s_setprio 0
	s_barrier
	ds_read_b128 v[200:203], v152
	ds_read_b128 v[204:207], v152 offset:1024
	ds_read_b128 v[208:211], v152 offset:2048
	ds_read_b128 v[212:215], v152 offset:3072
	s_barrier
	s_waitcnt lgkmcnt(0)
	s_setprio 1
	v_mfma_f32_16x16x32_bf16 v[92:95], v[168:171], v[200:203], v[92:95]
	v_mfma_f32_16x16x32_bf16 v[88:91], v[168:171], v[208:211], v[88:91]
	v_mfma_f32_16x16x32_bf16 v[76:79], v[184:187], v[200:203], v[76:79]
	v_mfma_f32_16x16x32_bf16 v[72:75], v[184:187], v[208:211], v[72:75]
	v_mfma_f32_16x16x32_bf16 v[84:87], v[176:179], v[200:203], v[84:87]
	v_mfma_f32_16x16x32_bf16 v[80:83], v[176:179], v[208:211], v[80:83]
	v_mfma_f32_16x16x32_bf16 v[68:71], v[192:195], v[200:203], v[68:71]
	v_mfma_f32_16x16x32_bf16 v[64:67], v[192:195], v[208:211], v[64:67]
	v_mfma_f32_16x16x32_bf16 v[92:95], v[172:175], v[204:207], v[92:95]
	v_mfma_f32_16x16x32_bf16 v[88:91], v[172:175], v[212:215], v[88:91]
	v_mfma_f32_16x16x32_bf16 v[76:79], v[188:191], v[204:207], v[76:79]
	v_mfma_f32_16x16x32_bf16 v[72:75], v[188:191], v[212:215], v[72:75]
	v_mfma_f32_16x16x32_bf16 v[168:171], v[180:183], v[204:207], v[84:87]
	v_mfma_f32_16x16x32_bf16 v[172:175], v[180:183], v[212:215], v[80:83]
	v_mfma_f32_16x16x32_bf16 v[176:179], v[196:199], v[204:207], v[68:71]
	v_mfma_f32_16x16x32_bf16 v[180:183], v[196:199], v[212:215], v[64:67]
	s_setprio 0
	s_barrier
	s_nop 0
	ds_read_b128 v[64:67], v148 offset:16384
	ds_read_b128 v[68:71], v148 offset:17408
	ds_read_b128 v[80:83], v149 offset:16384
	ds_read_b128 v[84:87], v149 offset:17408
	ds_read_b128 v[184:187], v150 offset:16384
	ds_read_b128 v[188:191], v150 offset:17408
	ds_read_b128 v[192:195], v151 offset:16384
	ds_read_b128 v[196:199], v151 offset:17408
	s_waitcnt vmcnt(4)
	s_barrier
	s_waitcnt lgkmcnt(0)
	s_setprio 1
	v_mfma_f32_16x16x32_bf16 v[60:63], v[64:67], v[132:135], v[60:63]
	v_mfma_f32_16x16x32_bf16 v[56:59], v[64:67], v[160:163], v[56:59]
	v_mfma_f32_16x16x32_bf16 v[52:55], v[80:83], v[132:135], v[52:55]
	v_mfma_f32_16x16x32_bf16 v[48:51], v[80:83], v[160:163], v[48:51]
	v_mfma_f32_16x16x32_bf16 v[44:47], v[184:187], v[132:135], v[44:47]
	v_mfma_f32_16x16x32_bf16 v[40:43], v[184:187], v[160:163], v[40:43]
	v_mfma_f32_16x16x32_bf16 v[36:39], v[192:195], v[132:135], v[36:39]
	v_mfma_f32_16x16x32_bf16 v[32:35], v[192:195], v[160:163], v[32:35]
	v_mfma_f32_16x16x32_bf16 v[60:63], v[68:71], v[156:159], v[60:63]
	v_mfma_f32_16x16x32_bf16 v[56:59], v[68:71], v[164:167], v[56:59]
	v_mfma_f32_16x16x32_bf16 v[52:55], v[84:87], v[156:159], v[52:55]
	v_mfma_f32_16x16x32_bf16 v[48:51], v[84:87], v[164:167], v[48:51]
	v_mfma_f32_16x16x32_bf16 v[44:47], v[188:191], v[156:159], v[44:47]
	v_mfma_f32_16x16x32_bf16 v[40:43], v[188:191], v[164:167], v[40:43]
	v_mfma_f32_16x16x32_bf16 v[36:39], v[196:199], v[156:159], v[36:39]
	v_mfma_f32_16x16x32_bf16 v[32:35], v[196:199], v[164:167], v[32:35]
	s_setprio 0
	s_setprio 1
	v_mfma_f32_16x16x32_bf16 v[28:31], v[64:67], v[200:203], v[28:31]
	v_mfma_f32_16x16x32_bf16 v[24:27], v[64:67], v[208:211], v[24:27]
	v_mfma_f32_16x16x32_bf16 v[4:7], v[192:195], v[200:203], v[4:7]
	v_mfma_f32_16x16x32_bf16 v[0:3], v[192:195], v[208:211], v[0:3]
	v_mfma_f32_16x16x32_bf16 v[20:23], v[80:83], v[200:203], v[20:23]
	v_mfma_f32_16x16x32_bf16 v[16:19], v[80:83], v[208:211], v[16:19]
	v_mfma_f32_16x16x32_bf16 v[12:15], v[184:187], v[200:203], v[12:15]
	v_mfma_f32_16x16x32_bf16 v[8:11], v[184:187], v[208:211], v[8:11]
	v_mfma_f32_16x16x32_bf16 v[28:31], v[68:71], v[204:207], v[28:31]
	v_mfma_f32_16x16x32_bf16 v[24:27], v[68:71], v[212:215], v[24:27]
	v_mfma_f32_16x16x32_bf16 v[4:7], v[196:199], v[204:207], v[4:7]
	v_mfma_f32_16x16x32_bf16 v[0:3], v[196:199], v[212:215], v[0:3]
	v_mfma_f32_16x16x32_bf16 v[132:135], v[84:87], v[204:207], v[20:23]
	v_mfma_f32_16x16x32_bf16 v[156:159], v[84:87], v[212:215], v[16:19]
	v_mfma_f32_16x16x32_bf16 v[160:163], v[188:191], v[204:207], v[12:15]
	v_mfma_f32_16x16x32_bf16 v[164:167], v[188:191], v[212:215], v[8:11]
	s_setprio 0
	s_barrier
; #define LDA(dst, b, h) _Pragma("unroll") for (int m = 0; m < 4; ++m) _Pragma("unroll") for (int k = 0; k < 2; ++k) \
;     dst[m][k] = *reinterpret_cast<const bf16x8*>((char*)SA(b, h) + lds_byte(wr * 64 + m * 16 + fr, k * 32 + fq * 8))
; #define LDB(dst, b, h) _Pragma("unroll") for (int n = 0; n < 2; ++n) _Pragma("unroll") for (int k = 0; k < 2; ++k) \
;     dst[n][k] = *reinterpret_cast<const bf16x8*>((char*)SB(b, h) + lds_byte(wc * 32 + n * 16 + fr, k * 32 + fq * 8))
; #define MMA(ai, bj, At_, Bt_) do { __builtin_amdgcn_s_setprio(1); \
;     _Pragma("unroll") for (int k = 0; k < 2; ++k) _Pragma("unroll") for (int m = 0; m < 4; ++m) _Pragma("unroll") for (int n = 0; n < 2; ++n) \
;       acc[ai][bj][m][n] = __builtin_amdgcn_mfma_f32_16x16x32_bf16(At_[m][k], Bt_[n][k], acc[ai][bj][m][n], 0, 0, 0); \
;     __builtin_amdgcn_s_setprio(0); } while (0)
; #define WAIT_V(n) asm volatile("s_waitcnt vmcnt(" #n ")" ::: "memory")
; #define BAR __builtin_amdgcn_s_barrier()
; template <int EPI, int N, int K>
; __device__ __forceinline__ void gemm_phase(const bf16_t* __restrict__ A, const bf16_t* __restrict__ Bt, const EpiArgs ea) {
;     ...
;     { LDB(B0, 1, 0); LDA(At, 1, 0); WAIT_V(2); BAR; WAIT_L(0); MMA(0, 0, At, B0); BAR;
;       LDB(B1, 1, 1); WAIT_V(0); BAR; WAIT_L(0); MMA(0, 1, At, B1); BAR;
;       LDA(At, 1, 1); BAR; WAIT_L(0); MMA(1, 0, At, B0); MMA(1, 1, At, B1); BAR; }
;     if (wr == 0) BAR;
	s_nop 0
	ds_read_b128 v[8:11], v153
	ds_read_b128 v[12:15], v153 offset:1024
	ds_read_b128 v[16:19], v153 offset:2048
	ds_read_b128 v[184:187], v153 offset:3072
	ds_read_b128 v[20:23], v148 offset:32768
	ds_read_b128 v[188:191], v148 offset:33792
	ds_read_b128 v[192:195], v149 offset:32768
	ds_read_b128 v[196:199], v149 offset:33792
	ds_read_b128 v[200:203], v150 offset:32768
	ds_read_b128 v[204:207], v150 offset:33792
	ds_read_b128 v[208:211], v151 offset:32768
	ds_read_b128 v[212:215], v151 offset:33792
	s_waitcnt vmcnt(2)
	s_barrier
	s_waitcnt lgkmcnt(0)
	s_setprio 1
	v_mfma_f32_16x16x32_bf16 v[64:67], v[20:23], v[8:11], v[124:127]
	v_mfma_f32_16x16x32_bf16 v[68:71], v[20:23], v[16:19], v[120:123]
	v_mfma_f32_16x16x32_bf16 v[80:83], v[192:195], v[8:11], v[116:119]
	v_mfma_f32_16x16x32_bf16 v[84:87], v[192:195], v[16:19], v[112:115]
	v_mfma_f32_16x16x32_bf16 v[108:111], v[200:203], v[8:11], v[108:111]
	v_mfma_f32_16x16x32_bf16 v[104:107], v[200:203], v[16:19], v[104:107]
	v_mfma_f32_16x16x32_bf16 v[120:123], v[208:211], v[8:11], v[100:103]
	v_mfma_f32_16x16x32_bf16 v[124:127], v[208:211], v[16:19], v[96:99]
	v_mfma_f32_16x16x32_bf16 v[116:119], v[188:191], v[12:15], v[64:67]
	v_mfma_f32_16x16x32_bf16 v[112:115], v[188:191], v[184:187], v[68:71]
	v_mfma_f32_16x16x32_bf16 v[100:103], v[196:199], v[12:15], v[80:83]
	v_mfma_f32_16x16x32_bf16 v[96:99], v[196:199], v[184:187], v[84:87]
	v_mfma_f32_16x16x32_bf16 v[84:87], v[204:207], v[12:15], v[108:111]
	v_mfma_f32_16x16x32_bf16 v[80:83], v[204:207], v[184:187], v[104:107]
	v_mfma_f32_16x16x32_bf16 v[68:71], v[212:215], v[12:15], v[120:123]
	v_mfma_f32_16x16x32_bf16 v[64:67], v[212:215], v[184:187], v[124:127]
	s_setprio 0
	s_barrier
	ds_read_b128 v[216:219], v154
	ds_read_b128 v[220:223], v154 offset:1024
	ds_read_b128 v[224:227], v154 offset:2048
	ds_read_b128 v[228:231], v154 offset:3072
	s_waitcnt vmcnt(0)
	s_barrier
	s_waitcnt lgkmcnt(0)
	s_setprio 1
	v_mfma_f32_16x16x32_bf16 v[92:95], v[20:23], v[216:219], v[92:95]
	v_mfma_f32_16x16x32_bf16 v[20:23], v[20:23], v[224:227], v[88:91]
	v_mfma_f32_16x16x32_bf16 v[88:91], v[192:195], v[216:219], v[168:171]
	v_mfma_f32_16x16x32_bf16 v[104:107], v[192:195], v[224:227], v[172:175]
	v_mfma_f32_16x16x32_bf16 v[76:79], v[200:203], v[216:219], v[76:79]
	v_mfma_f32_16x16x32_bf16 v[72:75], v[200:203], v[224:227], v[72:75]
	v_mfma_f32_16x16x32_bf16 v[168:171], v[208:211], v[216:219], v[176:179]
	v_mfma_f32_16x16x32_bf16 v[172:175], v[208:211], v[224:227], v[180:183]
	v_mfma_f32_16x16x32_bf16 v[124:127], v[188:191], v[220:223], v[92:95]
	v_mfma_f32_16x16x32_bf16 v[120:123], v[188:191], v[228:231], v[20:23]
	v_mfma_f32_16x16x32_bf16 v[108:111], v[196:199], v[220:223], v[88:91]
	v_mfma_f32_16x16x32_bf16 v[104:107], v[196:199], v[228:231], v[104:107]
	v_mfma_f32_16x16x32_bf16 v[92:95], v[204:207], v[220:223], v[76:79]
	v_mfma_f32_16x16x32_bf16 v[88:91], v[204:207], v[228:231], v[72:75]
	v_mfma_f32_16x16x32_bf16 v[76:79], v[212:215], v[220:223], v[168:171]
	v_mfma_f32_16x16x32_bf16 v[72:75], v[212:215], v[228:231], v[172:175]
	s_setprio 0
	s_barrier
	ds_read_b128 v[168:171], v148 offset:49152
	ds_read_b128 v[172:175], v148 offset:50176
	ds_read_b128 v[176:179], v149 offset:49152
	ds_read_b128 v[180:183], v149 offset:50176
	ds_read_b128 v[188:191], v150 offset:49152
	ds_read_b128 v[192:195], v150 offset:50176
	ds_read_b128 v[196:199], v151 offset:49152
	ds_read_b128 v[200:203], v151 offset:50176
	s_barrier
	s_waitcnt lgkmcnt(0)
	s_setprio 1
	v_mfma_f32_16x16x32_bf16 v[20:23], v[168:171], v[8:11], v[60:63]
	v_mfma_f32_16x16x32_bf16 v[56:59], v[168:171], v[16:19], v[56:59]
	v_mfma_f32_16x16x32_bf16 v[60:63], v[176:179], v[8:11], v[52:55]
	v_mfma_f32_16x16x32_bf16 v[204:207], v[176:179], v[16:19], v[48:51]
	v_mfma_f32_16x16x32_bf16 v[44:47], v[188:191], v[8:11], v[44:47]
	v_mfma_f32_16x16x32_bf16 v[40:43], v[188:191], v[16:19], v[40:43]
	v_mfma_f32_16x16x32_bf16 v[8:11], v[196:199], v[8:11], v[36:39]
	v_mfma_f32_16x16x32_bf16 v[208:211], v[196:199], v[16:19], v[32:35]
	v_mfma_f32_16x16x32_bf16 v[52:55], v[172:175], v[12:15], v[20:23]
	v_mfma_f32_16x16x32_bf16 v[48:51], v[172:175], v[184:187], v[56:59]
	v_mfma_f32_16x16x32_bf16 v[36:39], v[180:183], v[12:15], v[60:63]
	v_mfma_f32_16x16x32_bf16 v[32:35], v[180:183], v[184:187], v[204:207]
	v_mfma_f32_16x16x32_bf16 v[20:23], v[192:195], v[12:15], v[44:47]
	v_mfma_f32_16x16x32_bf16 v[16:19], v[192:195], v[184:187], v[40:43]
	v_mfma_f32_16x16x32_bf16 v[8:11], v[200:203], v[12:15], v[8:11]
	v_mfma_f32_16x16x32_bf16 v[12:15], v[200:203], v[184:187], v[208:211]
	s_setprio 0
	s_setprio 1
	v_mfma_f32_16x16x32_bf16 v[28:31], v[168:171], v[216:219], v[28:31]
	v_mfma_f32_16x16x32_bf16 v[24:27], v[168:171], v[224:227], v[24:27]
	v_mfma_f32_16x16x32_bf16 v[40:43], v[176:179], v[216:219], v[132:135]
	v_mfma_f32_16x16x32_bf16 v[132:135], v[176:179], v[224:227], v[156:159]
	v_mfma_f32_16x16x32_bf16 v[156:159], v[188:191], v[216:219], v[160:163]
	v_mfma_f32_16x16x32_bf16 v[160:163], v[188:191], v[224:227], v[164:167]
	v_mfma_f32_16x16x32_bf16 v[4:7], v[196:199], v[216:219], v[4:7]
	v_mfma_f32_16x16x32_bf16 v[0:3], v[196:199], v[224:227], v[0:3]
	v_mfma_f32_16x16x32_bf16 v[60:63], v[172:175], v[220:223], v[28:31]
	v_mfma_f32_16x16x32_bf16 v[56:59], v[172:175], v[228:231], v[24:27]
	v_mfma_f32_16x16x32_bf16 v[44:47], v[180:183], v[220:223], v[40:43]
	v_mfma_f32_16x16x32_bf16 v[40:43], v[180:183], v[228:231], v[132:135]
	v_mfma_f32_16x16x32_bf16 v[28:31], v[192:195], v[220:223], v[156:159]
	v_mfma_f32_16x16x32_bf16 v[24:27], v[192:195], v[228:231], v[160:163]
	v_mfma_f32_16x16x32_bf16 v[4:7], v[200:203], v[220:223], v[4:7]
	v_mfma_f32_16x16x32_bf16 v[0:3], v[200:203], v[228:231], v[0:3]
	s_setprio 0
	s_barrier
	s_and_saveexec_b64 s[2:3], s[8:9]
	s_cbranch_execz .LBB0_393
	s_barrier

; #define STAGE_A(POFF, h, kt) STAGE_AX(POFF, h, kt, brow)
; #define LDA(dst, b, h) _Pragma("unroll") for (int m = 0; m < 4; ++m) _Pragma("unroll") for (int k = 0; k < 2; ++k) \
;     dst[m][k] = *reinterpret_cast<const bf16x8*>((char*)SA(b, h) + lds_byte(wr * 64 + m * 16 + fr, k * 32 + fq * 8))
; #define LDB(dst, b, h) _Pragma("unroll") for (int n = 0; n < 2; ++n) _Pragma("unroll") for (int k = 0; k < 2; ++k) \
;     dst[n][k] = *reinterpret_cast<const bf16x8*>((char*)SB(b, h) + lds_byte(wc * 32 + n * 16 + fr, k * 32 + fq * 8))
; #define MMA(ai, bj, At_, Bt_) do { __builtin_amdgcn_s_setprio(1); \
;     _Pragma("unroll") for (int k = 0; k < 2; ++k) _Pragma("unroll") for (int m = 0; m < 4; ++m) _Pragma("unroll") for (int n = 0; n < 2; ++n) \
;       acc[ai][bj][m][n] = __builtin_amdgcn_mfma_f32_16x16x32_bf16(At_[m][k], Bt_[n][k], acc[ai][bj][m][n], 0, 0, 0); \
;     __builtin_amdgcn_s_setprio(0); } while (0)
; #define WAIT_V(n) asm volatile("s_waitcnt vmcnt(" #n ")" ::: "memory")
; #define BAR __builtin_amdgcn_s_barrier()
; #define SCHED __builtin_amdgcn_sched_barrier(0)
; #define TILE_RC(w_, brow_, bcol_) do { const int wg_ = ((w_) & 7) * qx + ((w_) >> 3); const int gid_ = wg_ / nig; \
;     brow_ = (gid_ * 8 + ((wg_ % nig) & 7)) * 256; bcol_ = ((wg_ % nig) >> 3) * 256; } while (0)
; template <int EPI, int N, int K>
; __device__ __forceinline__ void gemm_phase(const bf16_t* __restrict__ A, const bf16_t* __restrict__ Bt, const EpiArgs ea) {
;     ...
;   for (int w = blockIdx.x; w < nwg; w += gridDim.x) {
;     int brow, bcol; TILE_RC(w, brow, bcol);
;     f32x4 acc[2][2][4][2];
; #pragma unroll
;     for (int a = 0; a < 2; ++a)
; #pragma unroll
;       for (int b = 0; b < 2; ++b)
; #pragma unroll
;         for (int m = 0; m < 4; ++m)
; #pragma unroll
;           for (int n = 0; n < 2; ++n) acc[a][b][m][n] = (f32x4){0.f, 0.f, 0.f, 0.f};
;     bf16x8 At[4][2], B0[2][2], B1[2][2];
;     if (wr == 1) BAR;
;     if (w == (int)blockIdx.x) { WAIT_V(0); } else { WAIT_V(24); }
;     BAR;
;     BAR;
;     for (int t = 0; t < nt - 2; t += 2) {
;       LDB(B0, 0, 0); SCHED; LDA(At, 0, 0); STAGE_A(SA_OFF(1, 1), 1, t + 1);
;       WAIT_L(8); BAR; WAIT_L(0); MMA(0, 0, At, B0); BAR; SCHED;
.LBB0_508:
	s_lshl_b32 s2, s31, 8
	s_and_b32 s2, s2, 0x700
	s_ashr_i32 s3, s31, 3
	s_add_i32 s3, s2, s3
	s_ashr_i32 s2, s3, 31
	s_lshr_b32 s2, s2, 24
	s_add_i32 s12, s3, s2
	s_ashr_i32 s2, s12, 8
	s_and_b32 s12, s12, 0xffffff00
	s_sub_i32 s34, s3, s12
	s_lshl_b32 s3, s34, 8
	s_lshl_b32 s12, s34, 5
	s_lshl_b32 s13, s34, 17
	s_and_b32 s34, s34, 7
	s_lshl_b32 s35, s2, 23
	s_lshl_b32 s34, s34, 20
	v_mov_b32_e32 v0, 0
	s_and_b32 s13, s13, 0xfff00000
	s_or_b32 s34, s35, s34
	s_mov_b32 s35, -2
	s_mov_b32 s36, 0
	v_mov_b32_e32 v1, v0
	v_mov_b32_e32 v2, v0
	v_mov_b32_e32 v3, v0
	v_mov_b32_e32 v4, v0
	v_mov_b32_e32 v5, v0
	v_mov_b32_e32 v6, v0
	v_mov_b32_e32 v7, v0
	v_mov_b32_e32 v8, v0
	v_mov_b32_e32 v9, v0
	v_mov_b32_e32 v10, v0
	v_mov_b32_e32 v11, v0
	v_mov_b32_e32 v12, v0
	v_mov_b32_e32 v13, v0
	v_mov_b32_e32 v14, v0
	v_mov_b32_e32 v15, v0
	v_mov_b32_e32 v16, v0
	v_mov_b32_e32 v17, v0
	v_mov_b32_e32 v18, v0
	v_mov_b32_e32 v19, v0
	v_mov_b32_e32 v20, v0
	v_mov_b32_e32 v21, v0
	v_mov_b32_e32 v22, v0
	v_mov_b32_e32 v23, v0
	v_mov_b32_e32 v24, v0
	v_mov_b32_e32 v25, v0
	v_mov_b32_e32 v26, v0
	v_mov_b32_e32 v27, v0
	v_mov_b32_e32 v28, v0
	v_mov_b32_e32 v29, v0
	v_mov_b32_e32 v30, v0
	v_mov_b32_e32 v31, v0
	v_mov_b32_e32 v32, v0
	v_mov_b32_e32 v33, v0
	v_mov_b32_e32 v34, v0
	v_mov_b32_e32 v35, v0
	v_mov_b32_e32 v36, v0
	v_mov_b32_e32 v37, v0
	v_mov_b32_e32 v38, v0
	v_mov_b32_e32 v39, v0
	v_mov_b32_e32 v40, v0
	v_mov_b32_e32 v41, v0
	v_mov_b32_e32 v42, v0
	v_mov_b32_e32 v43, v0
	v_mov_b32_e32 v44, v0
	v_mov_b32_e32 v45, v0
	v_mov_b32_e32 v46, v0
	v_mov_b32_e32 v47, v0
	v_mov_b32_e32 v48, v0
	v_mov_b32_e32 v49, v0
	v_mov_b32_e32 v50, v0
	v_mov_b32_e32 v51, v0
	v_mov_b32_e32 v52, v0
	v_mov_b32_e32 v53, v0
	v_mov_b32_e32 v54, v0
	v_mov_b32_e32 v55, v0
	v_mov_b32_e32 v56, v0
	v_mov_b32_e32 v57, v0
	v_mov_b32_e32 v58, v0
	v_mov_b32_e32 v59, v0
	v_mov_b32_e32 v60, v0
	v_mov_b32_e32 v61, v0
	v_mov_b32_e32 v62, v0
	v_mov_b32_e32 v63, v0
	v_mov_b32_e32 v64, v0
	v_mov_b32_e32 v65, v0
	v_mov_b32_e32 v66, v0
	v_mov_b32_e32 v67, v0
	v_mov_b32_e32 v68, v0
	v_mov_b32_e32 v69, v0
	v_mov_b32_e32 v70, v0
	v_mov_b32_e32 v71, v0
	v_mov_b32_e32 v72, v0
	v_mov_b32_e32 v73, v0
	v_mov_b32_e32 v74, v0
	v_mov_b32_e32 v75, v0
	v_mov_b32_e32 v76, v0
	v_mov_b32_e32 v77, v0
	v_mov_b32_e32 v78, v0
	v_mov_b32_e32 v79, v0
	v_mov_b32_e32 v80, v0
	v_mov_b32_e32 v81, v0
	v_mov_b32_e32 v82, v0
	v_mov_b32_e32 v83, v0
	v_mov_b32_e32 v84, v0
	v_mov_b32_e32 v85, v0
	v_mov_b32_e32 v86, v0
	v_mov_b32_e32 v87, v0
	v_mov_b32_e32 v88, v0
	v_mov_b32_e32 v89, v0
	v_mov_b32_e32 v90, v0
	v_mov_b32_e32 v91, v0
	v_mov_b32_e32 v92, v0
	v_mov_b32_e32 v93, v0
	v_mov_b32_e32 v94, v0
	v_mov_b32_e32 v95, v0
	v_mov_b32_e32 v96, v0
	v_mov_b32_e32 v97, v0
	v_mov_b32_e32 v98, v0
	v_mov_b32_e32 v99, v0
	v_mov_b32_e32 v100, v0
	v_mov_b32_e32 v101, v0
	v_mov_b32_e32 v102, v0
	v_mov_b32_e32 v103, v0
	v_mov_b32_e32 v104, v0
	v_mov_b32_e32 v105, v0
	v_mov_b32_e32 v106, v0
	v_mov_b32_e32 v107, v0
	v_mov_b32_e32 v108, v0
	v_mov_b32_e32 v109, v0
	v_mov_b32_e32 v110, v0
	v_mov_b32_e32 v111, v0
	v_mov_b32_e32 v112, v0
	v_mov_b32_e32 v113, v0
	v_mov_b32_e32 v114, v0
	v_mov_b32_e32 v115, v0
	v_mov_b32_e32 v116, v0
	v_mov_b32_e32 v117, v0
	v_mov_b32_e32 v118, v0
	v_mov_b32_e32 v119, v0
	v_mov_b32_e32 v120, v0
	v_mov_b32_e32 v121, v0
	v_mov_b32_e32 v122, v0
	v_mov_b32_e32 v123, v0
	v_mov_b32_e32 v124, v0
	v_mov_b32_e32 v125, v0
	v_mov_b32_e32 v126, v0
	v_mov_b32_e32 v127, v0
	s_barrier
	s_barrier
	ds_read_b128 v[132:135], v148
	ds_read_b128 v[156:159], v148 offset:1024
	ds_read_b128 v[160:163], v148 offset:2048
	ds_read_b128 v[164:167], v148 offset:3072
	ds_read_b128 v[168:171], v149
	ds_read_b128 v[172:175], v149 offset:1024
	ds_read_b128 v[176:179], v150
	ds_read_b128 v[180:183], v150 offset:1024
	ds_read_b128 v[184:187], v151
	ds_read_b128 v[188:191], v151 offset:1024
	ds_read_b128 v[192:195], v152
	ds_read_b128 v[196:199], v152 offset:1024
.LBB0_509:
	ds_read_b128 v[218:221], v149 offset:16384
	ds_read_b128 v[222:225], v149 offset:17408
	ds_read_b128 v[226:229], v150 offset:16384
	ds_read_b128 v[230:233], v150 offset:17408
	ds_read_b128 v[238:241], v151 offset:16384
	ds_read_b128 v[242:245], v151 offset:17408
	s_add_i32 s37, s34, s36
	s_or_b32 s38, s37, 0x80080
	s_mov_b32 m0, s29
	s_nop 0
	buffer_load_dwordx4 v136, s[48:51], s38 offen lds
	s_or_b32 s38, s37, 0xc0080
	s_mov_b32 m0, s30
	s_nop 0
	buffer_load_dwordx4 v136, s[48:51], s38 offen lds
	s_barrier
	s_waitcnt lgkmcnt(6)
	s_setprio 1
	v_mfma_f32_16x16x32_bf16 v[124:127], v[168:171], v[132:135], v[124:127]
	v_mfma_f32_16x16x32_bf16 v[120:123], v[168:171], v[160:163], v[120:123]
	v_mfma_f32_16x16x32_bf16 v[116:119], v[176:179], v[132:135], v[116:119]
	v_mfma_f32_16x16x32_bf16 v[112:115], v[176:179], v[160:163], v[112:115]
	v_mfma_f32_16x16x32_bf16 v[108:111], v[184:187], v[132:135], v[108:111]
	v_mfma_f32_16x16x32_bf16 v[104:107], v[184:187], v[160:163], v[104:107]
	v_mfma_f32_16x16x32_bf16 v[100:103], v[192:195], v[132:135], v[100:103]
	v_mfma_f32_16x16x32_bf16 v[96:99], v[192:195], v[160:163], v[96:99]
	v_mfma_f32_16x16x32_bf16 v[124:127], v[172:175], v[156:159], v[124:127]
	v_mfma_f32_16x16x32_bf16 v[120:123], v[172:175], v[164:167], v[120:123]
	v_mfma_f32_16x16x32_bf16 v[116:119], v[180:183], v[156:159], v[116:119]
	v_mfma_f32_16x16x32_bf16 v[112:115], v[180:183], v[164:167], v[112:115]
	v_mfma_f32_16x16x32_bf16 v[108:111], v[188:191], v[156:159], v[108:111]
	v_mfma_f32_16x16x32_bf16 v[104:107], v[188:191], v[164:167], v[104:107]
	v_mfma_f32_16x16x32_bf16 v[100:103], v[196:199], v[156:159], v[100:103]
	v_mfma_f32_16x16x32_bf16 v[96:99], v[196:199], v[164:167], v[96:99]
	s_setprio 0
	s_barrier
; #define STAGE_A(POFF, h, kt) STAGE_AX(POFF, h, kt, brow)
; #define STAGE_B(POFF, h, kt) STAGE_BX(POFF, h, kt, bcol)
; #define LDA(dst, b, h) _Pragma("unroll") for (int m = 0; m < 4; ++m) _Pragma("unroll") for (int k = 0; k < 2; ++k) \
;     dst[m][k] = *reinterpret_cast<const bf16x8*>((char*)SA(b, h) + lds_byte(wr * 64 + m * 16 + fr, k * 32 + fq * 8))
; #define LDB(dst, b, h) _Pragma("unroll") for (int n = 0; n < 2; ++n) _Pragma("unroll") for (int k = 0; k < 2; ++k) \
;     dst[n][k] = *reinterpret_cast<const bf16x8*>((char*)SB(b, h) + lds_byte(wc * 32 + n * 16 + fr, k * 32 + fq * 8))
; #define MMA(ai, bj, At_, Bt_) do { __builtin_amdgcn_s_setprio(1); \
;     _Pragma("unroll") for (int k = 0; k < 2; ++k) _Pragma("unroll") for (int m = 0; m < 4; ++m) _Pragma("unroll") for (int n = 0; n < 2; ++n) \
;       acc[ai][bj][m][n] = __builtin_amdgcn_mfma_f32_16x16x32_bf16(At_[m][k], Bt_[n][k], acc[ai][bj][m][n], 0, 0, 0); \
;     __builtin_amdgcn_s_setprio(0); } while (0)
; #define WAIT_V(n) asm volatile("s_waitcnt vmcnt(" #n ")" ::: "memory")
; #define BAR __builtin_amdgcn_s_barrier()
; #define SCHED __builtin_amdgcn_sched_barrier(0)
; template <int EPI, int N, int K>
; __device__ __forceinline__ void gemm_phase(const bf16_t* __restrict__ A, const bf16_t* __restrict__ Bt, const EpiArgs ea) {
;     ...
;       LDB(B1, 0, 1); STAGE_B(SB_OFF(0, 0), 0, t + 2);
;       BAR; WAIT_L(0); MMA(0, 1, At, B1); BAR;
;       LDA(At, 0, 1); STAGE_A(SA_OFF(0, 0), 0, t + 2);
;       BAR; WAIT_L(0); MMA(1, 0, At, B0); BAR; SCHED;
;       STAGE_B(SB_OFF(0, 1), 1, t + 2);
;       WAIT_V(6); BAR; MMA(1, 1, At, B1); BAR;
;       LDB(B0, 1, 0); SCHED; LDA(At, 1, 0); STAGE_A(SA_OFF(0, 1), 1, t + 2);
;       WAIT_L(8); BAR; WAIT_L(0); MMA(0, 0, At, B0); BAR; SCHED;
	ds_read_b128 v[200:203], v153
	ds_read_b128 v[204:207], v153 offset:1024
	ds_read_b128 v[208:211], v153 offset:2048
	ds_read_b128 v[212:215], v153 offset:3072
	ds_read_b128 v[246:249], v152 offset:16384
	ds_read_b128 v[250:253], v152 offset:17408
	s_add_i32 s38, s13, s36
	s_add_i32 s39, s38, 0x100
	s_mov_b32 m0, s15
	s_nop 0
	buffer_load_dwordx4 v137, s[80:83], s39 offen lds
	s_add_i32 s39, s38, 0x80100
	s_mov_b32 m0, s16
	s_nop 0
	buffer_load_dwordx4 v137, s[80:83], s39 offen lds
	s_waitcnt vmcnt(6)
	s_barrier
	s_waitcnt lgkmcnt(2)
	s_setprio 1
	v_mfma_f32_16x16x32_bf16 v[92:95], v[168:171], v[200:203], v[92:95]
	v_mfma_f32_16x16x32_bf16 v[88:91], v[168:171], v[208:211], v[88:91]
	v_mfma_f32_16x16x32_bf16 v[84:87], v[176:179], v[200:203], v[84:87]
	v_mfma_f32_16x16x32_bf16 v[80:83], v[176:179], v[208:211], v[80:83]
	v_mfma_f32_16x16x32_bf16 v[76:79], v[184:187], v[200:203], v[76:79]
	v_mfma_f32_16x16x32_bf16 v[72:75], v[184:187], v[208:211], v[72:75]
	v_mfma_f32_16x16x32_bf16 v[68:71], v[192:195], v[200:203], v[68:71]
	v_mfma_f32_16x16x32_bf16 v[64:67], v[192:195], v[208:211], v[64:67]
	v_mfma_f32_16x16x32_bf16 v[92:95], v[172:175], v[204:207], v[92:95]
	v_mfma_f32_16x16x32_bf16 v[88:91], v[172:175], v[212:215], v[88:91]
	v_mfma_f32_16x16x32_bf16 v[84:87], v[180:183], v[204:207], v[84:87]
	v_mfma_f32_16x16x32_bf16 v[80:83], v[180:183], v[212:215], v[80:83]
	v_mfma_f32_16x16x32_bf16 v[76:79], v[188:191], v[204:207], v[76:79]
	v_mfma_f32_16x16x32_bf16 v[72:75], v[188:191], v[212:215], v[72:75]
	v_mfma_f32_16x16x32_bf16 v[68:71], v[196:199], v[204:207], v[68:71]
	v_mfma_f32_16x16x32_bf16 v[64:67], v[196:199], v[212:215], v[64:67]
	s_setprio 0
	s_barrier
	ds_read_b128 v[168:171], v149 offset:32768
	ds_read_b128 v[172:175], v149 offset:33792
	ds_read_b128 v[176:179], v150 offset:32768
	ds_read_b128 v[180:183], v150 offset:33792
	ds_read_b128 v[184:187], v151 offset:32768
	ds_read_b128 v[188:191], v151 offset:33792
	s_add_i32 s39, s37, 0x100
	s_mov_b32 m0, s14
	s_nop 0
	buffer_load_dwordx4 v136, s[48:51], s39 offen lds
	s_add_i32 s40, s37, 0x40100
	s_mov_b32 m0, s17
	s_nop 0
	buffer_load_dwordx4 v136, s[48:51], s40 offen lds
	s_waitcnt vmcnt(10)
	s_barrier
	s_waitcnt lgkmcnt(6)
	s_setprio 1
	v_mfma_f32_16x16x32_bf16 v[60:63], v[218:221], v[132:135], v[60:63]
	v_mfma_f32_16x16x32_bf16 v[56:59], v[218:221], v[160:163], v[56:59]
	v_mfma_f32_16x16x32_bf16 v[52:55], v[226:229], v[132:135], v[52:55]
	v_mfma_f32_16x16x32_bf16 v[48:51], v[226:229], v[160:163], v[48:51]
	v_mfma_f32_16x16x32_bf16 v[44:47], v[238:241], v[132:135], v[44:47]
	v_mfma_f32_16x16x32_bf16 v[40:43], v[238:241], v[160:163], v[40:43]
	v_mfma_f32_16x16x32_bf16 v[36:39], v[246:249], v[132:135], v[36:39]
	v_mfma_f32_16x16x32_bf16 v[32:35], v[246:249], v[160:163], v[32:35]
	v_mfma_f32_16x16x32_bf16 v[60:63], v[222:225], v[156:159], v[60:63]
	v_mfma_f32_16x16x32_bf16 v[56:59], v[222:225], v[164:167], v[56:59]
	v_mfma_f32_16x16x32_bf16 v[52:55], v[230:233], v[156:159], v[52:55]
	v_mfma_f32_16x16x32_bf16 v[48:51], v[230:233], v[164:167], v[48:51]
	v_mfma_f32_16x16x32_bf16 v[44:47], v[242:245], v[156:159], v[44:47]
	v_mfma_f32_16x16x32_bf16 v[40:43], v[242:245], v[164:167], v[40:43]
	v_mfma_f32_16x16x32_bf16 v[36:39], v[250:253], v[156:159], v[36:39]
	v_mfma_f32_16x16x32_bf16 v[32:35], v[250:253], v[164:167], v[32:35]
	s_setprio 0
	s_barrier
	ds_read_b128 v[132:135], v154
	ds_read_b128 v[156:159], v154 offset:1024
	ds_read_b128 v[160:163], v154 offset:2048
	ds_read_b128 v[164:167], v154 offset:3072
	ds_read_b128 v[192:195], v152 offset:32768
	ds_read_b128 v[196:199], v152 offset:33792
	s_add_i32 s40, s38, 0x2100
	s_mov_b32 m0, s18
	s_nop 0
	buffer_load_dwordx4 v137, s[80:83], s40 offen lds
	s_add_i32 s40, s38, 0x82100
	s_mov_b32 m0, s19
	s_nop 0
	buffer_load_dwordx4 v137, s[80:83], s40 offen lds
	s_waitcnt vmcnt(6)
	s_barrier
	s_setprio 1
	v_mfma_f32_16x16x32_bf16 v[28:31], v[218:221], v[200:203], v[28:31]
	v_mfma_f32_16x16x32_bf16 v[24:27], v[218:221], v[208:211], v[24:27]
	v_mfma_f32_16x16x32_bf16 v[20:23], v[226:229], v[200:203], v[20:23]
	v_mfma_f32_16x16x32_bf16 v[16:19], v[226:229], v[208:211], v[16:19]
	v_mfma_f32_16x16x32_bf16 v[12:15], v[238:241], v[200:203], v[12:15]
	v_mfma_f32_16x16x32_bf16 v[8:11], v[238:241], v[208:211], v[8:11]
	v_mfma_f32_16x16x32_bf16 v[4:7], v[246:249], v[200:203], v[4:7]
	v_mfma_f32_16x16x32_bf16 v[0:3], v[246:249], v[208:211], v[0:3]
	v_mfma_f32_16x16x32_bf16 v[28:31], v[222:225], v[204:207], v[28:31]
	v_mfma_f32_16x16x32_bf16 v[24:27], v[222:225], v[212:215], v[24:27]
	v_mfma_f32_16x16x32_bf16 v[20:23], v[230:233], v[204:207], v[20:23]
	v_mfma_f32_16x16x32_bf16 v[16:19], v[230:233], v[212:215], v[16:19]
	v_mfma_f32_16x16x32_bf16 v[12:15], v[242:245], v[204:207], v[12:15]
	v_mfma_f32_16x16x32_bf16 v[8:11], v[242:245], v[212:215], v[8:11]
	v_mfma_f32_16x16x32_bf16 v[4:7], v[250:253], v[204:207], v[4:7]
	v_mfma_f32_16x16x32_bf16 v[0:3], v[250:253], v[212:215], v[0:3]
	s_setprio 0
	s_barrier
	ds_read_b128 v[218:221], v149 offset:49152
	ds_read_b128 v[222:225], v149 offset:50176
	ds_read_b128 v[226:229], v150 offset:49152
	ds_read_b128 v[230:233], v150 offset:50176
	ds_read_b128 v[238:241], v151 offset:49152
	ds_read_b128 v[242:245], v151 offset:50176
	s_or_b32 s40, s39, 0x80000
	s_mov_b32 m0, s21
	s_nop 0
	buffer_load_dwordx4 v136, s[48:51], s40 offen lds
	s_or_b32 s39, s39, 0xc0000
	s_mov_b32 m0, s22
	s_nop 0
	buffer_load_dwordx4 v136, s[48:51], s39 offen lds
	s_barrier
; #define STAGE_A(POFF, h, kt) STAGE_AX(POFF, h, kt, brow)
; #define STAGE_B(POFF, h, kt) STAGE_BX(POFF, h, kt, bcol)
; #define LDA(dst, b, h) _Pragma("unroll") for (int m = 0; m < 4; ++m) _Pragma("unroll") for (int k = 0; k < 2; ++k) \
;     dst[m][k] = *reinterpret_cast<const bf16x8*>((char*)SA(b, h) + lds_byte(wr * 64 + m * 16 + fr, k * 32 + fq * 8))
; #define LDB(dst, b, h) _Pragma("unroll") for (int n = 0; n < 2; ++n) _Pragma("unroll") for (int k = 0; k < 2; ++k) \
;     dst[n][k] = *reinterpret_cast<const bf16x8*>((char*)SB(b, h) + lds_byte(wc * 32 + n * 16 + fr, k * 32 + fq * 8))
; #define MMA(ai, bj, At_, Bt_) do { __builtin_amdgcn_s_setprio(1); \
;     _Pragma("unroll") for (int k = 0; k < 2; ++k) _Pragma("unroll") for (int m = 0; m < 4; ++m) _Pragma("unroll") for (int n = 0; n < 2; ++n) \
;       acc[ai][bj][m][n] = __builtin_amdgcn_mfma_f32_16x16x32_bf16(At_[m][k], Bt_[n][k], acc[ai][bj][m][n], 0, 0, 0); \
;     __builtin_amdgcn_s_setprio(0); } while (0)
; #define WAIT_V(n) asm volatile("s_waitcnt vmcnt(" #n ")" ::: "memory")
; #define BAR __builtin_amdgcn_s_barrier()
; #define SCHED __builtin_amdgcn_sched_barrier(0)
; template <int EPI, int N, int K>
; __device__ __forceinline__ void gemm_phase(const bf16_t* __restrict__ A, const bf16_t* __restrict__ Bt, const EpiArgs ea) {
;     ...
;       WAIT_L(8); BAR; WAIT_L(0); MMA(0, 0, At, B0); BAR; SCHED;
;       LDB(B1, 1, 1); STAGE_B(SB_OFF(1, 0), 0, t + 3);
;       BAR; WAIT_L(0); MMA(0, 1, At, B1); BAR;
;       LDA(At, 1, 1); STAGE_A(SA_OFF(1, 0), 0, t + 3);
;       BAR; WAIT_L(0); MMA(1, 0, At, B0); BAR; SCHED;
;       STAGE_B(SB_OFF(1, 1), 1, t + 3);
;       WAIT_V(6); BAR; MMA(1, 1, At, B1); BAR;
	s_waitcnt lgkmcnt(6)
	s_setprio 1
	v_mfma_f32_16x16x32_bf16 v[124:127], v[168:171], v[132:135], v[124:127]
	v_mfma_f32_16x16x32_bf16 v[120:123], v[168:171], v[160:163], v[120:123]
	v_mfma_f32_16x16x32_bf16 v[116:119], v[176:179], v[132:135], v[116:119]
	v_mfma_f32_16x16x32_bf16 v[112:115], v[176:179], v[160:163], v[112:115]
	v_mfma_f32_16x16x32_bf16 v[108:111], v[184:187], v[132:135], v[108:111]
	v_mfma_f32_16x16x32_bf16 v[104:107], v[184:187], v[160:163], v[104:107]
	v_mfma_f32_16x16x32_bf16 v[100:103], v[192:195], v[132:135], v[100:103]
	v_mfma_f32_16x16x32_bf16 v[96:99], v[192:195], v[160:163], v[96:99]
	v_mfma_f32_16x16x32_bf16 v[124:127], v[172:175], v[156:159], v[124:127]
	v_mfma_f32_16x16x32_bf16 v[120:123], v[172:175], v[164:167], v[120:123]
	v_mfma_f32_16x16x32_bf16 v[116:119], v[180:183], v[156:159], v[116:119]
	v_mfma_f32_16x16x32_bf16 v[112:115], v[180:183], v[164:167], v[112:115]
	v_mfma_f32_16x16x32_bf16 v[108:111], v[188:191], v[156:159], v[108:111]
	v_mfma_f32_16x16x32_bf16 v[104:107], v[188:191], v[164:167], v[104:107]
	v_mfma_f32_16x16x32_bf16 v[100:103], v[196:199], v[156:159], v[100:103]
	v_mfma_f32_16x16x32_bf16 v[96:99], v[196:199], v[164:167], v[96:99]
	s_setprio 0
	s_barrier
	ds_read_b128 v[200:203], v155
	ds_read_b128 v[204:207], v155 offset:1024
	ds_read_b128 v[208:211], v155 offset:2048
	ds_read_b128 v[212:215], v155 offset:3072
	ds_read_b128 v[246:249], v152 offset:49152
	ds_read_b128 v[250:253], v152 offset:50176
	s_add_i32 s39, s38, 0x180
	s_mov_b32 m0, s23
	s_nop 0
	buffer_load_dwordx4 v137, s[80:83], s39 offen lds
	s_add_i32 s39, s38, 0x80180
	s_mov_b32 m0, s24
	s_nop 0
	buffer_load_dwordx4 v137, s[80:83], s39 offen lds
	s_waitcnt vmcnt(6)
	s_barrier
	s_waitcnt lgkmcnt(2)
	s_setprio 1
	v_mfma_f32_16x16x32_bf16 v[92:95], v[168:171], v[200:203], v[92:95]
	v_mfma_f32_16x16x32_bf16 v[88:91], v[168:171], v[208:211], v[88:91]
	v_mfma_f32_16x16x32_bf16 v[84:87], v[176:179], v[200:203], v[84:87]
	v_mfma_f32_16x16x32_bf16 v[80:83], v[176:179], v[208:211], v[80:83]
	v_mfma_f32_16x16x32_bf16 v[76:79], v[184:187], v[200:203], v[76:79]
	v_mfma_f32_16x16x32_bf16 v[72:75], v[184:187], v[208:211], v[72:75]
	v_mfma_f32_16x16x32_bf16 v[68:71], v[192:195], v[200:203], v[68:71]
	v_mfma_f32_16x16x32_bf16 v[64:67], v[192:195], v[208:211], v[64:67]
	v_mfma_f32_16x16x32_bf16 v[92:95], v[172:175], v[204:207], v[92:95]
	v_mfma_f32_16x16x32_bf16 v[88:91], v[172:175], v[212:215], v[88:91]
	v_mfma_f32_16x16x32_bf16 v[84:87], v[180:183], v[204:207], v[84:87]
	v_mfma_f32_16x16x32_bf16 v[80:83], v[180:183], v[212:215], v[80:83]
	v_mfma_f32_16x16x32_bf16 v[76:79], v[188:191], v[204:207], v[76:79]
	v_mfma_f32_16x16x32_bf16 v[72:75], v[188:191], v[212:215], v[72:75]
	v_mfma_f32_16x16x32_bf16 v[68:71], v[196:199], v[204:207], v[68:71]
	v_mfma_f32_16x16x32_bf16 v[64:67], v[196:199], v[212:215], v[64:67]
	s_setprio 0
	s_barrier
	ds_read_b128 v[168:171], v149
	ds_read_b128 v[172:175], v149 offset:1024
	ds_read_b128 v[176:179], v150
	ds_read_b128 v[180:183], v150 offset:1024
	ds_read_b128 v[184:187], v151
	ds_read_b128 v[188:191], v151 offset:1024
	s_add_i32 s39, s37, 0x180
	s_mov_b32 m0, s25
	s_nop 0
	buffer_load_dwordx4 v136, s[48:51], s39 offen lds
	s_add_i32 s37, s37, 0x40180
	s_mov_b32 m0, s26
	s_nop 0
	buffer_load_dwordx4 v136, s[48:51], s37 offen lds
	s_waitcnt vmcnt(10)
	s_barrier
	s_waitcnt lgkmcnt(6)
	s_setprio 1
	v_mfma_f32_16x16x32_bf16 v[60:63], v[218:221], v[132:135], v[60:63]
	v_mfma_f32_16x16x32_bf16 v[56:59], v[218:221], v[160:163], v[56:59]
	v_mfma_f32_16x16x32_bf16 v[52:55], v[226:229], v[132:135], v[52:55]
	v_mfma_f32_16x16x32_bf16 v[48:51], v[226:229], v[160:163], v[48:51]
	v_mfma_f32_16x16x32_bf16 v[44:47], v[238:241], v[132:135], v[44:47]
	v_mfma_f32_16x16x32_bf16 v[40:43], v[238:241], v[160:163], v[40:43]
	v_mfma_f32_16x16x32_bf16 v[36:39], v[246:249], v[132:135], v[36:39]
	v_mfma_f32_16x16x32_bf16 v[32:35], v[246:249], v[160:163], v[32:35]
	v_mfma_f32_16x16x32_bf16 v[60:63], v[222:225], v[156:159], v[60:63]
	v_mfma_f32_16x16x32_bf16 v[56:59], v[222:225], v[164:167], v[56:59]
	v_mfma_f32_16x16x32_bf16 v[52:55], v[230:233], v[156:159], v[52:55]
	v_mfma_f32_16x16x32_bf16 v[48:51], v[230:233], v[164:167], v[48:51]
	v_mfma_f32_16x16x32_bf16 v[44:47], v[242:245], v[156:159], v[44:47]
	v_mfma_f32_16x16x32_bf16 v[40:43], v[242:245], v[164:167], v[40:43]
	v_mfma_f32_16x16x32_bf16 v[36:39], v[250:253], v[156:159], v[36:39]
	v_mfma_f32_16x16x32_bf16 v[32:35], v[250:253], v[164:167], v[32:35]
	s_setprio 0
	s_barrier
	ds_read_b128 v[132:135], v148
	ds_read_b128 v[156:159], v148 offset:1024
	ds_read_b128 v[160:163], v148 offset:2048
	ds_read_b128 v[164:167], v148 offset:3072
	ds_read_b128 v[192:195], v152
	ds_read_b128 v[196:199], v152 offset:1024
	s_add_i32 s37, s38, 0x2180
	s_mov_b32 m0, s27
	s_nop 0
	buffer_load_dwordx4 v137, s[80:83], s37 offen lds
	s_add_i32 s38, s38, 0x82180
	s_mov_b32 m0, s28
	s_nop 0
	buffer_load_dwordx4 v137, s[80:83], s38 offen lds
	s_waitcnt vmcnt(6)
	s_barrier
	s_setprio 1
	v_mfma_f32_16x16x32_bf16 v[28:31], v[218:221], v[200:203], v[28:31]
	v_mfma_f32_16x16x32_bf16 v[24:27], v[218:221], v[208:211], v[24:27]
	v_mfma_f32_16x16x32_bf16 v[20:23], v[226:229], v[200:203], v[20:23]
	v_mfma_f32_16x16x32_bf16 v[16:19], v[226:229], v[208:211], v[16:19]
	v_mfma_f32_16x16x32_bf16 v[12:15], v[238:241], v[200:203], v[12:15]
	v_mfma_f32_16x16x32_bf16 v[8:11], v[238:241], v[208:211], v[8:11]
	v_mfma_f32_16x16x32_bf16 v[4:7], v[246:249], v[200:203], v[4:7]
	v_mfma_f32_16x16x32_bf16 v[0:3], v[246:249], v[208:211], v[0:3]
	v_mfma_f32_16x16x32_bf16 v[28:31], v[222:225], v[204:207], v[28:31]
	v_mfma_f32_16x16x32_bf16 v[24:27], v[222:225], v[212:215], v[24:27]
	v_mfma_f32_16x16x32_bf16 v[20:23], v[230:233], v[204:207], v[20:23]
	v_mfma_f32_16x16x32_bf16 v[16:19], v[230:233], v[212:215], v[16:19]
	v_mfma_f32_16x16x32_bf16 v[12:15], v[242:245], v[204:207], v[12:15]
	v_mfma_f32_16x16x32_bf16 v[8:11], v[242:245], v[212:215], v[8:11]
	v_mfma_f32_16x16x32_bf16 v[4:7], v[250:253], v[204:207], v[4:7]
	v_mfma_f32_16x16x32_bf16 v[0:3], v[250:253], v[212:215], v[0:3]
	s_setprio 0
	s_add_i32 s35, s35, 2
	s_addk_i32 s36, 0x100
	s_cmp_lt_u32 s35, 28
	s_barrier
; #define STAGE_A(POFF, h, kt) STAGE_AX(POFF, h, kt, brow)
; #define LDA(dst, b, h) _Pragma("unroll") for (int m = 0; m < 4; ++m) _Pragma("unroll") for (int k = 0; k < 2; ++k) \
;     dst[m][k] = *reinterpret_cast<const bf16x8*>((char*)SA(b, h) + lds_byte(wr * 64 + m * 16 + fr, k * 32 + fq * 8))
; #define LDB(dst, b, h) _Pragma("unroll") for (int n = 0; n < 2; ++n) _Pragma("unroll") for (int k = 0; k < 2; ++k) \
;     dst[n][k] = *reinterpret_cast<const bf16x8*>((char*)SB(b, h) + lds_byte(wc * 32 + n * 16 + fr, k * 32 + fq * 8))
; #define MMA(ai, bj, At_, Bt_) do { __builtin_amdgcn_s_setprio(1); \
;     _Pragma("unroll") for (int k = 0; k < 2; ++k) _Pragma("unroll") for (int m = 0; m < 4; ++m) _Pragma("unroll") for (int n = 0; n < 2; ++n) \
;       acc[ai][bj][m][n] = __builtin_amdgcn_mfma_f32_16x16x32_bf16(At_[m][k], Bt_[n][k], acc[ai][bj][m][n], 0, 0, 0); \
;     __builtin_amdgcn_s_setprio(0); } while (0)
; #define WAIT_V(n) asm volatile("s_waitcnt vmcnt(" #n ")" ::: "memory")
; #define BAR __builtin_amdgcn_s_barrier()
; template <int EPI, int N, int K>
; __device__ __forceinline__ void gemm_phase(const bf16_t* __restrict__ A, const bf16_t* __restrict__ Bt, const EpiArgs ea) {
;     ...
;       WAIT_V(6); BAR; MMA(1, 1, At, B1); BAR;
;     }
;     { LDB(B0, 0, 0); LDA(At, 0, 0); STAGE_A(SA_OFF(1, 1), 1, nt - 1);
;       BAR; WAIT_L(0); MMA(0, 0, At, B0); BAR;
;       LDB(B1, 0, 1); BAR; WAIT_L(0); MMA(0, 1, At, B1); BAR;
;       LDA(At, 0, 1); WAIT_V(4); BAR; WAIT_L(0); MMA(1, 0, At, B0); MMA(1, 1, At, B1); BAR; }
	s_cbranch_scc1 .LBB0_509
	s_and_b32 s3, s3, 0x700
	s_lshl_b32 s2, s2, 11
	s_or_b32 s34, s3, s2
	s_lshl_b32 s2, s34, 12
	s_or_b32 s3, s2, 0x80f80
	s_mov_b32 m0, s29
	s_nop 0
	buffer_load_dwordx4 v136, s[48:51], s3 offen lds
	s_or_b32 s2, s2, 0xc0f80
	s_mov_b32 m0, s30
	s_nop 0
	buffer_load_dwordx4 v136, s[48:51], s2 offen lds
	s_barrier
	s_waitcnt lgkmcnt(0)
	s_setprio 1
	v_mfma_f32_16x16x32_bf16 v[124:127], v[168:171], v[132:135], v[124:127]
	v_mfma_f32_16x16x32_bf16 v[120:123], v[168:171], v[160:163], v[120:123]
	v_mfma_f32_16x16x32_bf16 v[116:119], v[176:179], v[132:135], v[116:119]
	v_mfma_f32_16x16x32_bf16 v[112:115], v[176:179], v[160:163], v[112:115]
	v_mfma_f32_16x16x32_bf16 v[108:111], v[184:187], v[132:135], v[108:111]
	v_mfma_f32_16x16x32_bf16 v[104:107], v[184:187], v[160:163], v[104:107]
	v_mfma_f32_16x16x32_bf16 v[100:103], v[192:195], v[132:135], v[100:103]
	v_mfma_f32_16x16x32_bf16 v[96:99], v[192:195], v[160:163], v[96:99]
	v_mfma_f32_16x16x32_bf16 v[124:127], v[172:175], v[156:159], v[124:127]
	v_mfma_f32_16x16x32_bf16 v[120:123], v[172:175], v[164:167], v[120:123]
	v_mfma_f32_16x16x32_bf16 v[116:119], v[180:183], v[156:159], v[116:119]
	v_mfma_f32_16x16x32_bf16 v[112:115], v[180:183], v[164:167], v[112:115]
	v_mfma_f32_16x16x32_bf16 v[108:111], v[188:191], v[156:159], v[108:111]
	v_mfma_f32_16x16x32_bf16 v[104:107], v[188:191], v[164:167], v[104:107]
	v_mfma_f32_16x16x32_bf16 v[100:103], v[196:199], v[156:159], v[100:103]
	v_mfma_f32_16x16x32_bf16 v[96:99], v[196:199], v[164:167], v[96:99]
	s_setprio 0
	s_barrier
	ds_read_b128 v[200:203], v153
	ds_read_b128 v[204:207], v153 offset:1024
	ds_read_b128 v[208:211], v153 offset:2048
	ds_read_b128 v[212:215], v153 offset:3072
	s_barrier
	s_waitcnt lgkmcnt(0)
	s_setprio 1
	v_mfma_f32_16x16x32_bf16 v[92:95], v[168:171], v[200:203], v[92:95]
	v_mfma_f32_16x16x32_bf16 v[88:91], v[168:171], v[208:211], v[88:91]
	v_mfma_f32_16x16x32_bf16 v[76:79], v[184:187], v[200:203], v[76:79]
	v_mfma_f32_16x16x32_bf16 v[72:75], v[184:187], v[208:211], v[72:75]
	v_mfma_f32_16x16x32_bf16 v[84:87], v[176:179], v[200:203], v[84:87]
	v_mfma_f32_16x16x32_bf16 v[80:83], v[176:179], v[208:211], v[80:83]
	v_mfma_f32_16x16x32_bf16 v[68:71], v[192:195], v[200:203], v[68:71]
	v_mfma_f32_16x16x32_bf16 v[64:67], v[192:195], v[208:211], v[64:67]
	v_mfma_f32_16x16x32_bf16 v[92:95], v[172:175], v[204:207], v[92:95]
	v_mfma_f32_16x16x32_bf16 v[88:91], v[172:175], v[212:215], v[88:91]
	v_mfma_f32_16x16x32_bf16 v[76:79], v[188:191], v[204:207], v[76:79]
	v_mfma_f32_16x16x32_bf16 v[72:75], v[188:191], v[212:215], v[72:75]
	v_mfma_f32_16x16x32_bf16 v[168:171], v[180:183], v[204:207], v[84:87]
	v_mfma_f32_16x16x32_bf16 v[172:175], v[180:183], v[212:215], v[80:83]
	v_mfma_f32_16x16x32_bf16 v[176:179], v[196:199], v[204:207], v[68:71]
	v_mfma_f32_16x16x32_bf16 v[180:183], v[196:199], v[212:215], v[64:67]
	s_setprio 0
	s_barrier
	s_nop 0
	ds_read_b128 v[64:67], v149 offset:16384
	ds_read_b128 v[68:71], v149 offset:17408
	ds_read_b128 v[80:83], v150 offset:16384
	ds_read_b128 v[84:87], v150 offset:17408
	ds_read_b128 v[184:187], v151 offset:16384
	ds_read_b128 v[188:191], v151 offset:17408
	ds_read_b128 v[192:195], v152 offset:16384
	ds_read_b128 v[196:199], v152 offset:17408
	s_waitcnt vmcnt(4)
	s_barrier
	s_waitcnt lgkmcnt(0)
	s_setprio 1
	v_mfma_f32_16x16x32_bf16 v[60:63], v[64:67], v[132:135], v[60:63]
	v_mfma_f32_16x16x32_bf16 v[56:59], v[64:67], v[160:163], v[56:59]
	v_mfma_f32_16x16x32_bf16 v[52:55], v[80:83], v[132:135], v[52:55]
	v_mfma_f32_16x16x32_bf16 v[48:51], v[80:83], v[160:163], v[48:51]
	v_mfma_f32_16x16x32_bf16 v[44:47], v[184:187], v[132:135], v[44:47]
	v_mfma_f32_16x16x32_bf16 v[40:43], v[184:187], v[160:163], v[40:43]
	v_mfma_f32_16x16x32_bf16 v[36:39], v[192:195], v[132:135], v[36:39]
	v_mfma_f32_16x16x32_bf16 v[32:35], v[192:195], v[160:163], v[32:35]
	v_mfma_f32_16x16x32_bf16 v[60:63], v[68:71], v[156:159], v[60:63]
	v_mfma_f32_16x16x32_bf16 v[56:59], v[68:71], v[164:167], v[56:59]
	v_mfma_f32_16x16x32_bf16 v[52:55], v[84:87], v[156:159], v[52:55]
	v_mfma_f32_16x16x32_bf16 v[48:51], v[84:87], v[164:167], v[48:51]
	v_mfma_f32_16x16x32_bf16 v[44:47], v[188:191], v[156:159], v[44:47]
	v_mfma_f32_16x16x32_bf16 v[40:43], v[188:191], v[164:167], v[40:43]
	v_mfma_f32_16x16x32_bf16 v[36:39], v[196:199], v[156:159], v[36:39]
	v_mfma_f32_16x16x32_bf16 v[32:35], v[196:199], v[164:167], v[32:35]
	s_setprio 0
	s_setprio 1
	v_mfma_f32_16x16x32_bf16 v[28:31], v[64:67], v[200:203], v[28:31]
	v_mfma_f32_16x16x32_bf16 v[24:27], v[64:67], v[208:211], v[24:27]
	v_mfma_f32_16x16x32_bf16 v[12:15], v[184:187], v[200:203], v[12:15]
	v_mfma_f32_16x16x32_bf16 v[8:11], v[184:187], v[208:211], v[8:11]
	v_mfma_f32_16x16x32_bf16 v[20:23], v[80:83], v[200:203], v[20:23]
	v_mfma_f32_16x16x32_bf16 v[16:19], v[80:83], v[208:211], v[16:19]
	v_mfma_f32_16x16x32_bf16 v[4:7], v[192:195], v[200:203], v[4:7]
	v_mfma_f32_16x16x32_bf16 v[0:3], v[192:195], v[208:211], v[0:3]
	v_mfma_f32_16x16x32_bf16 v[28:31], v[68:71], v[204:207], v[28:31]
	v_mfma_f32_16x16x32_bf16 v[24:27], v[68:71], v[212:215], v[24:27]
	v_mfma_f32_16x16x32_bf16 v[12:15], v[188:191], v[204:207], v[12:15]
	v_mfma_f32_16x16x32_bf16 v[8:11], v[188:191], v[212:215], v[8:11]
	v_mfma_f32_16x16x32_bf16 v[132:135], v[84:87], v[204:207], v[20:23]
	v_mfma_f32_16x16x32_bf16 v[156:159], v[84:87], v[212:215], v[16:19]
	v_mfma_f32_16x16x32_bf16 v[160:163], v[196:199], v[204:207], v[4:7]
	v_mfma_f32_16x16x32_bf16 v[164:167], v[196:199], v[212:215], v[0:3]
	s_setprio 0
	s_barrier
; #define LDA(dst, b, h) _Pragma("unroll") for (int m = 0; m < 4; ++m) _Pragma("unroll") for (int k = 0; k < 2; ++k) \
;     dst[m][k] = *reinterpret_cast<const bf16x8*>((char*)SA(b, h) + lds_byte(wr * 64 + m * 16 + fr, k * 32 + fq * 8))
; #define LDB(dst, b, h) _Pragma("unroll") for (int n = 0; n < 2; ++n) _Pragma("unroll") for (int k = 0; k < 2; ++k) \
;     dst[n][k] = *reinterpret_cast<const bf16x8*>((char*)SB(b, h) + lds_byte(wc * 32 + n * 16 + fr, k * 32 + fq * 8))
; #define MMA(ai, bj, At_, Bt_) do { __builtin_amdgcn_s_setprio(1); \
;     _Pragma("unroll") for (int k = 0; k < 2; ++k) _Pragma("unroll") for (int m = 0; m < 4; ++m) _Pragma("unroll") for (int n = 0; n < 2; ++n) \
;       acc[ai][bj][m][n] = __builtin_amdgcn_mfma_f32_16x16x32_bf16(At_[m][k], Bt_[n][k], acc[ai][bj][m][n], 0, 0, 0); \
;     __builtin_amdgcn_s_setprio(0); } while (0)
; #define WAIT_V(n) asm volatile("s_waitcnt vmcnt(" #n ")" ::: "memory")
; #define BAR __builtin_amdgcn_s_barrier()
; template <int EPI, int N, int K>
; __device__ __forceinline__ void gemm_phase(const bf16_t* __restrict__ A, const bf16_t* __restrict__ Bt, const EpiArgs ea) {
;     ...
;     { LDB(B0, 1, 0); LDA(At, 1, 0); WAIT_V(2); BAR; WAIT_L(0); MMA(0, 0, At, B0); BAR;
;       LDB(B1, 1, 1); WAIT_V(0); BAR; WAIT_L(0); MMA(0, 1, At, B1); BAR;
;       LDA(At, 1, 1); BAR; WAIT_L(0); MMA(1, 0, At, B0); MMA(1, 1, At, B1); BAR; }
;     if (wr == 0) BAR;
	s_nop 0
	ds_read_b128 v[0:3], v154
	ds_read_b128 v[4:7], v154 offset:1024
	ds_read_b128 v[16:19], v154 offset:2048
	ds_read_b128 v[184:187], v154 offset:3072
	ds_read_b128 v[20:23], v149 offset:32768
	ds_read_b128 v[188:191], v149 offset:33792
	ds_read_b128 v[192:195], v150 offset:32768
	ds_read_b128 v[196:199], v150 offset:33792
	ds_read_b128 v[200:203], v151 offset:32768
	ds_read_b128 v[204:207], v151 offset:33792
	ds_read_b128 v[208:211], v152 offset:32768
	ds_read_b128 v[212:215], v152 offset:33792
	s_waitcnt vmcnt(2)
	s_barrier
	s_waitcnt lgkmcnt(0)
	s_setprio 1
	v_mfma_f32_16x16x32_bf16 v[64:67], v[20:23], v[0:3], v[124:127]
	v_mfma_f32_16x16x32_bf16 v[68:71], v[20:23], v[16:19], v[120:123]
	v_mfma_f32_16x16x32_bf16 v[80:83], v[192:195], v[0:3], v[116:119]
	v_mfma_f32_16x16x32_bf16 v[84:87], v[192:195], v[16:19], v[112:115]
	v_mfma_f32_16x16x32_bf16 v[108:111], v[200:203], v[0:3], v[108:111]
	v_mfma_f32_16x16x32_bf16 v[104:107], v[200:203], v[16:19], v[104:107]
	v_mfma_f32_16x16x32_bf16 v[120:123], v[208:211], v[0:3], v[100:103]
	v_mfma_f32_16x16x32_bf16 v[124:127], v[208:211], v[16:19], v[96:99]
	v_mfma_f32_16x16x32_bf16 v[112:115], v[188:191], v[4:7], v[64:67]
	v_mfma_f32_16x16x32_bf16 v[116:119], v[188:191], v[184:187], v[68:71]
	v_mfma_f32_16x16x32_bf16 v[96:99], v[196:199], v[4:7], v[80:83]
	v_mfma_f32_16x16x32_bf16 v[100:103], v[196:199], v[184:187], v[84:87]
	v_mfma_f32_16x16x32_bf16 v[80:83], v[204:207], v[4:7], v[108:111]
	v_mfma_f32_16x16x32_bf16 v[84:87], v[204:207], v[184:187], v[104:107]
	v_mfma_f32_16x16x32_bf16 v[64:67], v[212:215], v[4:7], v[120:123]
	v_mfma_f32_16x16x32_bf16 v[68:71], v[212:215], v[184:187], v[124:127]
	s_setprio 0
	s_barrier
	ds_read_b128 v[216:219], v155
	ds_read_b128 v[220:223], v155 offset:1024
	ds_read_b128 v[224:227], v155 offset:2048
	ds_read_b128 v[228:231], v155 offset:3072
	s_waitcnt vmcnt(0)
	s_barrier
	s_waitcnt lgkmcnt(0)
	s_setprio 1
	v_mfma_f32_16x16x32_bf16 v[92:95], v[20:23], v[216:219], v[92:95]
	v_mfma_f32_16x16x32_bf16 v[20:23], v[20:23], v[224:227], v[88:91]
	v_mfma_f32_16x16x32_bf16 v[88:91], v[192:195], v[216:219], v[168:171]
	v_mfma_f32_16x16x32_bf16 v[108:111], v[192:195], v[224:227], v[172:175]
	v_mfma_f32_16x16x32_bf16 v[76:79], v[200:203], v[216:219], v[76:79]
	v_mfma_f32_16x16x32_bf16 v[72:75], v[200:203], v[224:227], v[72:75]
	v_mfma_f32_16x16x32_bf16 v[168:171], v[208:211], v[216:219], v[176:179]
	v_mfma_f32_16x16x32_bf16 v[172:175], v[208:211], v[224:227], v[180:183]
	v_mfma_f32_16x16x32_bf16 v[120:123], v[188:191], v[220:223], v[92:95]
	v_mfma_f32_16x16x32_bf16 v[124:127], v[188:191], v[228:231], v[20:23]
	v_mfma_f32_16x16x32_bf16 v[104:107], v[196:199], v[220:223], v[88:91]
	v_mfma_f32_16x16x32_bf16 v[108:111], v[196:199], v[228:231], v[108:111]
	v_mfma_f32_16x16x32_bf16 v[88:91], v[204:207], v[220:223], v[76:79]
	v_mfma_f32_16x16x32_bf16 v[92:95], v[204:207], v[228:231], v[72:75]
	v_mfma_f32_16x16x32_bf16 v[72:75], v[212:215], v[220:223], v[168:171]
	v_mfma_f32_16x16x32_bf16 v[76:79], v[212:215], v[228:231], v[172:175]
	s_setprio 0
	s_barrier
	ds_read_b128 v[168:171], v149 offset:49152
	ds_read_b128 v[172:175], v149 offset:50176
	ds_read_b128 v[176:179], v150 offset:49152
	ds_read_b128 v[180:183], v150 offset:50176
	ds_read_b128 v[188:191], v151 offset:49152
	ds_read_b128 v[192:195], v151 offset:50176
	ds_read_b128 v[196:199], v152 offset:49152
	ds_read_b128 v[200:203], v152 offset:50176
	s_barrier
	s_waitcnt lgkmcnt(0)
	s_setprio 1
	v_mfma_f32_16x16x32_bf16 v[20:23], v[168:171], v[0:3], v[60:63]
	v_mfma_f32_16x16x32_bf16 v[56:59], v[168:171], v[16:19], v[56:59]
	v_mfma_f32_16x16x32_bf16 v[60:63], v[176:179], v[0:3], v[52:55]
	v_mfma_f32_16x16x32_bf16 v[204:207], v[176:179], v[16:19], v[48:51]
	v_mfma_f32_16x16x32_bf16 v[44:47], v[188:191], v[0:3], v[44:47]
	v_mfma_f32_16x16x32_bf16 v[40:43], v[188:191], v[16:19], v[40:43]
	v_mfma_f32_16x16x32_bf16 v[0:3], v[196:199], v[0:3], v[36:39]
	v_mfma_f32_16x16x32_bf16 v[208:211], v[196:199], v[16:19], v[32:35]
	v_mfma_f32_16x16x32_bf16 v[48:51], v[172:175], v[4:7], v[20:23]
	v_mfma_f32_16x16x32_bf16 v[52:55], v[172:175], v[184:187], v[56:59]
	v_mfma_f32_16x16x32_bf16 v[32:35], v[180:183], v[4:7], v[60:63]
	v_mfma_f32_16x16x32_bf16 v[36:39], v[180:183], v[184:187], v[204:207]
	v_mfma_f32_16x16x32_bf16 v[16:19], v[192:195], v[4:7], v[44:47]
	v_mfma_f32_16x16x32_bf16 v[20:23], v[192:195], v[184:187], v[40:43]
	v_mfma_f32_16x16x32_bf16 v[0:3], v[200:203], v[4:7], v[0:3]
	v_mfma_f32_16x16x32_bf16 v[4:7], v[200:203], v[184:187], v[208:211]
	s_setprio 0
	s_setprio 1
	v_mfma_f32_16x16x32_bf16 v[28:31], v[168:171], v[216:219], v[28:31]
	v_mfma_f32_16x16x32_bf16 v[24:27], v[168:171], v[224:227], v[24:27]
	v_mfma_f32_16x16x32_bf16 v[40:43], v[176:179], v[216:219], v[132:135]
	v_mfma_f32_16x16x32_bf16 v[44:47], v[176:179], v[224:227], v[156:159]
	v_mfma_f32_16x16x32_bf16 v[12:15], v[188:191], v[216:219], v[12:15]
	v_mfma_f32_16x16x32_bf16 v[8:11], v[188:191], v[224:227], v[8:11]
	v_mfma_f32_16x16x32_bf16 v[132:135], v[196:199], v[216:219], v[160:163]
	v_mfma_f32_16x16x32_bf16 v[156:159], v[196:199], v[224:227], v[164:167]
	v_mfma_f32_16x16x32_bf16 v[56:59], v[172:175], v[220:223], v[28:31]
	v_mfma_f32_16x16x32_bf16 v[60:63], v[172:175], v[228:231], v[24:27]
	v_mfma_f32_16x16x32_bf16 v[40:43], v[180:183], v[220:223], v[40:43]
	v_mfma_f32_16x16x32_bf16 v[44:47], v[180:183], v[228:231], v[44:47]
	v_mfma_f32_16x16x32_bf16 v[24:27], v[192:195], v[220:223], v[12:15]
	v_mfma_f32_16x16x32_bf16 v[28:31], v[192:195], v[228:231], v[8:11]
	v_mfma_f32_16x16x32_bf16 v[8:11], v[200:203], v[220:223], v[132:135]
	v_mfma_f32_16x16x32_bf16 v[12:15], v[200:203], v[228:231], v[156:159]
	s_setprio 0
	s_barrier
	s_and_saveexec_b64 s[2:3], s[8:9]
	s_cbranch_execz .LBB0_512
	s_barrier

; #define STAGE_A(POFF, h, kt) STAGE_AX(POFF, h, kt, brow)
; #define LDA(dst, b, h) _Pragma("unroll") for (int m = 0; m < 4; ++m) _Pragma("unroll") for (int k = 0; k < 2; ++k) \
;     dst[m][k] = *reinterpret_cast<const bf16x8*>((char*)SA(b, h) + lds_byte(wr * 64 + m * 16 + fr, k * 32 + fq * 8))
; #define LDB(dst, b, h) _Pragma("unroll") for (int n = 0; n < 2; ++n) _Pragma("unroll") for (int k = 0; k < 2; ++k) \
;     dst[n][k] = *reinterpret_cast<const bf16x8*>((char*)SB(b, h) + lds_byte(wc * 32 + n * 16 + fr, k * 32 + fq * 8))
; #define MMA(ai, bj, At_, Bt_) do { __builtin_amdgcn_s_setprio(1); \
;     _Pragma("unroll") for (int k = 0; k < 2; ++k) _Pragma("unroll") for (int m = 0; m < 4; ++m) _Pragma("unroll") for (int n = 0; n < 2; ++n) \
;       acc[ai][bj][m][n] = __builtin_amdgcn_mfma_f32_16x16x32_bf16(At_[m][k], Bt_[n][k], acc[ai][bj][m][n], 0, 0, 0); \
;     __builtin_amdgcn_s_setprio(0); } while (0)
; #define WAIT_V(n) asm volatile("s_waitcnt vmcnt(" #n ")" ::: "memory")
; #define BAR __builtin_amdgcn_s_barrier()
; #define SCHED __builtin_amdgcn_sched_barrier(0)
; #define TILE_RC(w_, brow_, bcol_) do { const int wg_ = ((w_) & 7) * qx + ((w_) >> 3); const int gid_ = wg_ / nig; \
;     brow_ = (gid_ * 8 + ((wg_ % nig) & 7)) * 256; bcol_ = ((wg_ % nig) >> 3) * 256; } while (0)
; template <int EPI, int N, int K>
; __device__ __forceinline__ void gemm_phase(const bf16_t* __restrict__ A, const bf16_t* __restrict__ Bt, const EpiArgs ea) {
;     ...
;   for (int w = blockIdx.x; w < nwg; w += gridDim.x) {
;     int brow, bcol; TILE_RC(w, brow, bcol);
;     f32x4 acc[2][2][4][2];
; #pragma unroll
;     for (int a = 0; a < 2; ++a)
; #pragma unroll
;       for (int b = 0; b < 2; ++b)
; #pragma unroll
;         for (int m = 0; m < 4; ++m)
; #pragma unroll
;           for (int n = 0; n < 2; ++n) acc[a][b][m][n] = (f32x4){0.f, 0.f, 0.f, 0.f};
;     bf16x8 At[4][2], B0[2][2], B1[2][2];
;     if (wr == 1) BAR;
;     if (w == (int)blockIdx.x) { WAIT_V(0); } else { WAIT_V(24); }
;     BAR;
;     BAR;
;     for (int t = 0; t < nt - 2; t += 2) {
;       LDB(B0, 0, 0); SCHED; LDA(At, 0, 0); STAGE_A(SA_OFF(1, 1), 1, t + 1);
;       WAIT_L(8); BAR; WAIT_L(0); MMA(0, 0, At, B0); BAR; SCHED;
.LBB0_567:
	s_lshl_b32 s2, s28, 6
	s_and_b32 s2, s2, 0x1c0
	s_ashr_i32 s3, s28, 3
	s_add_i32 s3, s2, s3
	s_ashr_i32 s2, s3, 31
	s_lshr_b32 s2, s2, 26
	s_add_i32 s10, s3, s2
	s_ashr_i32 s2, s10, 6
	s_andn2_b32 s10, s10, 63
	s_sub_i32 s29, s3, s10
	s_lshl_b32 s3, s29, 8
	s_lshl_b32 s10, s29, 5
	s_lshl_b32 s11, s29, 19
	s_and_b32 s29, s29, 7
	s_lshl_b32 s30, s2, 25
	s_lshl_b32 s29, s29, 22
	v_mov_b32_e32 v0, 0
	s_and_b32 s11, s11, 0xffc00000
	s_or_b32 s29, s30, s29
	s_mov_b32 s30, -2
	s_mov_b32 s31, 0
	v_mov_b32_e32 v1, v0
	v_mov_b32_e32 v2, v0
	v_mov_b32_e32 v3, v0
	v_mov_b32_e32 v4, v0
	v_mov_b32_e32 v5, v0
	v_mov_b32_e32 v6, v0
	v_mov_b32_e32 v7, v0
	v_mov_b32_e32 v8, v0
	v_mov_b32_e32 v9, v0
	v_mov_b32_e32 v10, v0
	v_mov_b32_e32 v11, v0
	v_mov_b32_e32 v12, v0
	v_mov_b32_e32 v13, v0
	v_mov_b32_e32 v14, v0
	v_mov_b32_e32 v15, v0
	v_mov_b32_e32 v16, v0
	v_mov_b32_e32 v17, v0
	v_mov_b32_e32 v18, v0
	v_mov_b32_e32 v19, v0
	v_mov_b32_e32 v20, v0
	v_mov_b32_e32 v21, v0
	v_mov_b32_e32 v22, v0
	v_mov_b32_e32 v23, v0
	v_mov_b32_e32 v24, v0
	v_mov_b32_e32 v25, v0
	v_mov_b32_e32 v26, v0
	v_mov_b32_e32 v27, v0
	v_mov_b32_e32 v28, v0
	v_mov_b32_e32 v29, v0
	v_mov_b32_e32 v30, v0
	v_mov_b32_e32 v31, v0
	v_mov_b32_e32 v32, v0
	v_mov_b32_e32 v33, v0
	v_mov_b32_e32 v34, v0
	v_mov_b32_e32 v35, v0
	v_mov_b32_e32 v36, v0
	v_mov_b32_e32 v37, v0
	v_mov_b32_e32 v38, v0
	v_mov_b32_e32 v39, v0
	v_mov_b32_e32 v40, v0
	v_mov_b32_e32 v41, v0
	v_mov_b32_e32 v42, v0
	v_mov_b32_e32 v43, v0
	v_mov_b32_e32 v44, v0
	v_mov_b32_e32 v45, v0
	v_mov_b32_e32 v46, v0
	v_mov_b32_e32 v47, v0
	v_mov_b32_e32 v48, v0
	v_mov_b32_e32 v49, v0
	v_mov_b32_e32 v50, v0
	v_mov_b32_e32 v51, v0
	v_mov_b32_e32 v52, v0
	v_mov_b32_e32 v53, v0
	v_mov_b32_e32 v54, v0
	v_mov_b32_e32 v55, v0
	v_mov_b32_e32 v56, v0
	v_mov_b32_e32 v57, v0
	v_mov_b32_e32 v58, v0
	v_mov_b32_e32 v59, v0
	v_mov_b32_e32 v60, v0
	v_mov_b32_e32 v61, v0
	v_mov_b32_e32 v62, v0
	v_mov_b32_e32 v63, v0
	v_mov_b32_e32 v64, v0
	v_mov_b32_e32 v65, v0
	v_mov_b32_e32 v66, v0
	v_mov_b32_e32 v67, v0
	v_mov_b32_e32 v68, v0
	v_mov_b32_e32 v69, v0
	v_mov_b32_e32 v70, v0
	v_mov_b32_e32 v71, v0
	v_mov_b32_e32 v72, v0
	v_mov_b32_e32 v73, v0
	v_mov_b32_e32 v74, v0
	v_mov_b32_e32 v75, v0
	v_mov_b32_e32 v76, v0
	v_mov_b32_e32 v77, v0
	v_mov_b32_e32 v78, v0
	v_mov_b32_e32 v79, v0
	v_mov_b32_e32 v80, v0
	v_mov_b32_e32 v81, v0
	v_mov_b32_e32 v82, v0
	v_mov_b32_e32 v83, v0
	v_mov_b32_e32 v84, v0
	v_mov_b32_e32 v85, v0
	v_mov_b32_e32 v86, v0
	v_mov_b32_e32 v87, v0
	v_mov_b32_e32 v88, v0
	v_mov_b32_e32 v89, v0
	v_mov_b32_e32 v90, v0
	v_mov_b32_e32 v91, v0
	v_mov_b32_e32 v92, v0
	v_mov_b32_e32 v93, v0
	v_mov_b32_e32 v94, v0
	v_mov_b32_e32 v95, v0
	v_mov_b32_e32 v96, v0
	v_mov_b32_e32 v97, v0
	v_mov_b32_e32 v98, v0
	v_mov_b32_e32 v99, v0
	v_mov_b32_e32 v100, v0
	v_mov_b32_e32 v101, v0
	v_mov_b32_e32 v102, v0
	v_mov_b32_e32 v103, v0
	v_mov_b32_e32 v104, v0
	v_mov_b32_e32 v105, v0
	v_mov_b32_e32 v106, v0
	v_mov_b32_e32 v107, v0
	v_mov_b32_e32 v108, v0
	v_mov_b32_e32 v109, v0
	v_mov_b32_e32 v110, v0
	v_mov_b32_e32 v111, v0
	v_mov_b32_e32 v112, v0
	v_mov_b32_e32 v113, v0
	v_mov_b32_e32 v114, v0
	v_mov_b32_e32 v115, v0
	v_mov_b32_e32 v116, v0
	v_mov_b32_e32 v117, v0
	v_mov_b32_e32 v118, v0
	v_mov_b32_e32 v119, v0
	v_mov_b32_e32 v120, v0
	v_mov_b32_e32 v121, v0
	v_mov_b32_e32 v122, v0
	v_mov_b32_e32 v123, v0
	v_mov_b32_e32 v124, v0
	v_mov_b32_e32 v125, v0
	v_mov_b32_e32 v126, v0
	v_mov_b32_e32 v127, v0
	s_barrier
	s_barrier
	ds_read_b128 v[132:135], v147
	ds_read_b128 v[156:159], v147 offset:1024
	ds_read_b128 v[160:163], v147 offset:2048
	ds_read_b128 v[164:167], v147 offset:3072
	ds_read_b128 v[168:171], v148
	ds_read_b128 v[172:175], v148 offset:1024
	ds_read_b128 v[176:179], v149
	ds_read_b128 v[180:183], v149 offset:1024
	ds_read_b128 v[184:187], v150
	ds_read_b128 v[188:191], v150 offset:1024
	ds_read_b128 v[192:195], v151
	ds_read_b128 v[196:199], v151 offset:1024
.LBB0_568:
	ds_read_b128 v[218:221], v148 offset:16384
	ds_read_b128 v[222:225], v148 offset:17408
	ds_read_b128 v[226:229], v149 offset:16384
	ds_read_b128 v[230:233], v149 offset:17408
	ds_read_b128 v[238:241], v150 offset:16384
	ds_read_b128 v[242:245], v150 offset:17408
	s_add_i32 s34, s29, s31
	s_or_b32 s35, s34, 0x200080
	s_mov_b32 m0, s26
	s_nop 0
	buffer_load_dwordx4 v131, s[64:67], s35 offen lds
	s_or_b32 s35, s34, 0x300080
	s_mov_b32 m0, s27
	s_nop 0
	buffer_load_dwordx4 v131, s[64:67], s35 offen lds
	s_barrier
	s_waitcnt lgkmcnt(6)
	s_setprio 1
	v_mfma_f32_16x16x32_bf16 v[124:127], v[168:171], v[132:135], v[124:127]
	v_mfma_f32_16x16x32_bf16 v[120:123], v[168:171], v[160:163], v[120:123]
	v_mfma_f32_16x16x32_bf16 v[116:119], v[176:179], v[132:135], v[116:119]
	v_mfma_f32_16x16x32_bf16 v[112:115], v[176:179], v[160:163], v[112:115]
	v_mfma_f32_16x16x32_bf16 v[108:111], v[184:187], v[132:135], v[108:111]
	v_mfma_f32_16x16x32_bf16 v[104:107], v[184:187], v[160:163], v[104:107]
	v_mfma_f32_16x16x32_bf16 v[100:103], v[192:195], v[132:135], v[100:103]
	v_mfma_f32_16x16x32_bf16 v[96:99], v[192:195], v[160:163], v[96:99]
	v_mfma_f32_16x16x32_bf16 v[124:127], v[172:175], v[156:159], v[124:127]
	v_mfma_f32_16x16x32_bf16 v[120:123], v[172:175], v[164:167], v[120:123]
	v_mfma_f32_16x16x32_bf16 v[116:119], v[180:183], v[156:159], v[116:119]
	v_mfma_f32_16x16x32_bf16 v[112:115], v[180:183], v[164:167], v[112:115]
	v_mfma_f32_16x16x32_bf16 v[108:111], v[188:191], v[156:159], v[108:111]
	v_mfma_f32_16x16x32_bf16 v[104:107], v[188:191], v[164:167], v[104:107]
	v_mfma_f32_16x16x32_bf16 v[100:103], v[196:199], v[156:159], v[100:103]
	v_mfma_f32_16x16x32_bf16 v[96:99], v[196:199], v[164:167], v[96:99]
	s_setprio 0
	s_barrier
; #define STAGE_A(POFF, h, kt) STAGE_AX(POFF, h, kt, brow)
; #define STAGE_B(POFF, h, kt) STAGE_BX(POFF, h, kt, bcol)
; #define LDA(dst, b, h) _Pragma("unroll") for (int m = 0; m < 4; ++m) _Pragma("unroll") for (int k = 0; k < 2; ++k) \
;     dst[m][k] = *reinterpret_cast<const bf16x8*>((char*)SA(b, h) + lds_byte(wr * 64 + m * 16 + fr, k * 32 + fq * 8))
; #define LDB(dst, b, h) _Pragma("unroll") for (int n = 0; n < 2; ++n) _Pragma("unroll") for (int k = 0; k < 2; ++k) \
;     dst[n][k] = *reinterpret_cast<const bf16x8*>((char*)SB(b, h) + lds_byte(wc * 32 + n * 16 + fr, k * 32 + fq * 8))
; #define MMA(ai, bj, At_, Bt_) do { __builtin_amdgcn_s_setprio(1); \
;     _Pragma("unroll") for (int k = 0; k < 2; ++k) _Pragma("unroll") for (int m = 0; m < 4; ++m) _Pragma("unroll") for (int n = 0; n < 2; ++n) \
;       acc[ai][bj][m][n] = __builtin_amdgcn_mfma_f32_16x16x32_bf16(At_[m][k], Bt_[n][k], acc[ai][bj][m][n], 0, 0, 0); \
;     __builtin_amdgcn_s_setprio(0); } while (0)
; #define WAIT_V(n) asm volatile("s_waitcnt vmcnt(" #n ")" ::: "memory")
; #define BAR __builtin_amdgcn_s_barrier()
; #define SCHED __builtin_amdgcn_sched_barrier(0)
; template <int EPI, int N, int K>
; __device__ __forceinline__ void gemm_phase(const bf16_t* __restrict__ A, const bf16_t* __restrict__ Bt, const EpiArgs ea) {
;     ...
;       LDB(B1, 0, 1); STAGE_B(SB_OFF(0, 0), 0, t + 2);
;       BAR; WAIT_L(0); MMA(0, 1, At, B1); BAR;
;       LDA(At, 0, 1); STAGE_A(SA_OFF(0, 0), 0, t + 2);
;       BAR; WAIT_L(0); MMA(1, 0, At, B0); BAR; SCHED;
;       STAGE_B(SB_OFF(0, 1), 1, t + 2);
;       WAIT_V(6); BAR; MMA(1, 1, At, B1); BAR;
;       LDB(B0, 1, 0); SCHED; LDA(At, 1, 0); STAGE_A(SA_OFF(0, 1), 1, t + 2);
;       WAIT_L(8); BAR; WAIT_L(0); MMA(0, 0, At, B0); BAR; SCHED;
	ds_read_b128 v[200:203], v152
	ds_read_b128 v[204:207], v152 offset:1024
	ds_read_b128 v[208:211], v152 offset:2048
	ds_read_b128 v[212:215], v152 offset:3072
	ds_read_b128 v[246:249], v151 offset:16384
	ds_read_b128 v[250:253], v151 offset:17408
	s_add_i32 s35, s11, s31
	s_add_i32 s36, s35, 0x100
	s_mov_b32 m0, s13
	s_nop 0
	buffer_load_dwordx4 v144, s[80:83], s36 offen lds
	s_add_i32 s36, s35, 0x200100
	s_mov_b32 m0, s14
	s_nop 0
	buffer_load_dwordx4 v144, s[80:83], s36 offen lds
	s_waitcnt vmcnt(6)
	s_barrier
	s_waitcnt lgkmcnt(2)
	s_setprio 1
	v_mfma_f32_16x16x32_bf16 v[92:95], v[168:171], v[200:203], v[92:95]
	v_mfma_f32_16x16x32_bf16 v[88:91], v[168:171], v[208:211], v[88:91]
	v_mfma_f32_16x16x32_bf16 v[84:87], v[176:179], v[200:203], v[84:87]
	v_mfma_f32_16x16x32_bf16 v[80:83], v[176:179], v[208:211], v[80:83]
	v_mfma_f32_16x16x32_bf16 v[76:79], v[184:187], v[200:203], v[76:79]
	v_mfma_f32_16x16x32_bf16 v[72:75], v[184:187], v[208:211], v[72:75]
	v_mfma_f32_16x16x32_bf16 v[68:71], v[192:195], v[200:203], v[68:71]
	v_mfma_f32_16x16x32_bf16 v[64:67], v[192:195], v[208:211], v[64:67]
	v_mfma_f32_16x16x32_bf16 v[92:95], v[172:175], v[204:207], v[92:95]
	v_mfma_f32_16x16x32_bf16 v[88:91], v[172:175], v[212:215], v[88:91]
	v_mfma_f32_16x16x32_bf16 v[84:87], v[180:183], v[204:207], v[84:87]
	v_mfma_f32_16x16x32_bf16 v[80:83], v[180:183], v[212:215], v[80:83]
	v_mfma_f32_16x16x32_bf16 v[76:79], v[188:191], v[204:207], v[76:79]
	v_mfma_f32_16x16x32_bf16 v[72:75], v[188:191], v[212:215], v[72:75]
	v_mfma_f32_16x16x32_bf16 v[68:71], v[196:199], v[204:207], v[68:71]
	v_mfma_f32_16x16x32_bf16 v[64:67], v[196:199], v[212:215], v[64:67]
	s_setprio 0
	s_barrier
	ds_read_b128 v[168:171], v148 offset:32768
	ds_read_b128 v[172:175], v148 offset:33792
	ds_read_b128 v[176:179], v149 offset:32768
	ds_read_b128 v[180:183], v149 offset:33792
	ds_read_b128 v[184:187], v150 offset:32768
	ds_read_b128 v[188:191], v150 offset:33792
	s_add_i32 s36, s34, 0x100
	s_mov_b32 m0, s12
	s_nop 0
	buffer_load_dwordx4 v131, s[64:67], s36 offen lds
	s_add_i32 s37, s34, 0x100100
	s_mov_b32 m0, s15
	s_nop 0
	buffer_load_dwordx4 v131, s[64:67], s37 offen lds
	s_waitcnt vmcnt(10)
	s_barrier
	s_waitcnt lgkmcnt(6)
	s_setprio 1
	v_mfma_f32_16x16x32_bf16 v[60:63], v[218:221], v[132:135], v[60:63]
	v_mfma_f32_16x16x32_bf16 v[56:59], v[218:221], v[160:163], v[56:59]
	v_mfma_f32_16x16x32_bf16 v[52:55], v[226:229], v[132:135], v[52:55]
	v_mfma_f32_16x16x32_bf16 v[48:51], v[226:229], v[160:163], v[48:51]
	v_mfma_f32_16x16x32_bf16 v[44:47], v[238:241], v[132:135], v[44:47]
	v_mfma_f32_16x16x32_bf16 v[40:43], v[238:241], v[160:163], v[40:43]
	v_mfma_f32_16x16x32_bf16 v[36:39], v[246:249], v[132:135], v[36:39]
	v_mfma_f32_16x16x32_bf16 v[32:35], v[246:249], v[160:163], v[32:35]
	v_mfma_f32_16x16x32_bf16 v[60:63], v[222:225], v[156:159], v[60:63]
	v_mfma_f32_16x16x32_bf16 v[56:59], v[222:225], v[164:167], v[56:59]
	v_mfma_f32_16x16x32_bf16 v[52:55], v[230:233], v[156:159], v[52:55]
	v_mfma_f32_16x16x32_bf16 v[48:51], v[230:233], v[164:167], v[48:51]
	v_mfma_f32_16x16x32_bf16 v[44:47], v[242:245], v[156:159], v[44:47]
	v_mfma_f32_16x16x32_bf16 v[40:43], v[242:245], v[164:167], v[40:43]
	v_mfma_f32_16x16x32_bf16 v[36:39], v[250:253], v[156:159], v[36:39]
	v_mfma_f32_16x16x32_bf16 v[32:35], v[250:253], v[164:167], v[32:35]
	s_setprio 0
	s_barrier
	ds_read_b128 v[132:135], v153
	ds_read_b128 v[156:159], v153 offset:1024
	ds_read_b128 v[160:163], v153 offset:2048
	ds_read_b128 v[164:167], v153 offset:3072
	ds_read_b128 v[192:195], v151 offset:32768
	ds_read_b128 v[196:199], v151 offset:33792
	s_add_i32 s37, s35, 0x8100
	s_mov_b32 m0, s16
	s_nop 0
	buffer_load_dwordx4 v144, s[80:83], s37 offen lds
	s_add_i32 s37, s35, 0x208100
	s_mov_b32 m0, s17
	s_nop 0
	buffer_load_dwordx4 v144, s[80:83], s37 offen lds
	s_waitcnt vmcnt(6)
	s_barrier
	s_setprio 1
	v_mfma_f32_16x16x32_bf16 v[28:31], v[218:221], v[200:203], v[28:31]
	v_mfma_f32_16x16x32_bf16 v[24:27], v[218:221], v[208:211], v[24:27]
	v_mfma_f32_16x16x32_bf16 v[20:23], v[226:229], v[200:203], v[20:23]
	v_mfma_f32_16x16x32_bf16 v[16:19], v[226:229], v[208:211], v[16:19]
	v_mfma_f32_16x16x32_bf16 v[12:15], v[238:241], v[200:203], v[12:15]
	v_mfma_f32_16x16x32_bf16 v[8:11], v[238:241], v[208:211], v[8:11]
	v_mfma_f32_16x16x32_bf16 v[4:7], v[246:249], v[200:203], v[4:7]
	v_mfma_f32_16x16x32_bf16 v[0:3], v[246:249], v[208:211], v[0:3]
	v_mfma_f32_16x16x32_bf16 v[28:31], v[222:225], v[204:207], v[28:31]
	v_mfma_f32_16x16x32_bf16 v[24:27], v[222:225], v[212:215], v[24:27]
	v_mfma_f32_16x16x32_bf16 v[20:23], v[230:233], v[204:207], v[20:23]
	v_mfma_f32_16x16x32_bf16 v[16:19], v[230:233], v[212:215], v[16:19]
	v_mfma_f32_16x16x32_bf16 v[12:15], v[242:245], v[204:207], v[12:15]
	v_mfma_f32_16x16x32_bf16 v[8:11], v[242:245], v[212:215], v[8:11]
	v_mfma_f32_16x16x32_bf16 v[4:7], v[250:253], v[204:207], v[4:7]
	v_mfma_f32_16x16x32_bf16 v[0:3], v[250:253], v[212:215], v[0:3]
	s_setprio 0
	s_barrier
	ds_read_b128 v[218:221], v148 offset:49152
	ds_read_b128 v[222:225], v148 offset:50176
	ds_read_b128 v[226:229], v149 offset:49152
	ds_read_b128 v[230:233], v149 offset:50176
	ds_read_b128 v[238:241], v150 offset:49152
	ds_read_b128 v[242:245], v150 offset:50176
	s_or_b32 s37, s36, 0x200000
	s_mov_b32 m0, s18
	s_nop 0
	buffer_load_dwordx4 v131, s[64:67], s37 offen lds
	s_or_b32 s36, s36, 0x300000
	s_mov_b32 m0, s19
	s_nop 0
	buffer_load_dwordx4 v131, s[64:67], s36 offen lds
	s_barrier
; #define STAGE_A(POFF, h, kt) STAGE_AX(POFF, h, kt, brow)
; #define STAGE_B(POFF, h, kt) STAGE_BX(POFF, h, kt, bcol)
; #define LDA(dst, b, h) _Pragma("unroll") for (int m = 0; m < 4; ++m) _Pragma("unroll") for (int k = 0; k < 2; ++k) \
;     dst[m][k] = *reinterpret_cast<const bf16x8*>((char*)SA(b, h) + lds_byte(wr * 64 + m * 16 + fr, k * 32 + fq * 8))
; #define LDB(dst, b, h) _Pragma("unroll") for (int n = 0; n < 2; ++n) _Pragma("unroll") for (int k = 0; k < 2; ++k) \
;     dst[n][k] = *reinterpret_cast<const bf16x8*>((char*)SB(b, h) + lds_byte(wc * 32 + n * 16 + fr, k * 32 + fq * 8))
; #define MMA(ai, bj, At_, Bt_) do { __builtin_amdgcn_s_setprio(1); \
;     _Pragma("unroll") for (int k = 0; k < 2; ++k) _Pragma("unroll") for (int m = 0; m < 4; ++m) _Pragma("unroll") for (int n = 0; n < 2; ++n) \
;       acc[ai][bj][m][n] = __builtin_amdgcn_mfma_f32_16x16x32_bf16(At_[m][k], Bt_[n][k], acc[ai][bj][m][n], 0, 0, 0); \
;     __builtin_amdgcn_s_setprio(0); } while (0)
; #define WAIT_V(n) asm volatile("s_waitcnt vmcnt(" #n ")" ::: "memory")
; #define BAR __builtin_amdgcn_s_barrier()
; #define SCHED __builtin_amdgcn_sched_barrier(0)
; template <int EPI, int N, int K>
; __device__ __forceinline__ void gemm_phase(const bf16_t* __restrict__ A, const bf16_t* __restrict__ Bt, const EpiArgs ea) {
;     ...
;       WAIT_L(8); BAR; WAIT_L(0); MMA(0, 0, At, B0); BAR; SCHED;
;       LDB(B1, 1, 1); STAGE_B(SB_OFF(1, 0), 0, t + 3);
;       BAR; WAIT_L(0); MMA(0, 1, At, B1); BAR;
;       LDA(At, 1, 1); STAGE_A(SA_OFF(1, 0), 0, t + 3);
;       BAR; WAIT_L(0); MMA(1, 0, At, B0); BAR; SCHED;
;       STAGE_B(SB_OFF(1, 1), 1, t + 3);
;       WAIT_V(6); BAR; MMA(1, 1, At, B1); BAR;
	s_waitcnt lgkmcnt(6)
	s_setprio 1
	v_mfma_f32_16x16x32_bf16 v[124:127], v[168:171], v[132:135], v[124:127]
	v_mfma_f32_16x16x32_bf16 v[120:123], v[168:171], v[160:163], v[120:123]
	v_mfma_f32_16x16x32_bf16 v[116:119], v[176:179], v[132:135], v[116:119]
	v_mfma_f32_16x16x32_bf16 v[112:115], v[176:179], v[160:163], v[112:115]
	v_mfma_f32_16x16x32_bf16 v[108:111], v[184:187], v[132:135], v[108:111]
	v_mfma_f32_16x16x32_bf16 v[104:107], v[184:187], v[160:163], v[104:107]
	v_mfma_f32_16x16x32_bf16 v[100:103], v[192:195], v[132:135], v[100:103]
	v_mfma_f32_16x16x32_bf16 v[96:99], v[192:195], v[160:163], v[96:99]
	v_mfma_f32_16x16x32_bf16 v[124:127], v[172:175], v[156:159], v[124:127]
	v_mfma_f32_16x16x32_bf16 v[120:123], v[172:175], v[164:167], v[120:123]
	v_mfma_f32_16x16x32_bf16 v[116:119], v[180:183], v[156:159], v[116:119]
	v_mfma_f32_16x16x32_bf16 v[112:115], v[180:183], v[164:167], v[112:115]
	v_mfma_f32_16x16x32_bf16 v[108:111], v[188:191], v[156:159], v[108:111]
	v_mfma_f32_16x16x32_bf16 v[104:107], v[188:191], v[164:167], v[104:107]
	v_mfma_f32_16x16x32_bf16 v[100:103], v[196:199], v[156:159], v[100:103]
	v_mfma_f32_16x16x32_bf16 v[96:99], v[196:199], v[164:167], v[96:99]
	s_setprio 0
	s_barrier
	ds_read_b128 v[200:203], v154
	ds_read_b128 v[204:207], v154 offset:1024
	ds_read_b128 v[208:211], v154 offset:2048
	ds_read_b128 v[212:215], v154 offset:3072
	ds_read_b128 v[246:249], v151 offset:49152
	ds_read_b128 v[250:253], v151 offset:50176
	s_add_i32 s36, s35, 0x180
	s_mov_b32 m0, s20
	s_nop 0
	buffer_load_dwordx4 v144, s[80:83], s36 offen lds
	s_add_i32 s36, s35, 0x200180
	s_mov_b32 m0, s21
	s_nop 0
	buffer_load_dwordx4 v144, s[80:83], s36 offen lds
	s_waitcnt vmcnt(6)
	s_barrier
	s_waitcnt lgkmcnt(2)
	s_setprio 1
	v_mfma_f32_16x16x32_bf16 v[92:95], v[168:171], v[200:203], v[92:95]
	v_mfma_f32_16x16x32_bf16 v[88:91], v[168:171], v[208:211], v[88:91]
	v_mfma_f32_16x16x32_bf16 v[84:87], v[176:179], v[200:203], v[84:87]
	v_mfma_f32_16x16x32_bf16 v[80:83], v[176:179], v[208:211], v[80:83]
	v_mfma_f32_16x16x32_bf16 v[76:79], v[184:187], v[200:203], v[76:79]
	v_mfma_f32_16x16x32_bf16 v[72:75], v[184:187], v[208:211], v[72:75]
	v_mfma_f32_16x16x32_bf16 v[68:71], v[192:195], v[200:203], v[68:71]
	v_mfma_f32_16x16x32_bf16 v[64:67], v[192:195], v[208:211], v[64:67]
	v_mfma_f32_16x16x32_bf16 v[92:95], v[172:175], v[204:207], v[92:95]
	v_mfma_f32_16x16x32_bf16 v[88:91], v[172:175], v[212:215], v[88:91]
	v_mfma_f32_16x16x32_bf16 v[84:87], v[180:183], v[204:207], v[84:87]
	v_mfma_f32_16x16x32_bf16 v[80:83], v[180:183], v[212:215], v[80:83]
	v_mfma_f32_16x16x32_bf16 v[76:79], v[188:191], v[204:207], v[76:79]
	v_mfma_f32_16x16x32_bf16 v[72:75], v[188:191], v[212:215], v[72:75]
	v_mfma_f32_16x16x32_bf16 v[68:71], v[196:199], v[204:207], v[68:71]
	v_mfma_f32_16x16x32_bf16 v[64:67], v[196:199], v[212:215], v[64:67]
	s_setprio 0
	s_barrier
	ds_read_b128 v[168:171], v148
	ds_read_b128 v[172:175], v148 offset:1024
	ds_read_b128 v[176:179], v149
	ds_read_b128 v[180:183], v149 offset:1024
	ds_read_b128 v[184:187], v150
	ds_read_b128 v[188:191], v150 offset:1024
	s_add_i32 s36, s34, 0x180
	s_mov_b32 m0, s22
	s_nop 0
	buffer_load_dwordx4 v131, s[64:67], s36 offen lds
	s_add_i32 s34, s34, 0x100180
	s_mov_b32 m0, s23
	s_nop 0
	buffer_load_dwordx4 v131, s[64:67], s34 offen lds
	s_waitcnt vmcnt(10)
	s_barrier
	s_waitcnt lgkmcnt(6)
	s_setprio 1
	v_mfma_f32_16x16x32_bf16 v[60:63], v[218:221], v[132:135], v[60:63]
	v_mfma_f32_16x16x32_bf16 v[56:59], v[218:221], v[160:163], v[56:59]
	v_mfma_f32_16x16x32_bf16 v[52:55], v[226:229], v[132:135], v[52:55]
	v_mfma_f32_16x16x32_bf16 v[48:51], v[226:229], v[160:163], v[48:51]
	v_mfma_f32_16x16x32_bf16 v[44:47], v[238:241], v[132:135], v[44:47]
	v_mfma_f32_16x16x32_bf16 v[40:43], v[238:241], v[160:163], v[40:43]
	v_mfma_f32_16x16x32_bf16 v[36:39], v[246:249], v[132:135], v[36:39]
	v_mfma_f32_16x16x32_bf16 v[32:35], v[246:249], v[160:163], v[32:35]
	v_mfma_f32_16x16x32_bf16 v[60:63], v[222:225], v[156:159], v[60:63]
	v_mfma_f32_16x16x32_bf16 v[56:59], v[222:225], v[164:167], v[56:59]
	v_mfma_f32_16x16x32_bf16 v[52:55], v[230:233], v[156:159], v[52:55]
	v_mfma_f32_16x16x32_bf16 v[48:51], v[230:233], v[164:167], v[48:51]
	v_mfma_f32_16x16x32_bf16 v[44:47], v[242:245], v[156:159], v[44:47]
	v_mfma_f32_16x16x32_bf16 v[40:43], v[242:245], v[164:167], v[40:43]
	v_mfma_f32_16x16x32_bf16 v[36:39], v[250:253], v[156:159], v[36:39]
	v_mfma_f32_16x16x32_bf16 v[32:35], v[250:253], v[164:167], v[32:35]
	s_setprio 0
	s_barrier
	ds_read_b128 v[132:135], v147
	ds_read_b128 v[156:159], v147 offset:1024
	ds_read_b128 v[160:163], v147 offset:2048
	ds_read_b128 v[164:167], v147 offset:3072
	ds_read_b128 v[192:195], v151
	ds_read_b128 v[196:199], v151 offset:1024
	s_add_i32 s34, s35, 0x8180
	s_mov_b32 m0, s24
	s_nop 0
	buffer_load_dwordx4 v144, s[80:83], s34 offen lds
	s_add_i32 s35, s35, 0x208180
	s_mov_b32 m0, s25
	s_nop 0
	buffer_load_dwordx4 v144, s[80:83], s35 offen lds
	s_waitcnt vmcnt(6)
	s_barrier
	s_setprio 1
	v_mfma_f32_16x16x32_bf16 v[28:31], v[218:221], v[200:203], v[28:31]
	v_mfma_f32_16x16x32_bf16 v[24:27], v[218:221], v[208:211], v[24:27]
	v_mfma_f32_16x16x32_bf16 v[20:23], v[226:229], v[200:203], v[20:23]
	v_mfma_f32_16x16x32_bf16 v[16:19], v[226:229], v[208:211], v[16:19]
	v_mfma_f32_16x16x32_bf16 v[12:15], v[238:241], v[200:203], v[12:15]
	v_mfma_f32_16x16x32_bf16 v[8:11], v[238:241], v[208:211], v[8:11]
	v_mfma_f32_16x16x32_bf16 v[4:7], v[246:249], v[200:203], v[4:7]
	v_mfma_f32_16x16x32_bf16 v[0:3], v[246:249], v[208:211], v[0:3]
	v_mfma_f32_16x16x32_bf16 v[28:31], v[222:225], v[204:207], v[28:31]
	v_mfma_f32_16x16x32_bf16 v[24:27], v[222:225], v[212:215], v[24:27]
	v_mfma_f32_16x16x32_bf16 v[20:23], v[230:233], v[204:207], v[20:23]
	v_mfma_f32_16x16x32_bf16 v[16:19], v[230:233], v[212:215], v[16:19]
	v_mfma_f32_16x16x32_bf16 v[12:15], v[242:245], v[204:207], v[12:15]
	v_mfma_f32_16x16x32_bf16 v[8:11], v[242:245], v[212:215], v[8:11]
	v_mfma_f32_16x16x32_bf16 v[4:7], v[250:253], v[204:207], v[4:7]
	v_mfma_f32_16x16x32_bf16 v[0:3], v[250:253], v[212:215], v[0:3]
	s_setprio 0
	s_add_i32 s30, s30, 2
	s_addk_i32 s31, 0x100
	s_cmpk_lt_u32 s30, 0x7c
	s_barrier
; #define STAGE_A(POFF, h, kt) STAGE_AX(POFF, h, kt, brow)
; #define LDA(dst, b, h) _Pragma("unroll") for (int m = 0; m < 4; ++m) _Pragma("unroll") for (int k = 0; k < 2; ++k) \
;     dst[m][k] = *reinterpret_cast<const bf16x8*>((char*)SA(b, h) + lds_byte(wr * 64 + m * 16 + fr, k * 32 + fq * 8))
; #define LDB(dst, b, h) _Pragma("unroll") for (int n = 0; n < 2; ++n) _Pragma("unroll") for (int k = 0; k < 2; ++k) \
;     dst[n][k] = *reinterpret_cast<const bf16x8*>((char*)SB(b, h) + lds_byte(wc * 32 + n * 16 + fr, k * 32 + fq * 8))
; #define MMA(ai, bj, At_, Bt_) do { __builtin_amdgcn_s_setprio(1); \
;     _Pragma("unroll") for (int k = 0; k < 2; ++k) _Pragma("unroll") for (int m = 0; m < 4; ++m) _Pragma("unroll") for (int n = 0; n < 2; ++n) \
;       acc[ai][bj][m][n] = __builtin_amdgcn_mfma_f32_16x16x32_bf16(At_[m][k], Bt_[n][k], acc[ai][bj][m][n], 0, 0, 0); \
;     __builtin_amdgcn_s_setprio(0); } while (0)
; #define WAIT_V(n) asm volatile("s_waitcnt vmcnt(" #n ")" ::: "memory")
; #define BAR __builtin_amdgcn_s_barrier()
; template <int EPI, int N, int K>
; __device__ __forceinline__ void gemm_phase(const bf16_t* __restrict__ A, const bf16_t* __restrict__ Bt, const EpiArgs ea) {
;     ...
;       WAIT_V(6); BAR; MMA(1, 1, At, B1); BAR;
;     }
;     { LDB(B0, 0, 0); LDA(At, 0, 0); STAGE_A(SA_OFF(1, 1), 1, nt - 1);
;       BAR; WAIT_L(0); MMA(0, 0, At, B0); BAR;
;       LDB(B1, 0, 1); BAR; WAIT_L(0); MMA(0, 1, At, B1); BAR;
;       LDA(At, 0, 1); WAIT_V(4); BAR; WAIT_L(0); MMA(1, 0, At, B0); MMA(1, 1, At, B1); BAR; }
	s_cbranch_scc1 .LBB0_568
	s_and_b32 s3, s3, 0x700
	s_lshl_b32 s2, s2, 11
	s_or_b32 s29, s3, s2
	s_lshl_b32 s2, s29, 14
	s_or_b32 s3, s2, 0x203f80
	s_mov_b32 m0, s26
	s_nop 0
	buffer_load_dwordx4 v131, s[64:67], s3 offen lds
	s_or_b32 s2, s2, 0x303f80
	s_mov_b32 m0, s27
	s_nop 0
	buffer_load_dwordx4 v131, s[64:67], s2 offen lds
	s_barrier
	s_waitcnt lgkmcnt(0)
	s_setprio 1
	v_mfma_f32_16x16x32_bf16 v[124:127], v[168:171], v[132:135], v[124:127]
	v_mfma_f32_16x16x32_bf16 v[120:123], v[168:171], v[160:163], v[120:123]
	v_mfma_f32_16x16x32_bf16 v[116:119], v[176:179], v[132:135], v[116:119]
	v_mfma_f32_16x16x32_bf16 v[112:115], v[176:179], v[160:163], v[112:115]
	v_mfma_f32_16x16x32_bf16 v[108:111], v[184:187], v[132:135], v[108:111]
	v_mfma_f32_16x16x32_bf16 v[104:107], v[184:187], v[160:163], v[104:107]
	v_mfma_f32_16x16x32_bf16 v[100:103], v[192:195], v[132:135], v[100:103]
	v_mfma_f32_16x16x32_bf16 v[96:99], v[192:195], v[160:163], v[96:99]
	v_mfma_f32_16x16x32_bf16 v[124:127], v[172:175], v[156:159], v[124:127]
	v_mfma_f32_16x16x32_bf16 v[120:123], v[172:175], v[164:167], v[120:123]
	v_mfma_f32_16x16x32_bf16 v[116:119], v[180:183], v[156:159], v[116:119]
	v_mfma_f32_16x16x32_bf16 v[112:115], v[180:183], v[164:167], v[112:115]
	v_mfma_f32_16x16x32_bf16 v[108:111], v[188:191], v[156:159], v[108:111]
	v_mfma_f32_16x16x32_bf16 v[104:107], v[188:191], v[164:167], v[104:107]
	v_mfma_f32_16x16x32_bf16 v[100:103], v[196:199], v[156:159], v[100:103]
	v_mfma_f32_16x16x32_bf16 v[96:99], v[196:199], v[164:167], v[96:99]
	s_setprio 0
	s_barrier
	ds_read_b128 v[200:203], v152
	ds_read_b128 v[204:207], v152 offset:1024
	ds_read_b128 v[208:211], v152 offset:2048
	ds_read_b128 v[212:215], v152 offset:3072
	s_barrier
	s_waitcnt lgkmcnt(0)
	s_setprio 1
	v_mfma_f32_16x16x32_bf16 v[92:95], v[168:171], v[200:203], v[92:95]
	v_mfma_f32_16x16x32_bf16 v[88:91], v[168:171], v[208:211], v[88:91]
	v_mfma_f32_16x16x32_bf16 v[76:79], v[184:187], v[200:203], v[76:79]
	v_mfma_f32_16x16x32_bf16 v[72:75], v[184:187], v[208:211], v[72:75]
	v_mfma_f32_16x16x32_bf16 v[84:87], v[176:179], v[200:203], v[84:87]
	v_mfma_f32_16x16x32_bf16 v[80:83], v[176:179], v[208:211], v[80:83]
	v_mfma_f32_16x16x32_bf16 v[68:71], v[192:195], v[200:203], v[68:71]
	v_mfma_f32_16x16x32_bf16 v[64:67], v[192:195], v[208:211], v[64:67]
	v_mfma_f32_16x16x32_bf16 v[92:95], v[172:175], v[204:207], v[92:95]
	v_mfma_f32_16x16x32_bf16 v[88:91], v[172:175], v[212:215], v[88:91]
	v_mfma_f32_16x16x32_bf16 v[76:79], v[188:191], v[204:207], v[76:79]
	v_mfma_f32_16x16x32_bf16 v[72:75], v[188:191], v[212:215], v[72:75]
	v_mfma_f32_16x16x32_bf16 v[168:171], v[180:183], v[204:207], v[84:87]
	v_mfma_f32_16x16x32_bf16 v[172:175], v[180:183], v[212:215], v[80:83]
	v_mfma_f32_16x16x32_bf16 v[176:179], v[196:199], v[204:207], v[68:71]
	v_mfma_f32_16x16x32_bf16 v[180:183], v[196:199], v[212:215], v[64:67]
	s_setprio 0
	s_barrier
	s_nop 0
	ds_read_b128 v[64:67], v148 offset:16384
	ds_read_b128 v[68:71], v148 offset:17408
	ds_read_b128 v[80:83], v149 offset:16384
	ds_read_b128 v[84:87], v149 offset:17408
	ds_read_b128 v[184:187], v150 offset:16384
	ds_read_b128 v[188:191], v150 offset:17408
	ds_read_b128 v[192:195], v151 offset:16384
	ds_read_b128 v[196:199], v151 offset:17408
	s_waitcnt vmcnt(4)
	s_barrier
	s_waitcnt lgkmcnt(0)
	s_setprio 1
	v_mfma_f32_16x16x32_bf16 v[60:63], v[64:67], v[132:135], v[60:63]
	v_mfma_f32_16x16x32_bf16 v[56:59], v[64:67], v[160:163], v[56:59]
	v_mfma_f32_16x16x32_bf16 v[52:55], v[80:83], v[132:135], v[52:55]
	v_mfma_f32_16x16x32_bf16 v[48:51], v[80:83], v[160:163], v[48:51]
	v_mfma_f32_16x16x32_bf16 v[44:47], v[184:187], v[132:135], v[44:47]
	v_mfma_f32_16x16x32_bf16 v[40:43], v[184:187], v[160:163], v[40:43]
	v_mfma_f32_16x16x32_bf16 v[36:39], v[192:195], v[132:135], v[36:39]
	v_mfma_f32_16x16x32_bf16 v[32:35], v[192:195], v[160:163], v[32:35]
	v_mfma_f32_16x16x32_bf16 v[60:63], v[68:71], v[156:159], v[60:63]
	v_mfma_f32_16x16x32_bf16 v[56:59], v[68:71], v[164:167], v[56:59]
	v_mfma_f32_16x16x32_bf16 v[52:55], v[84:87], v[156:159], v[52:55]
	v_mfma_f32_16x16x32_bf16 v[48:51], v[84:87], v[164:167], v[48:51]
	v_mfma_f32_16x16x32_bf16 v[44:47], v[188:191], v[156:159], v[44:47]
	v_mfma_f32_16x16x32_bf16 v[40:43], v[188:191], v[164:167], v[40:43]
	v_mfma_f32_16x16x32_bf16 v[36:39], v[196:199], v[156:159], v[36:39]
	v_mfma_f32_16x16x32_bf16 v[32:35], v[196:199], v[164:167], v[32:35]
	s_setprio 0
	s_setprio 1
	v_mfma_f32_16x16x32_bf16 v[28:31], v[64:67], v[200:203], v[28:31]
	v_mfma_f32_16x16x32_bf16 v[24:27], v[64:67], v[208:211], v[24:27]
	v_mfma_f32_16x16x32_bf16 v[4:7], v[192:195], v[200:203], v[4:7]
	v_mfma_f32_16x16x32_bf16 v[0:3], v[192:195], v[208:211], v[0:3]
	v_mfma_f32_16x16x32_bf16 v[20:23], v[80:83], v[200:203], v[20:23]
	v_mfma_f32_16x16x32_bf16 v[16:19], v[80:83], v[208:211], v[16:19]
	v_mfma_f32_16x16x32_bf16 v[12:15], v[184:187], v[200:203], v[12:15]
	v_mfma_f32_16x16x32_bf16 v[8:11], v[184:187], v[208:211], v[8:11]
	v_mfma_f32_16x16x32_bf16 v[28:31], v[68:71], v[204:207], v[28:31]
	v_mfma_f32_16x16x32_bf16 v[24:27], v[68:71], v[212:215], v[24:27]
	v_mfma_f32_16x16x32_bf16 v[4:7], v[196:199], v[204:207], v[4:7]
	v_mfma_f32_16x16x32_bf16 v[0:3], v[196:199], v[212:215], v[0:3]
	v_mfma_f32_16x16x32_bf16 v[132:135], v[84:87], v[204:207], v[20:23]
	v_mfma_f32_16x16x32_bf16 v[156:159], v[84:87], v[212:215], v[16:19]
	v_mfma_f32_16x16x32_bf16 v[160:163], v[188:191], v[204:207], v[12:15]
	v_mfma_f32_16x16x32_bf16 v[164:167], v[188:191], v[212:215], v[8:11]
	s_setprio 0
	s_barrier
; #define LDA(dst, b, h) _Pragma("unroll") for (int m = 0; m < 4; ++m) _Pragma("unroll") for (int k = 0; k < 2; ++k) \
;     dst[m][k] = *reinterpret_cast<const bf16x8*>((char*)SA(b, h) + lds_byte(wr * 64 + m * 16 + fr, k * 32 + fq * 8))
; #define LDB(dst, b, h) _Pragma("unroll") for (int n = 0; n < 2; ++n) _Pragma("unroll") for (int k = 0; k < 2; ++k) \
;     dst[n][k] = *reinterpret_cast<const bf16x8*>((char*)SB(b, h) + lds_byte(wc * 32 + n * 16 + fr, k * 32 + fq * 8))
; #define MMA(ai, bj, At_, Bt_) do { __builtin_amdgcn_s_setprio(1); \
;     _Pragma("unroll") for (int k = 0; k < 2; ++k) _Pragma("unroll") for (int m = 0; m < 4; ++m) _Pragma("unroll") for (int n = 0; n < 2; ++n) \
;       acc[ai][bj][m][n] = __builtin_amdgcn_mfma_f32_16x16x32_bf16(At_[m][k], Bt_[n][k], acc[ai][bj][m][n], 0, 0, 0); \
;     __builtin_amdgcn_s_setprio(0); } while (0)
; #define WAIT_V(n) asm volatile("s_waitcnt vmcnt(" #n ")" ::: "memory")
; #define BAR __builtin_amdgcn_s_barrier()
; template <int EPI, int N, int K>
; __device__ __forceinline__ void gemm_phase(const bf16_t* __restrict__ A, const bf16_t* __restrict__ Bt, const EpiArgs ea) {
;     ...
;     { LDB(B0, 1, 0); LDA(At, 1, 0); WAIT_V(2); BAR; WAIT_L(0); MMA(0, 0, At, B0); BAR;
;       LDB(B1, 1, 1); WAIT_V(0); BAR; WAIT_L(0); MMA(0, 1, At, B1); BAR;
;       LDA(At, 1, 1); BAR; WAIT_L(0); MMA(1, 0, At, B0); MMA(1, 1, At, B1); BAR; }
;     if (wr == 0) BAR;
	s_nop 0
	ds_read_b128 v[8:11], v153
	ds_read_b128 v[12:15], v153 offset:1024
	ds_read_b128 v[16:19], v153 offset:2048
	ds_read_b128 v[184:187], v153 offset:3072
	ds_read_b128 v[20:23], v148 offset:32768
	ds_read_b128 v[188:191], v148 offset:33792
	ds_read_b128 v[192:195], v149 offset:32768
	ds_read_b128 v[196:199], v149 offset:33792
	ds_read_b128 v[200:203], v150 offset:32768
	ds_read_b128 v[204:207], v150 offset:33792
	ds_read_b128 v[208:211], v151 offset:32768
	ds_read_b128 v[212:215], v151 offset:33792
	s_waitcnt vmcnt(2)
	s_barrier
	s_waitcnt lgkmcnt(0)
	s_setprio 1
	v_mfma_f32_16x16x32_bf16 v[64:67], v[20:23], v[8:11], v[124:127]
	v_mfma_f32_16x16x32_bf16 v[68:71], v[20:23], v[16:19], v[120:123]
	v_mfma_f32_16x16x32_bf16 v[80:83], v[192:195], v[8:11], v[116:119]
	v_mfma_f32_16x16x32_bf16 v[84:87], v[192:195], v[16:19], v[112:115]
	v_mfma_f32_16x16x32_bf16 v[108:111], v[200:203], v[8:11], v[108:111]
	v_mfma_f32_16x16x32_bf16 v[104:107], v[200:203], v[16:19], v[104:107]
	v_mfma_f32_16x16x32_bf16 v[120:123], v[208:211], v[8:11], v[100:103]
	v_mfma_f32_16x16x32_bf16 v[124:127], v[208:211], v[16:19], v[96:99]
	v_mfma_f32_16x16x32_bf16 v[116:119], v[188:191], v[12:15], v[64:67]
	v_mfma_f32_16x16x32_bf16 v[112:115], v[188:191], v[184:187], v[68:71]
	v_mfma_f32_16x16x32_bf16 v[100:103], v[196:199], v[12:15], v[80:83]
	v_mfma_f32_16x16x32_bf16 v[96:99], v[196:199], v[184:187], v[84:87]
	v_mfma_f32_16x16x32_bf16 v[84:87], v[204:207], v[12:15], v[108:111]
	v_mfma_f32_16x16x32_bf16 v[80:83], v[204:207], v[184:187], v[104:107]
	v_mfma_f32_16x16x32_bf16 v[68:71], v[212:215], v[12:15], v[120:123]
	v_mfma_f32_16x16x32_bf16 v[64:67], v[212:215], v[184:187], v[124:127]
	s_setprio 0
	s_barrier
	ds_read_b128 v[216:219], v154
	ds_read_b128 v[220:223], v154 offset:1024
	ds_read_b128 v[224:227], v154 offset:2048
	ds_read_b128 v[228:231], v154 offset:3072
	s_waitcnt vmcnt(0)
	s_barrier
	s_waitcnt lgkmcnt(0)
	s_setprio 1
	v_mfma_f32_16x16x32_bf16 v[92:95], v[20:23], v[216:219], v[92:95]
	v_mfma_f32_16x16x32_bf16 v[20:23], v[20:23], v[224:227], v[88:91]
	v_mfma_f32_16x16x32_bf16 v[88:91], v[192:195], v[216:219], v[168:171]
	v_mfma_f32_16x16x32_bf16 v[104:107], v[192:195], v[224:227], v[172:175]
	v_mfma_f32_16x16x32_bf16 v[76:79], v[200:203], v[216:219], v[76:79]
	v_mfma_f32_16x16x32_bf16 v[72:75], v[200:203], v[224:227], v[72:75]
	v_mfma_f32_16x16x32_bf16 v[168:171], v[208:211], v[216:219], v[176:179]
	v_mfma_f32_16x16x32_bf16 v[172:175], v[208:211], v[224:227], v[180:183]
	v_mfma_f32_16x16x32_bf16 v[124:127], v[188:191], v[220:223], v[92:95]
	v_mfma_f32_16x16x32_bf16 v[120:123], v[188:191], v[228:231], v[20:23]
	v_mfma_f32_16x16x32_bf16 v[108:111], v[196:199], v[220:223], v[88:91]
	v_mfma_f32_16x16x32_bf16 v[104:107], v[196:199], v[228:231], v[104:107]
	v_mfma_f32_16x16x32_bf16 v[92:95], v[204:207], v[220:223], v[76:79]
	v_mfma_f32_16x16x32_bf16 v[88:91], v[204:207], v[228:231], v[72:75]
	v_mfma_f32_16x16x32_bf16 v[76:79], v[212:215], v[220:223], v[168:171]
	v_mfma_f32_16x16x32_bf16 v[72:75], v[212:215], v[228:231], v[172:175]
	s_setprio 0
	s_barrier
	ds_read_b128 v[168:171], v148 offset:49152
	ds_read_b128 v[172:175], v148 offset:50176
	ds_read_b128 v[176:179], v149 offset:49152
	ds_read_b128 v[180:183], v149 offset:50176
	ds_read_b128 v[188:191], v150 offset:49152
	ds_read_b128 v[192:195], v150 offset:50176
	ds_read_b128 v[196:199], v151 offset:49152
	ds_read_b128 v[200:203], v151 offset:50176
	s_barrier
	s_waitcnt lgkmcnt(0)
	s_setprio 1
	v_mfma_f32_16x16x32_bf16 v[20:23], v[168:171], v[8:11], v[60:63]
	v_mfma_f32_16x16x32_bf16 v[56:59], v[168:171], v[16:19], v[56:59]
	v_mfma_f32_16x16x32_bf16 v[60:63], v[176:179], v[8:11], v[52:55]
	v_mfma_f32_16x16x32_bf16 v[204:207], v[176:179], v[16:19], v[48:51]
	v_mfma_f32_16x16x32_bf16 v[44:47], v[188:191], v[8:11], v[44:47]
	v_mfma_f32_16x16x32_bf16 v[40:43], v[188:191], v[16:19], v[40:43]
	v_mfma_f32_16x16x32_bf16 v[8:11], v[196:199], v[8:11], v[36:39]
	v_mfma_f32_16x16x32_bf16 v[208:211], v[196:199], v[16:19], v[32:35]
	v_mfma_f32_16x16x32_bf16 v[52:55], v[172:175], v[12:15], v[20:23]
	v_mfma_f32_16x16x32_bf16 v[48:51], v[172:175], v[184:187], v[56:59]
	v_mfma_f32_16x16x32_bf16 v[36:39], v[180:183], v[12:15], v[60:63]
	v_mfma_f32_16x16x32_bf16 v[32:35], v[180:183], v[184:187], v[204:207]
	v_mfma_f32_16x16x32_bf16 v[20:23], v[192:195], v[12:15], v[44:47]
	v_mfma_f32_16x16x32_bf16 v[16:19], v[192:195], v[184:187], v[40:43]
	v_mfma_f32_16x16x32_bf16 v[8:11], v[200:203], v[12:15], v[8:11]
	v_mfma_f32_16x16x32_bf16 v[12:15], v[200:203], v[184:187], v[208:211]
	s_setprio 0
	s_setprio 1
	v_mfma_f32_16x16x32_bf16 v[28:31], v[168:171], v[216:219], v[28:31]
	v_mfma_f32_16x16x32_bf16 v[24:27], v[168:171], v[224:227], v[24:27]
	v_mfma_f32_16x16x32_bf16 v[40:43], v[176:179], v[216:219], v[132:135]
	v_mfma_f32_16x16x32_bf16 v[132:135], v[176:179], v[224:227], v[156:159]
	v_mfma_f32_16x16x32_bf16 v[156:159], v[188:191], v[216:219], v[160:163]
	v_mfma_f32_16x16x32_bf16 v[160:163], v[188:191], v[224:227], v[164:167]
	v_mfma_f32_16x16x32_bf16 v[4:7], v[196:199], v[216:219], v[4:7]
	v_mfma_f32_16x16x32_bf16 v[0:3], v[196:199], v[224:227], v[0:3]
	v_mfma_f32_16x16x32_bf16 v[60:63], v[172:175], v[220:223], v[28:31]
	v_mfma_f32_16x16x32_bf16 v[56:59], v[172:175], v[228:231], v[24:27]
	v_mfma_f32_16x16x32_bf16 v[44:47], v[180:183], v[220:223], v[40:43]
	v_mfma_f32_16x16x32_bf16 v[40:43], v[180:183], v[228:231], v[132:135]
	v_mfma_f32_16x16x32_bf16 v[28:31], v[192:195], v[220:223], v[156:159]
	v_mfma_f32_16x16x32_bf16 v[24:27], v[192:195], v[228:231], v[160:163]
	v_mfma_f32_16x16x32_bf16 v[4:7], v[200:203], v[220:223], v[4:7]
	v_mfma_f32_16x16x32_bf16 v[0:3], v[200:203], v[228:231], v[0:3]
	s_setprio 0
	s_barrier
	s_and_saveexec_b64 s[2:3], s[6:7]
	s_cbranch_execz .LBB0_571
	s_barrier
